# baseline (speedup 1.0000x reference)
; #define PG8_STAGE(bufoff, gbase, voff) do { _Pragma("unroll") for (int _i = 0; _i < 2; ++_i) \
;         __builtin_amdgcn_global_load_lds((const unsigned*)((const char*)(gbase) + (voff)[_i]), (LAS unsigned*)(lds + (bufoff) + ldsw + _i * 8192), 16, 0, 0); } while (0)
; #define PG8_LDA(dst, b, h) do { _Pragma("unroll") for (int m = 0; m < 4; ++m) _Pragma("unroll") for (int k = 0; k < 2; ++k) dst[m][k] = *(const LAS bf16x8*)(lds + PG8_SA(b, h) + aoff + m * 2048 + k * 1024); } while (0)
; #define PG8_LDB(dst, b, h) do { _Pragma("unroll") for (int n = 0; n < 2; ++n) _Pragma("unroll") for (int k = 0; k < 2; ++k) dst[n][k] = *(const LAS bf16x8*)(lds + PG8_SB(b, h) + boff + n * 2048 + k * 1024); } while (0)
; #define PG8_MMA(ai, bj, At, Bt) do { __builtin_amdgcn_s_setprio(1); _Pragma("unroll") for (int m = 0; m < 4; ++m) _Pragma("unroll") for (int n = 0; n < 2; ++n) _Pragma("unroll") for (int k = 0; k < 2; ++k) \
;         acc[ai][bj][m][n] = __builtin_amdgcn_mfma_f32_16x16x32_bf16(Bt[n][k], At[m][k], acc[ai][bj][m][n], 0, 0, 0); __builtin_amdgcn_s_setprio(0); } while (0)
; template <class Epi, class Sched>
; __device__ __forceinline__ void gemm_phase(const int tid, LAS unsigned char* lds, const Gemm g, const Sched& S, const Epi& E) {
;     ...
;         const bool has_next = S.next(ui + 1, nxt);
;         const char* nA = has_next ? (const char*)g.A + (size_t)nxt.pm * tstep : cA; const char* nB = has_next ? (const char*)g.Bt + (size_t)nxt.pn * tstep : cB;
;         for (int t = 0; t < nt; t += 2) {
;             const bool last = (t == nt - 2);
;             const char* a1 = cA + (size_t)(t + 1) * kstep;
;             const char* a2 = last ? nA : cA + (size_t)(t + 2) * kstep; const char* b2 = last ? nB : cB + (size_t)(t + 2) * kstep;
;             const char* a3 = a2 + kstep; const char* b3 = b2 + kstep;
;             if (last && has_next) S.a_ready(nxt);
;             PG8_LDB(B0, 0, 0); PG8_LDB(B1, 0, 1); PG8_SCHED; PG8_LDA(At, 0, 0); PG8_STAGE(PG8_SA(1, 1), a1 + hstep, voffA);
;             PG8_WAIT_V(8); PG8_WAIT_L(0); PG8_BAR; PG8_MMA(0, 0, At, B0); PG8_MMA(0, 1, At, B1); PG8_BAR; PG8_SCHED;
;             PG8_LDA(At, 0, 1); PG8_STAGE(PG8_SB(0, 0), b2, voffB); PG8_STAGE(PG8_SB(0, 1), b2 + hstep, voffB); PG8_STAGE(PG8_SA(0, 0), a2, voffA);
;             PG8_WAIT_V(8); PG8_WAIT_L(0); PG8_BAR; PG8_MMA(1, 0, At, B0); PG8_MMA(1, 1, At, B1); PG8_BAR; PG8_SCHED;
.LBB0_49:
	s_ashr_i32 s15, s14, 31
	s_lshl_b64 s[16:17], s[14:15], 20
	s_add_u32 s16, s41, s16
	s_addc_u32 s17, s55, s17
	s_and_b64 s[18:19], s[0:1], exec
	s_cselect_b32 s15, s17, s23
	s_cselect_b32 s66, s16, s22
	s_ashr_i32 s13, s12, 31
	s_lshl_b64 s[18:19], s[12:13], 20
	v_readlane_b32 s13, v243, 16
	s_add_u32 s18, s13, s18
	v_readlane_b32 s13, v243, 17
	s_addc_u32 s19, s13, s19
	s_and_b64 s[26:27], s[0:1], exec
	s_cselect_b32 s13, s19, s25
	s_cselect_b32 s67, s18, s24
	s_add_u32 s22, s22, 0x80080
	s_addc_u32 s23, s23, 0
	s_add_u32 s68, s24, 0x100
	v_mov_b32_e32 v0, 0
	s_addc_u32 s69, s25, 0
	s_mov_b32 s70, -2
	s_add_u32 s24, s22, 0xfff80080
	s_addc_u32 s25, s23, -1
	s_add_i32 s71, 0, 0x10000
	s_cmp_eq_u32 s70, 28
	s_cselect_b32 s27, s15, s25
	s_cselect_b32 s26, s66, s24
	v_add_u32_e32 v150, s71, v148
	s_cselect_b32 s25, s13, s69
	s_cselect_b32 s24, s67, s68
	s_add_i32 s74, 0, 0x14000
	ds_read_b128 v[138:141], v150
	ds_read_b128 v[142:145], v150 offset:1024
	ds_read_b128 v[170:173], v150 offset:2048
	ds_read_b128 v[174:177], v150 offset:3072
	v_add_u32_e32 v150, s74, v148
	ds_read_b128 v[178:181], v150
	ds_read_b128 v[182:185], v150 offset:1024
	ds_read_b128 v[186:189], v150 offset:2048
	ds_read_b128 v[200:203], v150 offset:3072
	v_lshl_add_u64 v[150:151], s[22:23], 0, v[134:135]
	s_add_i32 m0, s21, 0xc000
	ds_read_b128 v[204:207], v149
	ds_read_b128 v[208:211], v149 offset:1024
	ds_read_b128 v[212:215], v149 offset:2048
	ds_read_b128 v[216:219], v149 offset:3072
	ds_read_b128 v[220:223], v149 offset:4096
	ds_read_b128 v[224:227], v149 offset:5120
	ds_read_b128 v[228:231], v149 offset:6144
	ds_read_b128 v[232:235], v149 offset:7168
	global_load_lds_dwordx4 v[150:151], off
	v_lshl_add_u64 v[150:151], s[22:23], 0, v[136:137]
	s_add_i32 m0, s21, 0xe000
	s_nop 0
	global_load_lds_dwordx4 v[150:151], off
	s_waitcnt vmcnt(8)
	s_waitcnt lgkmcnt(0)
	s_barrier
	s_setprio 1
	s_waitcnt lgkmcnt(0)
	v_mfma_f32_16x16x32_bf16 v[124:127], v[138:141], v[204:207], 0
	v_mfma_f32_16x16x32_bf16 v[120:123], v[170:173], v[204:207], 0
	v_mfma_f32_16x16x32_bf16 v[112:115], v[138:141], v[212:215], 0
	v_mfma_f32_16x16x32_bf16 v[104:107], v[170:173], v[212:215], 0
	v_mfma_f32_16x16x32_bf16 v[96:99], v[138:141], v[220:223], 0
	v_mfma_f32_16x16x32_bf16 v[88:91], v[170:173], v[220:223], 0
	v_mfma_f32_16x16x32_bf16 v[80:83], v[138:141], v[228:231], 0
	v_mfma_f32_16x16x32_bf16 v[72:75], v[170:173], v[228:231], 0
	v_mfma_f32_16x16x32_bf16 v[124:127], v[142:145], v[208:211], v[124:127]
	v_mfma_f32_16x16x32_bf16 v[120:123], v[174:177], v[208:211], v[120:123]
	v_mfma_f32_16x16x32_bf16 v[112:115], v[142:145], v[216:219], v[112:115]
	v_mfma_f32_16x16x32_bf16 v[104:107], v[174:177], v[216:219], v[104:107]
	v_mfma_f32_16x16x32_bf16 v[96:99], v[142:145], v[224:227], v[96:99]
	v_mfma_f32_16x16x32_bf16 v[88:91], v[174:177], v[224:227], v[88:91]
	v_mfma_f32_16x16x32_bf16 v[80:83], v[142:145], v[232:235], v[80:83]
	v_mfma_f32_16x16x32_bf16 v[72:75], v[174:177], v[232:235], v[72:75]
	v_mfma_f32_16x16x32_bf16 v[116:119], v[178:181], v[204:207], 0
	v_mfma_f32_16x16x32_bf16 v[108:111], v[186:189], v[204:207], 0
	v_mfma_f32_16x16x32_bf16 v[100:103], v[178:181], v[212:215], 0
	v_mfma_f32_16x16x32_bf16 v[92:95], v[186:189], v[212:215], 0
	v_mfma_f32_16x16x32_bf16 v[84:87], v[178:181], v[220:223], 0
	v_mfma_f32_16x16x32_bf16 v[76:79], v[186:189], v[220:223], 0
	v_mfma_f32_16x16x32_bf16 v[68:71], v[178:181], v[228:231], 0
	v_mfma_f32_16x16x32_bf16 v[64:67], v[186:189], v[228:231], 0
	v_mfma_f32_16x16x32_bf16 v[116:119], v[182:185], v[208:211], v[116:119]
	v_mfma_f32_16x16x32_bf16 v[108:111], v[200:203], v[208:211], v[108:111]
	v_mfma_f32_16x16x32_bf16 v[100:103], v[182:185], v[216:219], v[100:103]
	v_mfma_f32_16x16x32_bf16 v[92:95], v[200:203], v[216:219], v[92:95]
	v_mfma_f32_16x16x32_bf16 v[84:87], v[182:185], v[224:227], v[84:87]
	v_mfma_f32_16x16x32_bf16 v[76:79], v[200:203], v[224:227], v[76:79]
	v_mfma_f32_16x16x32_bf16 v[68:71], v[182:185], v[232:235], v[68:71]
	v_mfma_f32_16x16x32_bf16 v[64:67], v[200:203], v[232:235], v[64:67]
	s_setprio 0
	s_barrier
	s_add_i32 s71, s71, s40
	v_lshl_add_u64 v[150:151], s[24:25], 0, v[152:153]
	s_mov_b32 m0, s71
	ds_read_b128 v[204:207], v149 offset:16384
	ds_read_b128 v[208:211], v149 offset:17408
	ds_read_b128 v[212:215], v149 offset:18432
	ds_read_b128 v[216:219], v149 offset:19456
	ds_read_b128 v[220:223], v149 offset:20480
	ds_read_b128 v[224:227], v149 offset:21504
	ds_read_b128 v[228:231], v149 offset:22528
	ds_read_b128 v[232:235], v149 offset:23552
	global_load_lds_dwordx4 v[150:151], off
	s_add_i32 m0, s71, 0x2000
	s_add_u32 s72, s24, 0x80000
	v_lshl_add_u64 v[190:191], s[24:25], 0, v[128:129]
	s_addc_u32 s73, s25, 0
	s_add_i32 s71, s74, s40
	global_load_lds_dwordx4 v[190:191], off
	v_lshl_add_u64 v[236:237], s[72:73], 0, v[152:153]
	s_mov_b32 m0, s71
	v_lshl_add_u64 v[238:239], s[26:27], 0, v[130:131]
	global_load_lds_dwordx4 v[236:237], off
	v_lshl_add_u64 v[236:237], s[72:73], 0, v[128:129]
	s_add_i32 m0, s71, 0x2000
	s_nop 0
	global_load_lds_dwordx4 v[236:237], off
	v_lshl_add_u64 v[236:237], s[26:27], 0, v[132:133]
	s_mov_b32 m0, s21
	s_nop 0
	global_load_lds_dwordx4 v[236:237], off
	s_mov_b32 m0, s56
	s_nop 0
	global_load_lds_dwordx4 v[238:239], off
	s_waitcnt vmcnt(8)
	s_waitcnt lgkmcnt(0)
	s_barrier
; #define PG8_STAGE(bufoff, gbase, voff) do { _Pragma("unroll") for (int _i = 0; _i < 2; ++_i) \
;         __builtin_amdgcn_global_load_lds((const unsigned*)((const char*)(gbase) + (voff)[_i]), (LAS unsigned*)(lds + (bufoff) + ldsw + _i * 8192), 16, 0, 0); } while (0)
; #define PG8_LDA(dst, b, h) do { _Pragma("unroll") for (int m = 0; m < 4; ++m) _Pragma("unroll") for (int k = 0; k < 2; ++k) dst[m][k] = *(const LAS bf16x8*)(lds + PG8_SA(b, h) + aoff + m * 2048 + k * 1024); } while (0)
; #define PG8_LDB(dst, b, h) do { _Pragma("unroll") for (int n = 0; n < 2; ++n) _Pragma("unroll") for (int k = 0; k < 2; ++k) dst[n][k] = *(const LAS bf16x8*)(lds + PG8_SB(b, h) + boff + n * 2048 + k * 1024); } while (0)
; #define PG8_MMA(ai, bj, At, Bt) do { __builtin_amdgcn_s_setprio(1); _Pragma("unroll") for (int m = 0; m < 4; ++m) _Pragma("unroll") for (int n = 0; n < 2; ++n) _Pragma("unroll") for (int k = 0; k < 2; ++k) \
;         acc[ai][bj][m][n] = __builtin_amdgcn_mfma_f32_16x16x32_bf16(Bt[n][k], At[m][k], acc[ai][bj][m][n], 0, 0, 0); __builtin_amdgcn_s_setprio(0); } while (0)
; #define PG8_WAIT_V(n) asm volatile("s_waitcnt vmcnt(" #n ")" ::: "memory")
; #define PG8_WAIT_L(n) asm volatile("s_waitcnt lgkmcnt(" #n ")" ::: "memory")
; #define PG8_BAR __builtin_amdgcn_s_barrier()
; #define PG8_SCHED __builtin_amdgcn_sched_barrier(0)
; template <class Epi, class Sched>
; __device__ __forceinline__ void gemm_phase(const int tid, LAS unsigned char* lds, const Gemm g, const Sched& S, const Epi& E) {
;     ...
;             PG8_WAIT_V(8); PG8_WAIT_L(0); PG8_BAR; PG8_MMA(1, 0, At, B0); PG8_MMA(1, 1, At, B1); PG8_BAR; PG8_SCHED;
;             PG8_LDB(B0, 1, 0); PG8_LDB(B1, 1, 1); PG8_SCHED; PG8_LDA(At, 1, 0); PG8_STAGE(PG8_SA(0, 1), a2 + hstep, voffA);
;             PG8_WAIT_V(8); PG8_WAIT_L(0); PG8_BAR; PG8_MMA(0, 0, At, B0); PG8_MMA(0, 1, At, B1); PG8_BAR; PG8_SCHED;
;             PG8_LDA(At, 1, 1); PG8_STAGE(PG8_SB(1, 0), b3, voffB); PG8_STAGE(PG8_SB(1, 1), b3 + hstep, voffB); PG8_STAGE(PG8_SA(1, 0), a3, voffA);
;             PG8_WAIT_V(8); PG8_WAIT_L(0); PG8_BAR; PG8_MMA(1, 0, At, B0); PG8_MMA(1, 1, At, B1); PG8_BAR; PG8_SCHED;
	s_setprio 1
	s_waitcnt lgkmcnt(0)
	v_mfma_f32_16x16x32_bf16 v[60:63], v[138:141], v[204:207], 0
	v_mfma_f32_16x16x32_bf16 v[56:59], v[170:173], v[204:207], 0
	v_mfma_f32_16x16x32_bf16 v[48:51], v[138:141], v[212:215], 0
	v_mfma_f32_16x16x32_bf16 v[40:43], v[170:173], v[212:215], 0
	v_mfma_f32_16x16x32_bf16 v[32:35], v[138:141], v[220:223], 0
	v_mfma_f32_16x16x32_bf16 v[24:27], v[170:173], v[220:223], 0
	v_mfma_f32_16x16x32_bf16 v[16:19], v[138:141], v[228:231], 0
	v_mfma_f32_16x16x32_bf16 v[8:11], v[170:173], v[228:231], 0
	v_mfma_f32_16x16x32_bf16 v[60:63], v[142:145], v[208:211], v[60:63]
	v_mfma_f32_16x16x32_bf16 v[56:59], v[174:177], v[208:211], v[56:59]
	v_mfma_f32_16x16x32_bf16 v[48:51], v[142:145], v[216:219], v[48:51]
	v_mfma_f32_16x16x32_bf16 v[40:43], v[174:177], v[216:219], v[40:43]
	v_mfma_f32_16x16x32_bf16 v[32:35], v[142:145], v[224:227], v[32:35]
	v_mfma_f32_16x16x32_bf16 v[24:27], v[174:177], v[224:227], v[24:27]
	v_mfma_f32_16x16x32_bf16 v[16:19], v[142:145], v[232:235], v[16:19]
	v_mfma_f32_16x16x32_bf16 v[8:11], v[174:177], v[232:235], v[8:11]
	v_mfma_f32_16x16x32_bf16 v[52:55], v[178:181], v[204:207], 0
	v_mfma_f32_16x16x32_bf16 v[44:47], v[186:189], v[204:207], 0
	v_mfma_f32_16x16x32_bf16 v[36:39], v[178:181], v[212:215], 0
	v_mfma_f32_16x16x32_bf16 v[28:31], v[186:189], v[212:215], 0
	v_mfma_f32_16x16x32_bf16 v[20:23], v[178:181], v[220:223], 0
	v_mfma_f32_16x16x32_bf16 v[12:15], v[186:189], v[220:223], 0
	v_mfma_f32_16x16x32_bf16 v[4:7], v[178:181], v[228:231], 0
	v_mfma_f32_16x16x32_bf16 v[0:3], v[186:189], v[228:231], 0
	v_mfma_f32_16x16x32_bf16 v[52:55], v[182:185], v[208:211], v[52:55]
	v_mfma_f32_16x16x32_bf16 v[44:47], v[200:203], v[208:211], v[44:47]
	v_mfma_f32_16x16x32_bf16 v[36:39], v[182:185], v[216:219], v[36:39]
	v_mfma_f32_16x16x32_bf16 v[28:31], v[200:203], v[216:219], v[28:31]
	v_mfma_f32_16x16x32_bf16 v[20:23], v[182:185], v[224:227], v[20:23]
	v_mfma_f32_16x16x32_bf16 v[12:15], v[200:203], v[224:227], v[12:15]
	v_mfma_f32_16x16x32_bf16 v[4:7], v[182:185], v[232:235], v[4:7]
	v_mfma_f32_16x16x32_bf16 v[0:3], v[200:203], v[232:235], v[0:3]
	s_setprio 0
	s_barrier
	s_add_i32 s71, 0, 0x18000
	s_add_i32 s72, 0, 0x1c000
	v_add_u32_e32 v174, s71, v148
	v_add_u32_e32 v199, s72, v148
	ds_read_b128 v[138:141], v174
	ds_read_b128 v[142:145], v174 offset:1024
	ds_read_b128 v[170:173], v174 offset:2048
	ds_read_b128 v[174:177], v174 offset:3072
	ds_read_b128 v[178:181], v199
	ds_read_b128 v[182:185], v199 offset:1024
	ds_read_b128 v[186:189], v199 offset:2048
	ds_read_b128 v[200:203], v199 offset:3072
	s_add_u32 s26, s26, 0x80000
	s_addc_u32 s27, s27, 0
	s_mov_b32 m0, s57
	v_lshl_add_u64 v[240:241], s[26:27], 0, v[132:133]
	ds_read_b128 v[204:207], v149 offset:32768
	ds_read_b128 v[208:211], v149 offset:33792
	ds_read_b128 v[212:215], v149 offset:34816
	ds_read_b128 v[216:219], v149 offset:35840
	ds_read_b128 v[220:223], v149 offset:36864
	ds_read_b128 v[224:227], v149 offset:37888
	ds_read_b128 v[228:231], v149 offset:38912
	ds_read_b128 v[232:235], v149 offset:39936
	global_load_lds_dwordx4 v[240:241], off
	v_lshl_add_u64 v[240:241], s[26:27], 0, v[130:131]
	s_mov_b32 m0, s58
	s_nop 0
	global_load_lds_dwordx4 v[240:241], off
	s_waitcnt vmcnt(8)
	s_waitcnt lgkmcnt(0)
	s_barrier
	s_setprio 1
	s_waitcnt lgkmcnt(0)
	v_mfma_f32_16x16x32_bf16 v[124:127], v[138:141], v[204:207], v[124:127]
	v_mfma_f32_16x16x32_bf16 v[120:123], v[170:173], v[204:207], v[120:123]
	v_mfma_f32_16x16x32_bf16 v[112:115], v[138:141], v[212:215], v[112:115]
	v_mfma_f32_16x16x32_bf16 v[104:107], v[170:173], v[212:215], v[104:107]
	v_mfma_f32_16x16x32_bf16 v[96:99], v[138:141], v[220:223], v[96:99]
	v_mfma_f32_16x16x32_bf16 v[88:91], v[170:173], v[220:223], v[88:91]
	v_mfma_f32_16x16x32_bf16 v[80:83], v[138:141], v[228:231], v[80:83]
	v_mfma_f32_16x16x32_bf16 v[72:75], v[170:173], v[228:231], v[72:75]
	v_mfma_f32_16x16x32_bf16 v[124:127], v[142:145], v[208:211], v[124:127]
	v_mfma_f32_16x16x32_bf16 v[120:123], v[174:177], v[208:211], v[120:123]
	v_mfma_f32_16x16x32_bf16 v[112:115], v[142:145], v[216:219], v[112:115]
	v_mfma_f32_16x16x32_bf16 v[104:107], v[174:177], v[216:219], v[104:107]
	v_mfma_f32_16x16x32_bf16 v[96:99], v[142:145], v[224:227], v[96:99]
	v_mfma_f32_16x16x32_bf16 v[88:91], v[174:177], v[224:227], v[88:91]
	v_mfma_f32_16x16x32_bf16 v[80:83], v[142:145], v[232:235], v[80:83]
	v_mfma_f32_16x16x32_bf16 v[72:75], v[174:177], v[232:235], v[72:75]
	v_mfma_f32_16x16x32_bf16 v[116:119], v[178:181], v[204:207], v[116:119]
	v_mfma_f32_16x16x32_bf16 v[108:111], v[186:189], v[204:207], v[108:111]
	v_mfma_f32_16x16x32_bf16 v[100:103], v[178:181], v[212:215], v[100:103]
	v_mfma_f32_16x16x32_bf16 v[92:95], v[186:189], v[212:215], v[92:95]
	v_mfma_f32_16x16x32_bf16 v[84:87], v[178:181], v[220:223], v[84:87]
	v_mfma_f32_16x16x32_bf16 v[76:79], v[186:189], v[220:223], v[76:79]
	v_mfma_f32_16x16x32_bf16 v[68:71], v[178:181], v[228:231], v[68:71]
	v_mfma_f32_16x16x32_bf16 v[64:67], v[186:189], v[228:231], v[64:67]
	v_mfma_f32_16x16x32_bf16 v[116:119], v[182:185], v[208:211], v[116:119]
	v_mfma_f32_16x16x32_bf16 v[108:111], v[200:203], v[208:211], v[108:111]
	v_mfma_f32_16x16x32_bf16 v[100:103], v[182:185], v[216:219], v[100:103]
	v_mfma_f32_16x16x32_bf16 v[92:95], v[200:203], v[216:219], v[92:95]
	v_mfma_f32_16x16x32_bf16 v[84:87], v[182:185], v[224:227], v[84:87]
	v_mfma_f32_16x16x32_bf16 v[76:79], v[200:203], v[224:227], v[76:79]
	v_mfma_f32_16x16x32_bf16 v[68:71], v[182:185], v[232:235], v[68:71]
	v_mfma_f32_16x16x32_bf16 v[64:67], v[200:203], v[232:235], v[64:67]
	s_setprio 0
	s_barrier
; #define PG8_STAGE(bufoff, gbase, voff) do { _Pragma("unroll") for (int _i = 0; _i < 2; ++_i) \
;         __builtin_amdgcn_global_load_lds((const unsigned*)((const char*)(gbase) + (voff)[_i]), (LAS unsigned*)(lds + (bufoff) + ldsw + _i * 8192), 16, 0, 0); } while (0)
; #define PG8_LDA(dst, b, h) do { _Pragma("unroll") for (int m = 0; m < 4; ++m) _Pragma("unroll") for (int k = 0; k < 2; ++k) dst[m][k] = *(const LAS bf16x8*)(lds + PG8_SA(b, h) + aoff + m * 2048 + k * 1024); } while (0)
; #define PG8_LDB(dst, b, h) do { _Pragma("unroll") for (int n = 0; n < 2; ++n) _Pragma("unroll") for (int k = 0; k < 2; ++k) dst[n][k] = *(const LAS bf16x8*)(lds + PG8_SB(b, h) + boff + n * 2048 + k * 1024); } while (0)
; #define PG8_MMA(ai, bj, At, Bt) do { __builtin_amdgcn_s_setprio(1); _Pragma("unroll") for (int m = 0; m < 4; ++m) _Pragma("unroll") for (int n = 0; n < 2; ++n) _Pragma("unroll") for (int k = 0; k < 2; ++k) \
;         acc[ai][bj][m][n] = __builtin_amdgcn_mfma_f32_16x16x32_bf16(Bt[n][k], At[m][k], acc[ai][bj][m][n], 0, 0, 0); __builtin_amdgcn_s_setprio(0); } while (0)
; #define PG8_WAIT_V(n) asm volatile("s_waitcnt vmcnt(" #n ")" ::: "memory")
; template <class Epi, class Sched>
; __device__ __forceinline__ void gemm_phase(const int tid, LAS unsigned char* lds, const Gemm g, const Sched& S, const Epi& E) {
;     ...
;             PG8_LDB(B0, 0, 0); PG8_LDB(B1, 0, 1); PG8_SCHED; PG8_LDA(At, 0, 0); PG8_STAGE(PG8_SA(1, 1), a1 + hstep, voffA);
;             PG8_WAIT_V(8); PG8_WAIT_L(0); PG8_BAR; PG8_MMA(0, 0, At, B0); PG8_MMA(0, 1, At, B1); PG8_BAR; PG8_SCHED;
;             PG8_LDA(At, 0, 1); PG8_STAGE(PG8_SB(0, 0), b2, voffB); PG8_STAGE(PG8_SB(0, 1), b2 + hstep, voffB); PG8_STAGE(PG8_SA(0, 0), a2, voffA);
;             PG8_WAIT_V(8); PG8_WAIT_L(0); PG8_BAR; PG8_MMA(1, 0, At, B0); PG8_MMA(1, 1, At, B1); PG8_BAR; PG8_SCHED;
;             PG8_LDB(B0, 1, 0); PG8_LDB(B1, 1, 1); PG8_SCHED; PG8_LDA(At, 1, 0); PG8_STAGE(PG8_SA(0, 1), a2 + hstep, voffA);
;             PG8_WAIT_V(8); PG8_WAIT_L(0); PG8_BAR; PG8_MMA(0, 0, At, B0); PG8_MMA(0, 1, At, B1); PG8_BAR; PG8_SCHED;
;             PG8_LDA(At, 1, 1); PG8_STAGE(PG8_SB(1, 0), b3, voffB); PG8_STAGE(PG8_SB(1, 1), b3 + hstep, voffB); PG8_STAGE(PG8_SA(1, 0), a3, voffA);
;             PG8_WAIT_V(8); PG8_WAIT_L(0); PG8_BAR; PG8_MMA(1, 0, At, B0); PG8_MMA(1, 1, At, B1); PG8_BAR; PG8_SCHED;
;         }
	s_add_i32 s26, s71, s40
	v_lshl_add_u64 v[150:151], v[150:151], 0, s[34:35]
	s_mov_b32 m0, s26
	ds_read_b128 v[204:207], v149 offset:49152
	ds_read_b128 v[208:211], v149 offset:50176
	ds_read_b128 v[212:215], v149 offset:51200
	ds_read_b128 v[216:219], v149 offset:52224
	ds_read_b128 v[220:223], v149 offset:53248
	ds_read_b128 v[224:227], v149 offset:54272
	ds_read_b128 v[228:231], v149 offset:55296
	ds_read_b128 v[232:235], v149 offset:56320
	global_load_lds_dwordx4 v[150:151], off
	s_add_i32 m0, s26, 0x2000
	s_add_u32 s24, s24, 0x80080
	v_lshl_add_u64 v[150:151], v[190:191], 0, s[34:35]
	s_addc_u32 s25, s25, 0
	s_add_i32 s26, s72, s40
	global_load_lds_dwordx4 v[150:151], off
	v_lshl_add_u64 v[150:151], s[24:25], 0, v[152:153]
	s_mov_b32 m0, s26
	s_nop 0
	global_load_lds_dwordx4 v[150:151], off
	v_lshl_add_u64 v[150:151], s[24:25], 0, v[128:129]
	s_add_i32 m0, s26, 0x2000
	s_nop 0
	global_load_lds_dwordx4 v[150:151], off
	v_lshl_add_u64 v[150:151], v[236:237], 0, s[34:35]
	s_mov_b32 m0, s61
	s_nop 0
	global_load_lds_dwordx4 v[150:151], off
	v_lshl_add_u64 v[150:151], v[238:239], 0, s[34:35]
	s_mov_b32 m0, s62
	s_nop 0
	global_load_lds_dwordx4 v[150:151], off
	s_waitcnt vmcnt(8)
	s_waitcnt lgkmcnt(0)
	s_barrier
	s_setprio 1
	s_waitcnt lgkmcnt(0)
	v_mfma_f32_16x16x32_bf16 v[60:63], v[138:141], v[204:207], v[60:63]
	v_mfma_f32_16x16x32_bf16 v[56:59], v[170:173], v[204:207], v[56:59]
	v_mfma_f32_16x16x32_bf16 v[48:51], v[138:141], v[212:215], v[48:51]
	v_mfma_f32_16x16x32_bf16 v[40:43], v[170:173], v[212:215], v[40:43]
	v_mfma_f32_16x16x32_bf16 v[32:35], v[138:141], v[220:223], v[32:35]
	v_mfma_f32_16x16x32_bf16 v[24:27], v[170:173], v[220:223], v[24:27]
	v_mfma_f32_16x16x32_bf16 v[16:19], v[138:141], v[228:231], v[16:19]
	v_mfma_f32_16x16x32_bf16 v[8:11], v[170:173], v[228:231], v[8:11]
	v_mfma_f32_16x16x32_bf16 v[60:63], v[142:145], v[208:211], v[60:63]
	v_mfma_f32_16x16x32_bf16 v[56:59], v[174:177], v[208:211], v[56:59]
	v_mfma_f32_16x16x32_bf16 v[48:51], v[142:145], v[216:219], v[48:51]
	v_mfma_f32_16x16x32_bf16 v[40:43], v[174:177], v[216:219], v[40:43]
	v_mfma_f32_16x16x32_bf16 v[32:35], v[142:145], v[224:227], v[32:35]
	v_mfma_f32_16x16x32_bf16 v[24:27], v[174:177], v[224:227], v[24:27]
	v_mfma_f32_16x16x32_bf16 v[16:19], v[142:145], v[232:235], v[16:19]
	v_mfma_f32_16x16x32_bf16 v[8:11], v[174:177], v[232:235], v[8:11]
	v_mfma_f32_16x16x32_bf16 v[52:55], v[178:181], v[204:207], v[52:55]
	v_mfma_f32_16x16x32_bf16 v[44:47], v[186:189], v[204:207], v[44:47]
	v_mfma_f32_16x16x32_bf16 v[36:39], v[178:181], v[212:215], v[36:39]
	v_mfma_f32_16x16x32_bf16 v[28:31], v[186:189], v[212:215], v[28:31]
	v_mfma_f32_16x16x32_bf16 v[20:23], v[178:181], v[220:223], v[20:23]
	v_mfma_f32_16x16x32_bf16 v[12:15], v[186:189], v[220:223], v[12:15]
	v_mfma_f32_16x16x32_bf16 v[4:7], v[178:181], v[228:231], v[4:7]
	v_mfma_f32_16x16x32_bf16 v[0:3], v[186:189], v[228:231], v[0:3]
	v_mfma_f32_16x16x32_bf16 v[52:55], v[182:185], v[208:211], v[52:55]
	v_mfma_f32_16x16x32_bf16 v[44:47], v[200:203], v[208:211], v[44:47]
	v_mfma_f32_16x16x32_bf16 v[36:39], v[182:185], v[216:219], v[36:39]
	v_mfma_f32_16x16x32_bf16 v[28:31], v[200:203], v[216:219], v[28:31]
	v_mfma_f32_16x16x32_bf16 v[20:23], v[182:185], v[224:227], v[20:23]
	v_mfma_f32_16x16x32_bf16 v[12:15], v[200:203], v[224:227], v[12:15]
	v_mfma_f32_16x16x32_bf16 v[4:7], v[182:185], v[232:235], v[4:7]
	v_mfma_f32_16x16x32_bf16 v[0:3], v[200:203], v[232:235], v[0:3]
	s_setprio 0
	s_barrier
	s_add_i32 s70, s70, 2
	s_add_u32 s22, s22, 0x100
	s_addc_u32 s23, s23, 0
	s_add_u32 s68, s68, 0x100
	s_addc_u32 s69, s69, 0
	s_cmp_gt_u32 s70, 29
.LBB0_50:
	s_add_u32 s24, s22, 0xfff80080
	s_addc_u32 s25, s23, -1
	s_add_i32 s71, 0, 0x10000
	s_cmp_eq_u32 s70, 28
	s_cselect_b32 s27, s15, s25
	s_cselect_b32 s26, s66, s24
	v_add_u32_e32 v150, s71, v148
	s_cselect_b32 s25, s13, s69
	s_cselect_b32 s24, s67, s68
	s_add_i32 s74, 0, 0x14000
	ds_read_b128 v[138:141], v150
	ds_read_b128 v[142:145], v150 offset:1024
	ds_read_b128 v[170:173], v150 offset:2048
	ds_read_b128 v[174:177], v150 offset:3072
	v_add_u32_e32 v150, s74, v148
	ds_read_b128 v[178:181], v150
	ds_read_b128 v[182:185], v150 offset:1024
	ds_read_b128 v[186:189], v150 offset:2048
	ds_read_b128 v[200:203], v150 offset:3072
	v_lshl_add_u64 v[150:151], s[22:23], 0, v[134:135]
	s_add_i32 m0, s21, 0xc000
	ds_read_b128 v[204:207], v149
	ds_read_b128 v[208:211], v149 offset:1024
	ds_read_b128 v[212:215], v149 offset:2048
	ds_read_b128 v[216:219], v149 offset:3072
	ds_read_b128 v[220:223], v149 offset:4096
	ds_read_b128 v[224:227], v149 offset:5120
	ds_read_b128 v[228:231], v149 offset:6144
	ds_read_b128 v[232:235], v149 offset:7168
	global_load_lds_dwordx4 v[150:151], off
	v_lshl_add_u64 v[150:151], s[22:23], 0, v[136:137]
	s_add_i32 m0, s21, 0xe000
	s_nop 0
	global_load_lds_dwordx4 v[150:151], off
	s_waitcnt vmcnt(8)
	s_waitcnt lgkmcnt(0)
	s_barrier
; #define PG8_STAGE(bufoff, gbase, voff) do { _Pragma("unroll") for (int _i = 0; _i < 2; ++_i) \
;         __builtin_amdgcn_global_load_lds((const unsigned*)((const char*)(gbase) + (voff)[_i]), (LAS unsigned*)(lds + (bufoff) + ldsw + _i * 8192), 16, 0, 0); } while (0)
; #define PG8_LDA(dst, b, h) do { _Pragma("unroll") for (int m = 0; m < 4; ++m) _Pragma("unroll") for (int k = 0; k < 2; ++k) dst[m][k] = *(const LAS bf16x8*)(lds + PG8_SA(b, h) + aoff + m * 2048 + k * 1024); } while (0)
; #define PG8_LDB(dst, b, h) do { _Pragma("unroll") for (int n = 0; n < 2; ++n) _Pragma("unroll") for (int k = 0; k < 2; ++k) dst[n][k] = *(const LAS bf16x8*)(lds + PG8_SB(b, h) + boff + n * 2048 + k * 1024); } while (0)
; #define PG8_MMA(ai, bj, At, Bt) do { __builtin_amdgcn_s_setprio(1); _Pragma("unroll") for (int m = 0; m < 4; ++m) _Pragma("unroll") for (int n = 0; n < 2; ++n) _Pragma("unroll") for (int k = 0; k < 2; ++k) \
;         acc[ai][bj][m][n] = __builtin_amdgcn_mfma_f32_16x16x32_bf16(Bt[n][k], At[m][k], acc[ai][bj][m][n], 0, 0, 0); __builtin_amdgcn_s_setprio(0); } while (0)
; #define PG8_WAIT_V(n) asm volatile("s_waitcnt vmcnt(" #n ")" ::: "memory")
; #define PG8_WAIT_L(n) asm volatile("s_waitcnt lgkmcnt(" #n ")" ::: "memory")
; #define PG8_BAR __builtin_amdgcn_s_barrier()
; #define PG8_SCHED __builtin_amdgcn_sched_barrier(0)
; template <class Epi, class Sched>
; __device__ __forceinline__ void gemm_phase(const int tid, LAS unsigned char* lds, const Gemm g, const Sched& S, const Epi& E) {
;     ...
;             PG8_LDB(B0, 0, 0); PG8_LDB(B1, 0, 1); PG8_SCHED; PG8_LDA(At, 0, 0); PG8_STAGE(PG8_SA(1, 1), a1 + hstep, voffA);
;             PG8_WAIT_V(8); PG8_WAIT_L(0); PG8_BAR; PG8_MMA(0, 0, At, B0); PG8_MMA(0, 1, At, B1); PG8_BAR; PG8_SCHED;
;             PG8_LDA(At, 0, 1); PG8_STAGE(PG8_SB(0, 0), b2, voffB); PG8_STAGE(PG8_SB(0, 1), b2 + hstep, voffB); PG8_STAGE(PG8_SA(0, 0), a2, voffA);
;             PG8_WAIT_V(8); PG8_WAIT_L(0); PG8_BAR; PG8_MMA(1, 0, At, B0); PG8_MMA(1, 1, At, B1); PG8_BAR; PG8_SCHED;
	s_setprio 1
	s_waitcnt lgkmcnt(0)
	v_mfma_f32_16x16x32_bf16 v[124:127], v[138:141], v[204:207], v[124:127]
	v_mfma_f32_16x16x32_bf16 v[120:123], v[170:173], v[204:207], v[120:123]
	v_mfma_f32_16x16x32_bf16 v[112:115], v[138:141], v[212:215], v[112:115]
	v_mfma_f32_16x16x32_bf16 v[104:107], v[170:173], v[212:215], v[104:107]
	v_mfma_f32_16x16x32_bf16 v[96:99], v[138:141], v[220:223], v[96:99]
	v_mfma_f32_16x16x32_bf16 v[88:91], v[170:173], v[220:223], v[88:91]
	v_mfma_f32_16x16x32_bf16 v[80:83], v[138:141], v[228:231], v[80:83]
	v_mfma_f32_16x16x32_bf16 v[72:75], v[170:173], v[228:231], v[72:75]
	v_mfma_f32_16x16x32_bf16 v[124:127], v[142:145], v[208:211], v[124:127]
	v_mfma_f32_16x16x32_bf16 v[120:123], v[174:177], v[208:211], v[120:123]
	v_mfma_f32_16x16x32_bf16 v[112:115], v[142:145], v[216:219], v[112:115]
	v_mfma_f32_16x16x32_bf16 v[104:107], v[174:177], v[216:219], v[104:107]
	v_mfma_f32_16x16x32_bf16 v[96:99], v[142:145], v[224:227], v[96:99]
	v_mfma_f32_16x16x32_bf16 v[88:91], v[174:177], v[224:227], v[88:91]
	v_mfma_f32_16x16x32_bf16 v[80:83], v[142:145], v[232:235], v[80:83]
	v_mfma_f32_16x16x32_bf16 v[72:75], v[174:177], v[232:235], v[72:75]
	v_mfma_f32_16x16x32_bf16 v[116:119], v[178:181], v[204:207], v[116:119]
	v_mfma_f32_16x16x32_bf16 v[108:111], v[186:189], v[204:207], v[108:111]
	v_mfma_f32_16x16x32_bf16 v[100:103], v[178:181], v[212:215], v[100:103]
	v_mfma_f32_16x16x32_bf16 v[92:95], v[186:189], v[212:215], v[92:95]
	v_mfma_f32_16x16x32_bf16 v[84:87], v[178:181], v[220:223], v[84:87]
	v_mfma_f32_16x16x32_bf16 v[76:79], v[186:189], v[220:223], v[76:79]
	v_mfma_f32_16x16x32_bf16 v[68:71], v[178:181], v[228:231], v[68:71]
	v_mfma_f32_16x16x32_bf16 v[64:67], v[186:189], v[228:231], v[64:67]
	v_mfma_f32_16x16x32_bf16 v[116:119], v[182:185], v[208:211], v[116:119]
	v_mfma_f32_16x16x32_bf16 v[108:111], v[200:203], v[208:211], v[108:111]
	v_mfma_f32_16x16x32_bf16 v[100:103], v[182:185], v[216:219], v[100:103]
	v_mfma_f32_16x16x32_bf16 v[92:95], v[200:203], v[216:219], v[92:95]
	v_mfma_f32_16x16x32_bf16 v[84:87], v[182:185], v[224:227], v[84:87]
	v_mfma_f32_16x16x32_bf16 v[76:79], v[200:203], v[224:227], v[76:79]
	v_mfma_f32_16x16x32_bf16 v[68:71], v[182:185], v[232:235], v[68:71]
	v_mfma_f32_16x16x32_bf16 v[64:67], v[200:203], v[232:235], v[64:67]
	s_setprio 0
	s_barrier
	s_add_i32 s71, s71, s40
	v_lshl_add_u64 v[150:151], s[24:25], 0, v[152:153]
	s_mov_b32 m0, s71
	ds_read_b128 v[204:207], v149 offset:16384
	ds_read_b128 v[208:211], v149 offset:17408
	ds_read_b128 v[212:215], v149 offset:18432
	ds_read_b128 v[216:219], v149 offset:19456
	ds_read_b128 v[220:223], v149 offset:20480
	ds_read_b128 v[224:227], v149 offset:21504
	ds_read_b128 v[228:231], v149 offset:22528
	ds_read_b128 v[232:235], v149 offset:23552
	global_load_lds_dwordx4 v[150:151], off
	s_add_i32 m0, s71, 0x2000
	s_add_u32 s72, s24, 0x80000
	v_lshl_add_u64 v[190:191], s[24:25], 0, v[128:129]
	s_addc_u32 s73, s25, 0
	s_add_i32 s71, s74, s40
	global_load_lds_dwordx4 v[190:191], off
	v_lshl_add_u64 v[236:237], s[72:73], 0, v[152:153]
	s_mov_b32 m0, s71
	v_lshl_add_u64 v[238:239], s[26:27], 0, v[130:131]
	global_load_lds_dwordx4 v[236:237], off
	v_lshl_add_u64 v[236:237], s[72:73], 0, v[128:129]
	s_add_i32 m0, s71, 0x2000
	s_nop 0
	global_load_lds_dwordx4 v[236:237], off
	v_lshl_add_u64 v[236:237], s[26:27], 0, v[132:133]
	s_mov_b32 m0, s21
	s_nop 0
	global_load_lds_dwordx4 v[236:237], off
	s_mov_b32 m0, s56
	s_nop 0
	global_load_lds_dwordx4 v[238:239], off
	s_waitcnt vmcnt(8)
	s_waitcnt lgkmcnt(0)
	s_barrier
	s_setprio 1
	s_waitcnt lgkmcnt(0)
	v_mfma_f32_16x16x32_bf16 v[60:63], v[138:141], v[204:207], v[60:63]
	v_mfma_f32_16x16x32_bf16 v[56:59], v[170:173], v[204:207], v[56:59]
	v_mfma_f32_16x16x32_bf16 v[48:51], v[138:141], v[212:215], v[48:51]
	v_mfma_f32_16x16x32_bf16 v[40:43], v[170:173], v[212:215], v[40:43]
	v_mfma_f32_16x16x32_bf16 v[32:35], v[138:141], v[220:223], v[32:35]
	v_mfma_f32_16x16x32_bf16 v[24:27], v[170:173], v[220:223], v[24:27]
	v_mfma_f32_16x16x32_bf16 v[16:19], v[138:141], v[228:231], v[16:19]
	v_mfma_f32_16x16x32_bf16 v[8:11], v[170:173], v[228:231], v[8:11]
	v_mfma_f32_16x16x32_bf16 v[60:63], v[142:145], v[208:211], v[60:63]
	v_mfma_f32_16x16x32_bf16 v[56:59], v[174:177], v[208:211], v[56:59]
	v_mfma_f32_16x16x32_bf16 v[48:51], v[142:145], v[216:219], v[48:51]
	v_mfma_f32_16x16x32_bf16 v[40:43], v[174:177], v[216:219], v[40:43]
	v_mfma_f32_16x16x32_bf16 v[32:35], v[142:145], v[224:227], v[32:35]
	v_mfma_f32_16x16x32_bf16 v[24:27], v[174:177], v[224:227], v[24:27]
	v_mfma_f32_16x16x32_bf16 v[16:19], v[142:145], v[232:235], v[16:19]
	v_mfma_f32_16x16x32_bf16 v[8:11], v[174:177], v[232:235], v[8:11]
	v_mfma_f32_16x16x32_bf16 v[52:55], v[178:181], v[204:207], v[52:55]
	v_mfma_f32_16x16x32_bf16 v[44:47], v[186:189], v[204:207], v[44:47]
	v_mfma_f32_16x16x32_bf16 v[36:39], v[178:181], v[212:215], v[36:39]
	v_mfma_f32_16x16x32_bf16 v[28:31], v[186:189], v[212:215], v[28:31]
	v_mfma_f32_16x16x32_bf16 v[20:23], v[178:181], v[220:223], v[20:23]
	v_mfma_f32_16x16x32_bf16 v[12:15], v[186:189], v[220:223], v[12:15]
	v_mfma_f32_16x16x32_bf16 v[4:7], v[178:181], v[228:231], v[4:7]
	v_mfma_f32_16x16x32_bf16 v[0:3], v[186:189], v[228:231], v[0:3]
	v_mfma_f32_16x16x32_bf16 v[52:55], v[182:185], v[208:211], v[52:55]
	v_mfma_f32_16x16x32_bf16 v[44:47], v[200:203], v[208:211], v[44:47]
	v_mfma_f32_16x16x32_bf16 v[36:39], v[182:185], v[216:219], v[36:39]
	v_mfma_f32_16x16x32_bf16 v[28:31], v[200:203], v[216:219], v[28:31]
	v_mfma_f32_16x16x32_bf16 v[20:23], v[182:185], v[224:227], v[20:23]
	v_mfma_f32_16x16x32_bf16 v[12:15], v[200:203], v[224:227], v[12:15]
	v_mfma_f32_16x16x32_bf16 v[4:7], v[182:185], v[232:235], v[4:7]
	v_mfma_f32_16x16x32_bf16 v[0:3], v[200:203], v[232:235], v[0:3]
	s_setprio 0
	s_barrier
; #define PG8_STAGE(bufoff, gbase, voff) do { _Pragma("unroll") for (int _i = 0; _i < 2; ++_i) \
;         __builtin_amdgcn_global_load_lds((const unsigned*)((const char*)(gbase) + (voff)[_i]), (LAS unsigned*)(lds + (bufoff) + ldsw + _i * 8192), 16, 0, 0); } while (0)
; #define PG8_LDA(dst, b, h) do { _Pragma("unroll") for (int m = 0; m < 4; ++m) _Pragma("unroll") for (int k = 0; k < 2; ++k) dst[m][k] = *(const LAS bf16x8*)(lds + PG8_SA(b, h) + aoff + m * 2048 + k * 1024); } while (0)
; #define PG8_LDB(dst, b, h) do { _Pragma("unroll") for (int n = 0; n < 2; ++n) _Pragma("unroll") for (int k = 0; k < 2; ++k) dst[n][k] = *(const LAS bf16x8*)(lds + PG8_SB(b, h) + boff + n * 2048 + k * 1024); } while (0)
; #define PG8_MMA(ai, bj, At, Bt) do { __builtin_amdgcn_s_setprio(1); _Pragma("unroll") for (int m = 0; m < 4; ++m) _Pragma("unroll") for (int n = 0; n < 2; ++n) _Pragma("unroll") for (int k = 0; k < 2; ++k) \
;         acc[ai][bj][m][n] = __builtin_amdgcn_mfma_f32_16x16x32_bf16(Bt[n][k], At[m][k], acc[ai][bj][m][n], 0, 0, 0); __builtin_amdgcn_s_setprio(0); } while (0)
; #define PG8_WAIT_V(n) asm volatile("s_waitcnt vmcnt(" #n ")" ::: "memory")
; #define PG8_WAIT_L(n) asm volatile("s_waitcnt lgkmcnt(" #n ")" ::: "memory")
; #define PG8_BAR __builtin_amdgcn_s_barrier()
; #define PG8_SCHED __builtin_amdgcn_sched_barrier(0)
; template <class Epi, class Sched>
; __device__ __forceinline__ void gemm_phase(const int tid, LAS unsigned char* lds, const Gemm g, const Sched& S, const Epi& E) {
;     ...
;             PG8_LDB(B0, 1, 0); PG8_LDB(B1, 1, 1); PG8_SCHED; PG8_LDA(At, 1, 0); PG8_STAGE(PG8_SA(0, 1), a2 + hstep, voffA);
;             PG8_WAIT_V(8); PG8_WAIT_L(0); PG8_BAR; PG8_MMA(0, 0, At, B0); PG8_MMA(0, 1, At, B1); PG8_BAR; PG8_SCHED;
	s_add_i32 s71, 0, 0x18000
	s_add_i32 s72, 0, 0x1c000
	v_add_u32_e32 v174, s71, v148
	v_add_u32_e32 v199, s72, v148
	ds_read_b128 v[138:141], v174
	ds_read_b128 v[142:145], v174 offset:1024
	ds_read_b128 v[170:173], v174 offset:2048
	ds_read_b128 v[174:177], v174 offset:3072
	ds_read_b128 v[178:181], v199
	ds_read_b128 v[182:185], v199 offset:1024
	ds_read_b128 v[186:189], v199 offset:2048
	ds_read_b128 v[200:203], v199 offset:3072
	s_add_u32 s26, s26, 0x80000
	s_addc_u32 s27, s27, 0
	s_mov_b32 m0, s57
	v_lshl_add_u64 v[240:241], s[26:27], 0, v[132:133]
	ds_read_b128 v[204:207], v149 offset:32768
	ds_read_b128 v[208:211], v149 offset:33792
	ds_read_b128 v[212:215], v149 offset:34816
	ds_read_b128 v[216:219], v149 offset:35840
	ds_read_b128 v[220:223], v149 offset:36864
	ds_read_b128 v[224:227], v149 offset:37888
	ds_read_b128 v[228:231], v149 offset:38912
	ds_read_b128 v[232:235], v149 offset:39936
	global_load_lds_dwordx4 v[240:241], off
	v_lshl_add_u64 v[240:241], s[26:27], 0, v[130:131]
	s_mov_b32 m0, s58
	s_nop 0
	global_load_lds_dwordx4 v[240:241], off
	s_waitcnt vmcnt(8)
	s_waitcnt lgkmcnt(0)
	s_barrier
	s_setprio 1
	s_waitcnt lgkmcnt(0)
	v_mfma_f32_16x16x32_bf16 v[124:127], v[138:141], v[204:207], v[124:127]
	v_mfma_f32_16x16x32_bf16 v[120:123], v[170:173], v[204:207], v[120:123]
	v_mfma_f32_16x16x32_bf16 v[112:115], v[138:141], v[212:215], v[112:115]
	v_mfma_f32_16x16x32_bf16 v[104:107], v[170:173], v[212:215], v[104:107]
	v_mfma_f32_16x16x32_bf16 v[96:99], v[138:141], v[220:223], v[96:99]
	v_mfma_f32_16x16x32_bf16 v[88:91], v[170:173], v[220:223], v[88:91]
	v_mfma_f32_16x16x32_bf16 v[80:83], v[138:141], v[228:231], v[80:83]
	v_mfma_f32_16x16x32_bf16 v[72:75], v[170:173], v[228:231], v[72:75]
	v_mfma_f32_16x16x32_bf16 v[124:127], v[142:145], v[208:211], v[124:127]
	v_mfma_f32_16x16x32_bf16 v[120:123], v[174:177], v[208:211], v[120:123]
	v_mfma_f32_16x16x32_bf16 v[112:115], v[142:145], v[216:219], v[112:115]
	v_mfma_f32_16x16x32_bf16 v[104:107], v[174:177], v[216:219], v[104:107]
	v_mfma_f32_16x16x32_bf16 v[96:99], v[142:145], v[224:227], v[96:99]
	v_mfma_f32_16x16x32_bf16 v[88:91], v[174:177], v[224:227], v[88:91]
	v_mfma_f32_16x16x32_bf16 v[80:83], v[142:145], v[232:235], v[80:83]
	v_mfma_f32_16x16x32_bf16 v[72:75], v[174:177], v[232:235], v[72:75]
	v_mfma_f32_16x16x32_bf16 v[116:119], v[178:181], v[204:207], v[116:119]
	v_mfma_f32_16x16x32_bf16 v[108:111], v[186:189], v[204:207], v[108:111]
	v_mfma_f32_16x16x32_bf16 v[100:103], v[178:181], v[212:215], v[100:103]
	v_mfma_f32_16x16x32_bf16 v[92:95], v[186:189], v[212:215], v[92:95]
	v_mfma_f32_16x16x32_bf16 v[84:87], v[178:181], v[220:223], v[84:87]
	v_mfma_f32_16x16x32_bf16 v[76:79], v[186:189], v[220:223], v[76:79]
	v_mfma_f32_16x16x32_bf16 v[68:71], v[178:181], v[228:231], v[68:71]
	v_mfma_f32_16x16x32_bf16 v[64:67], v[186:189], v[228:231], v[64:67]
	v_mfma_f32_16x16x32_bf16 v[116:119], v[182:185], v[208:211], v[116:119]
	v_mfma_f32_16x16x32_bf16 v[108:111], v[200:203], v[208:211], v[108:111]
	v_mfma_f32_16x16x32_bf16 v[100:103], v[182:185], v[216:219], v[100:103]
	v_mfma_f32_16x16x32_bf16 v[92:95], v[200:203], v[216:219], v[92:95]
	v_mfma_f32_16x16x32_bf16 v[84:87], v[182:185], v[224:227], v[84:87]
	v_mfma_f32_16x16x32_bf16 v[76:79], v[200:203], v[224:227], v[76:79]
	v_mfma_f32_16x16x32_bf16 v[68:71], v[182:185], v[232:235], v[68:71]
	v_mfma_f32_16x16x32_bf16 v[64:67], v[200:203], v[232:235], v[64:67]
	s_setprio 0
	s_barrier
; #define PG8_STAGE(bufoff, gbase, voff) do { _Pragma("unroll") for (int _i = 0; _i < 2; ++_i) \
;         __builtin_amdgcn_global_load_lds((const unsigned*)((const char*)(gbase) + (voff)[_i]), (LAS unsigned*)(lds + (bufoff) + ldsw + _i * 8192), 16, 0, 0); } while (0)
; #define PG8_LDA(dst, b, h) do { _Pragma("unroll") for (int m = 0; m < 4; ++m) _Pragma("unroll") for (int k = 0; k < 2; ++k) dst[m][k] = *(const LAS bf16x8*)(lds + PG8_SA(b, h) + aoff + m * 2048 + k * 1024); } while (0)
; #define PG8_MMA(ai, bj, At, Bt) do { __builtin_amdgcn_s_setprio(1); _Pragma("unroll") for (int m = 0; m < 4; ++m) _Pragma("unroll") for (int n = 0; n < 2; ++n) _Pragma("unroll") for (int k = 0; k < 2; ++k) \
;         acc[ai][bj][m][n] = __builtin_amdgcn_mfma_f32_16x16x32_bf16(Bt[n][k], At[m][k], acc[ai][bj][m][n], 0, 0, 0); __builtin_amdgcn_s_setprio(0); } while (0)
; #define PG8_WAIT_V(n) asm volatile("s_waitcnt vmcnt(" #n ")" ::: "memory")
; #define PG8_WAIT_L(n) asm volatile("s_waitcnt lgkmcnt(" #n ")" ::: "memory")
; #define PG8_BAR __builtin_amdgcn_s_barrier()
; #define PG8_SCHED __builtin_amdgcn_sched_barrier(0)
; template <class Epi, class Sched>
; __device__ __forceinline__ void gemm_phase(const int tid, LAS unsigned char* lds, const Gemm g, const Sched& S, const Epi& E) {
;     ...
;             PG8_LDA(At, 1, 1); PG8_STAGE(PG8_SB(1, 0), b3, voffB); PG8_STAGE(PG8_SB(1, 1), b3 + hstep, voffB); PG8_STAGE(PG8_SA(1, 0), a3, voffA);
;             PG8_WAIT_V(8); PG8_WAIT_L(0); PG8_BAR; PG8_MMA(1, 0, At, B0); PG8_MMA(1, 1, At, B1); PG8_BAR; PG8_SCHED;
;         }
	s_add_i32 s26, s71, s40
	v_lshl_add_u64 v[150:151], v[150:151], 0, s[34:35]
	s_mov_b32 m0, s26
	ds_read_b128 v[204:207], v149 offset:49152
	ds_read_b128 v[208:211], v149 offset:50176
	ds_read_b128 v[212:215], v149 offset:51200
	ds_read_b128 v[216:219], v149 offset:52224
	ds_read_b128 v[220:223], v149 offset:53248
	ds_read_b128 v[224:227], v149 offset:54272
	ds_read_b128 v[228:231], v149 offset:55296
	ds_read_b128 v[232:235], v149 offset:56320
	global_load_lds_dwordx4 v[150:151], off
	s_add_i32 m0, s26, 0x2000
	s_add_u32 s24, s24, 0x80080
	v_lshl_add_u64 v[150:151], v[190:191], 0, s[34:35]
	s_addc_u32 s25, s25, 0
	s_add_i32 s26, s72, s40
	global_load_lds_dwordx4 v[150:151], off
	v_lshl_add_u64 v[150:151], s[24:25], 0, v[152:153]
	s_mov_b32 m0, s26
	s_nop 0
	global_load_lds_dwordx4 v[150:151], off
	v_lshl_add_u64 v[150:151], s[24:25], 0, v[128:129]
	s_add_i32 m0, s26, 0x2000
	s_nop 0
	global_load_lds_dwordx4 v[150:151], off
	v_lshl_add_u64 v[150:151], v[236:237], 0, s[34:35]
	s_mov_b32 m0, s61
	s_nop 0
	global_load_lds_dwordx4 v[150:151], off
	v_lshl_add_u64 v[150:151], v[238:239], 0, s[34:35]
	s_mov_b32 m0, s62
	s_nop 0
	global_load_lds_dwordx4 v[150:151], off
	s_waitcnt vmcnt(8)
	s_waitcnt lgkmcnt(0)
	s_barrier
	s_setprio 1
	s_waitcnt lgkmcnt(0)
	v_mfma_f32_16x16x32_bf16 v[60:63], v[138:141], v[204:207], v[60:63]
	v_mfma_f32_16x16x32_bf16 v[56:59], v[170:173], v[204:207], v[56:59]
	v_mfma_f32_16x16x32_bf16 v[48:51], v[138:141], v[212:215], v[48:51]
	v_mfma_f32_16x16x32_bf16 v[40:43], v[170:173], v[212:215], v[40:43]
	v_mfma_f32_16x16x32_bf16 v[32:35], v[138:141], v[220:223], v[32:35]
	v_mfma_f32_16x16x32_bf16 v[24:27], v[170:173], v[220:223], v[24:27]
	v_mfma_f32_16x16x32_bf16 v[16:19], v[138:141], v[228:231], v[16:19]
	v_mfma_f32_16x16x32_bf16 v[8:11], v[170:173], v[228:231], v[8:11]
	v_mfma_f32_16x16x32_bf16 v[60:63], v[142:145], v[208:211], v[60:63]
	v_mfma_f32_16x16x32_bf16 v[56:59], v[174:177], v[208:211], v[56:59]
	v_mfma_f32_16x16x32_bf16 v[48:51], v[142:145], v[216:219], v[48:51]
	v_mfma_f32_16x16x32_bf16 v[40:43], v[174:177], v[216:219], v[40:43]
	v_mfma_f32_16x16x32_bf16 v[32:35], v[142:145], v[224:227], v[32:35]
	v_mfma_f32_16x16x32_bf16 v[24:27], v[174:177], v[224:227], v[24:27]
	v_mfma_f32_16x16x32_bf16 v[16:19], v[142:145], v[232:235], v[16:19]
	v_mfma_f32_16x16x32_bf16 v[8:11], v[174:177], v[232:235], v[8:11]
	v_mfma_f32_16x16x32_bf16 v[52:55], v[178:181], v[204:207], v[52:55]
	v_mfma_f32_16x16x32_bf16 v[44:47], v[186:189], v[204:207], v[44:47]
	v_mfma_f32_16x16x32_bf16 v[36:39], v[178:181], v[212:215], v[36:39]
	v_mfma_f32_16x16x32_bf16 v[28:31], v[186:189], v[212:215], v[28:31]
	v_mfma_f32_16x16x32_bf16 v[20:23], v[178:181], v[220:223], v[20:23]
	v_mfma_f32_16x16x32_bf16 v[12:15], v[186:189], v[220:223], v[12:15]
	v_mfma_f32_16x16x32_bf16 v[4:7], v[178:181], v[228:231], v[4:7]
	v_mfma_f32_16x16x32_bf16 v[0:3], v[186:189], v[228:231], v[0:3]
	v_mfma_f32_16x16x32_bf16 v[52:55], v[182:185], v[208:211], v[52:55]
	v_mfma_f32_16x16x32_bf16 v[44:47], v[200:203], v[208:211], v[44:47]
	v_mfma_f32_16x16x32_bf16 v[36:39], v[182:185], v[216:219], v[36:39]
	v_mfma_f32_16x16x32_bf16 v[28:31], v[200:203], v[216:219], v[28:31]
	v_mfma_f32_16x16x32_bf16 v[20:23], v[182:185], v[224:227], v[20:23]
	v_mfma_f32_16x16x32_bf16 v[12:15], v[200:203], v[224:227], v[12:15]
	v_mfma_f32_16x16x32_bf16 v[4:7], v[182:185], v[232:235], v[4:7]
	v_mfma_f32_16x16x32_bf16 v[0:3], v[200:203], v[232:235], v[0:3]
	s_setprio 0
	s_barrier
	s_add_i32 s70, s70, 2
	s_add_u32 s22, s22, 0x100
	s_addc_u32 s23, s23, 0
	s_add_u32 s68, s68, 0x100
	s_addc_u32 s69, s69, 0
	s_cmp_gt_u32 s70, 29
	s_cbranch_scc0 .LBB0_50
	s_and_b64 vcc, exec, s[10:11]
	s_cbranch_vccz .LBB0_53
	s_barrier

; #define PG8_STAGE(bufoff, gbase, voff) do { _Pragma("unroll") for (int _i = 0; _i < 2; ++_i) \
;         __builtin_amdgcn_global_load_lds((const unsigned*)((const char*)(gbase) + (voff)[_i]), (LAS unsigned*)(lds + (bufoff) + ldsw + _i * 8192), 16, 0, 0); } while (0)
; #define PG8_LDA(dst, b, h) do { _Pragma("unroll") for (int m = 0; m < 4; ++m) _Pragma("unroll") for (int k = 0; k < 2; ++k) dst[m][k] = *(const LAS bf16x8*)(lds + PG8_SA(b, h) + aoff + m * 2048 + k * 1024); } while (0)
; #define PG8_LDB(dst, b, h) do { _Pragma("unroll") for (int n = 0; n < 2; ++n) _Pragma("unroll") for (int k = 0; k < 2; ++k) dst[n][k] = *(const LAS bf16x8*)(lds + PG8_SB(b, h) + boff + n * 2048 + k * 1024); } while (0)
; #define PG8_MMA(ai, bj, At, Bt) do { __builtin_amdgcn_s_setprio(1); _Pragma("unroll") for (int m = 0; m < 4; ++m) _Pragma("unroll") for (int n = 0; n < 2; ++n) _Pragma("unroll") for (int k = 0; k < 2; ++k) \
;         acc[ai][bj][m][n] = __builtin_amdgcn_mfma_f32_16x16x32_bf16(Bt[n][k], At[m][k], acc[ai][bj][m][n], 0, 0, 0); __builtin_amdgcn_s_setprio(0); } while (0)
; template <class Epi, class Sched>
; __device__ __forceinline__ void gemm_phase(const int tid, LAS unsigned char* lds, const Gemm g, const Sched& S, const Epi& E) {
;     ...
;         const bool has_next = S.next(ui + 1, nxt);
;         const char* nA = has_next ? (const char*)g.A + (size_t)nxt.pm * tstep : cA; const char* nB = has_next ? (const char*)g.Bt + (size_t)nxt.pn * tstep : cB;
;         for (int t = 0; t < nt; t += 2) {
;             const bool last = (t == nt - 2);
;             const char* a1 = cA + (size_t)(t + 1) * kstep;
;             const char* a2 = last ? nA : cA + (size_t)(t + 2) * kstep; const char* b2 = last ? nB : cB + (size_t)(t + 2) * kstep;
;             const char* a3 = a2 + kstep; const char* b3 = b2 + kstep;
;             if (last && has_next) S.a_ready(nxt);
;             PG8_LDB(B0, 0, 0); PG8_LDB(B1, 0, 1); PG8_SCHED; PG8_LDA(At, 0, 0); PG8_STAGE(PG8_SA(1, 1), a1 + hstep, voffA);
;             PG8_WAIT_V(8); PG8_WAIT_L(0); PG8_BAR; PG8_MMA(0, 0, At, B0); PG8_MMA(0, 1, At, B1); PG8_BAR; PG8_SCHED;
;             PG8_LDA(At, 0, 1); PG8_STAGE(PG8_SB(0, 0), b2, voffB); PG8_STAGE(PG8_SB(0, 1), b2 + hstep, voffB); PG8_STAGE(PG8_SA(0, 0), a2, voffA);
;             PG8_WAIT_V(8); PG8_WAIT_L(0); PG8_BAR; PG8_MMA(1, 0, At, B0); PG8_MMA(1, 1, At, B1); PG8_BAR; PG8_SCHED;
.LBB0_394:
	s_ashr_i32 s15, s14, 31
	s_lshl_b64 s[16:17], s[14:15], 18
	s_add_u32 s16, s40, s16
	s_addc_u32 s17, s41, s17
	s_and_b64 s[18:19], s[0:1], exec
	s_cselect_b32 s15, s17, s23
	s_cselect_b32 s66, s16, s22
	s_ashr_i32 s13, s12, 31
	s_lshl_b64 s[18:19], s[12:13], 18
	s_add_u32 s18, s38, s18
	s_addc_u32 s19, s39, s19
	s_and_b64 s[26:27], s[0:1], exec
	s_cselect_b32 s13, s19, s25
	s_cselect_b32 s67, s18, s24
	s_add_u32 s22, s22, 0x20080
	s_addc_u32 s23, s23, 0
	s_add_u32 s68, s24, 0x100
	v_mov_b32_e32 v0, 0
	s_addc_u32 s69, s25, 0
	s_mov_b32 s70, -2
	s_add_u32 s24, s22, 0xfffe0080
	s_addc_u32 s25, s23, -1
	s_add_i32 s71, 0, 0x10000
	s_cmp_eq_u32 s70, 4
	s_cselect_b32 s27, s15, s25
	s_cselect_b32 s26, s66, s24
	v_add_u32_e32 v150, s71, v144
	s_cselect_b32 s25, s13, s69
	s_cselect_b32 s24, s67, s68
	s_add_i32 s74, 0, 0x14000
	ds_read_b128 v[138:141], v150
	ds_read_b128 v[146:149], v150 offset:1024
	ds_read_b128 v[170:173], v150 offset:2048
	ds_read_b128 v[174:177], v150 offset:3072
	v_add_u32_e32 v150, s74, v144
	ds_read_b128 v[178:181], v150
	ds_read_b128 v[182:185], v150 offset:1024
	ds_read_b128 v[186:189], v150 offset:2048
	ds_read_b128 v[200:203], v150 offset:3072
	v_lshl_add_u64 v[150:151], s[22:23], 0, v[134:135]
	s_add_i32 m0, s21, 0xc000
	ds_read_b128 v[204:207], v145
	ds_read_b128 v[208:211], v145 offset:1024
	ds_read_b128 v[212:215], v145 offset:2048
	ds_read_b128 v[216:219], v145 offset:3072
	ds_read_b128 v[220:223], v145 offset:4096
	ds_read_b128 v[224:227], v145 offset:5120
	ds_read_b128 v[228:231], v145 offset:6144
	ds_read_b128 v[232:235], v145 offset:7168
	global_load_lds_dwordx4 v[150:151], off
	v_lshl_add_u64 v[150:151], s[22:23], 0, v[136:137]
	s_add_i32 m0, s21, 0xe000
	s_nop 0
	global_load_lds_dwordx4 v[150:151], off
	s_waitcnt vmcnt(8)
	s_waitcnt lgkmcnt(0)
	s_barrier
	s_setprio 1
	s_waitcnt lgkmcnt(0)
	v_mfma_f32_16x16x32_bf16 v[124:127], v[138:141], v[204:207], 0
	v_mfma_f32_16x16x32_bf16 v[120:123], v[170:173], v[204:207], 0
	v_mfma_f32_16x16x32_bf16 v[108:111], v[138:141], v[212:215], 0
	v_mfma_f32_16x16x32_bf16 v[104:107], v[170:173], v[212:215], 0
	v_mfma_f32_16x16x32_bf16 v[92:95], v[138:141], v[220:223], 0
	v_mfma_f32_16x16x32_bf16 v[88:91], v[170:173], v[220:223], 0
	v_mfma_f32_16x16x32_bf16 v[76:79], v[138:141], v[228:231], 0
	v_mfma_f32_16x16x32_bf16 v[72:75], v[170:173], v[228:231], 0
	v_mfma_f32_16x16x32_bf16 v[124:127], v[146:149], v[208:211], v[124:127]
	v_mfma_f32_16x16x32_bf16 v[120:123], v[174:177], v[208:211], v[120:123]
	v_mfma_f32_16x16x32_bf16 v[108:111], v[146:149], v[216:219], v[108:111]
	v_mfma_f32_16x16x32_bf16 v[104:107], v[174:177], v[216:219], v[104:107]
	v_mfma_f32_16x16x32_bf16 v[92:95], v[146:149], v[224:227], v[92:95]
	v_mfma_f32_16x16x32_bf16 v[88:91], v[174:177], v[224:227], v[88:91]
	v_mfma_f32_16x16x32_bf16 v[76:79], v[146:149], v[232:235], v[76:79]
	v_mfma_f32_16x16x32_bf16 v[72:75], v[174:177], v[232:235], v[72:75]
	v_mfma_f32_16x16x32_bf16 v[116:119], v[178:181], v[204:207], 0
	v_mfma_f32_16x16x32_bf16 v[112:115], v[186:189], v[204:207], 0
	v_mfma_f32_16x16x32_bf16 v[100:103], v[178:181], v[212:215], 0
	v_mfma_f32_16x16x32_bf16 v[96:99], v[186:189], v[212:215], 0
	v_mfma_f32_16x16x32_bf16 v[84:87], v[178:181], v[220:223], 0
	v_mfma_f32_16x16x32_bf16 v[80:83], v[186:189], v[220:223], 0
	v_mfma_f32_16x16x32_bf16 v[68:71], v[178:181], v[228:231], 0
	v_mfma_f32_16x16x32_bf16 v[64:67], v[186:189], v[228:231], 0
	v_mfma_f32_16x16x32_bf16 v[116:119], v[182:185], v[208:211], v[116:119]
	v_mfma_f32_16x16x32_bf16 v[112:115], v[200:203], v[208:211], v[112:115]
	v_mfma_f32_16x16x32_bf16 v[100:103], v[182:185], v[216:219], v[100:103]
	v_mfma_f32_16x16x32_bf16 v[96:99], v[200:203], v[216:219], v[96:99]
	v_mfma_f32_16x16x32_bf16 v[84:87], v[182:185], v[224:227], v[84:87]
	v_mfma_f32_16x16x32_bf16 v[80:83], v[200:203], v[224:227], v[80:83]
	v_mfma_f32_16x16x32_bf16 v[68:71], v[182:185], v[232:235], v[68:71]
	v_mfma_f32_16x16x32_bf16 v[64:67], v[200:203], v[232:235], v[64:67]
	s_setprio 0
	s_barrier
	s_add_i32 s71, s71, s55
	v_lshl_add_u64 v[150:151], s[24:25], 0, v[152:153]
	s_mov_b32 m0, s71
	ds_read_b128 v[204:207], v145 offset:16384
	ds_read_b128 v[208:211], v145 offset:17408
	ds_read_b128 v[212:215], v145 offset:18432
	ds_read_b128 v[216:219], v145 offset:19456
	ds_read_b128 v[220:223], v145 offset:20480
	ds_read_b128 v[224:227], v145 offset:21504
	ds_read_b128 v[228:231], v145 offset:22528
	ds_read_b128 v[232:235], v145 offset:23552
	global_load_lds_dwordx4 v[150:151], off
	s_add_i32 m0, s71, 0x2000
	s_add_u32 s72, s24, 0x20000
	v_lshl_add_u64 v[190:191], s[24:25], 0, v[132:133]
	s_addc_u32 s73, s25, 0
	s_add_i32 s71, s74, s55
	global_load_lds_dwordx4 v[190:191], off
	v_lshl_add_u64 v[236:237], s[72:73], 0, v[152:153]
	s_mov_b32 m0, s71
	v_lshl_add_u64 v[238:239], s[26:27], 0, v[130:131]
	global_load_lds_dwordx4 v[236:237], off
	v_lshl_add_u64 v[236:237], s[72:73], 0, v[132:133]
	s_add_i32 m0, s71, 0x2000
	s_nop 0
	global_load_lds_dwordx4 v[236:237], off
	v_lshl_add_u64 v[236:237], s[26:27], 0, v[128:129]
	s_mov_b32 m0, s21
	s_nop 0
	global_load_lds_dwordx4 v[236:237], off
	s_mov_b32 m0, s56
	s_nop 0
	global_load_lds_dwordx4 v[238:239], off
	s_waitcnt vmcnt(8)
	s_waitcnt lgkmcnt(0)
	s_barrier
; #define PG8_STAGE(bufoff, gbase, voff) do { _Pragma("unroll") for (int _i = 0; _i < 2; ++_i) \
;         __builtin_amdgcn_global_load_lds((const unsigned*)((const char*)(gbase) + (voff)[_i]), (LAS unsigned*)(lds + (bufoff) + ldsw + _i * 8192), 16, 0, 0); } while (0)
; #define PG8_LDA(dst, b, h) do { _Pragma("unroll") for (int m = 0; m < 4; ++m) _Pragma("unroll") for (int k = 0; k < 2; ++k) dst[m][k] = *(const LAS bf16x8*)(lds + PG8_SA(b, h) + aoff + m * 2048 + k * 1024); } while (0)
; #define PG8_LDB(dst, b, h) do { _Pragma("unroll") for (int n = 0; n < 2; ++n) _Pragma("unroll") for (int k = 0; k < 2; ++k) dst[n][k] = *(const LAS bf16x8*)(lds + PG8_SB(b, h) + boff + n * 2048 + k * 1024); } while (0)
; #define PG8_MMA(ai, bj, At, Bt) do { __builtin_amdgcn_s_setprio(1); _Pragma("unroll") for (int m = 0; m < 4; ++m) _Pragma("unroll") for (int n = 0; n < 2; ++n) _Pragma("unroll") for (int k = 0; k < 2; ++k) \
;         acc[ai][bj][m][n] = __builtin_amdgcn_mfma_f32_16x16x32_bf16(Bt[n][k], At[m][k], acc[ai][bj][m][n], 0, 0, 0); __builtin_amdgcn_s_setprio(0); } while (0)
; #define PG8_WAIT_V(n) asm volatile("s_waitcnt vmcnt(" #n ")" ::: "memory")
; #define PG8_WAIT_L(n) asm volatile("s_waitcnt lgkmcnt(" #n ")" ::: "memory")
; #define PG8_BAR __builtin_amdgcn_s_barrier()
; #define PG8_SCHED __builtin_amdgcn_sched_barrier(0)
; template <class Epi, class Sched>
; __device__ __forceinline__ void gemm_phase(const int tid, LAS unsigned char* lds, const Gemm g, const Sched& S, const Epi& E) {
;     ...
;             PG8_WAIT_V(8); PG8_WAIT_L(0); PG8_BAR; PG8_MMA(1, 0, At, B0); PG8_MMA(1, 1, At, B1); PG8_BAR; PG8_SCHED;
;             PG8_LDB(B0, 1, 0); PG8_LDB(B1, 1, 1); PG8_SCHED; PG8_LDA(At, 1, 0); PG8_STAGE(PG8_SA(0, 1), a2 + hstep, voffA);
;             PG8_WAIT_V(8); PG8_WAIT_L(0); PG8_BAR; PG8_MMA(0, 0, At, B0); PG8_MMA(0, 1, At, B1); PG8_BAR; PG8_SCHED;
	s_setprio 1
	s_waitcnt lgkmcnt(0)
	v_mfma_f32_16x16x32_bf16 v[60:63], v[138:141], v[204:207], 0
	v_mfma_f32_16x16x32_bf16 v[56:59], v[170:173], v[204:207], 0
	v_mfma_f32_16x16x32_bf16 v[44:47], v[138:141], v[212:215], 0
	v_mfma_f32_16x16x32_bf16 v[40:43], v[170:173], v[212:215], 0
	v_mfma_f32_16x16x32_bf16 v[28:31], v[138:141], v[220:223], 0
	v_mfma_f32_16x16x32_bf16 v[24:27], v[170:173], v[220:223], 0
	v_mfma_f32_16x16x32_bf16 v[12:15], v[138:141], v[228:231], 0
	v_mfma_f32_16x16x32_bf16 v[8:11], v[170:173], v[228:231], 0
	v_mfma_f32_16x16x32_bf16 v[60:63], v[146:149], v[208:211], v[60:63]
	v_mfma_f32_16x16x32_bf16 v[56:59], v[174:177], v[208:211], v[56:59]
	v_mfma_f32_16x16x32_bf16 v[44:47], v[146:149], v[216:219], v[44:47]
	v_mfma_f32_16x16x32_bf16 v[40:43], v[174:177], v[216:219], v[40:43]
	v_mfma_f32_16x16x32_bf16 v[28:31], v[146:149], v[224:227], v[28:31]
	v_mfma_f32_16x16x32_bf16 v[24:27], v[174:177], v[224:227], v[24:27]
	v_mfma_f32_16x16x32_bf16 v[12:15], v[146:149], v[232:235], v[12:15]
	v_mfma_f32_16x16x32_bf16 v[8:11], v[174:177], v[232:235], v[8:11]
	v_mfma_f32_16x16x32_bf16 v[52:55], v[178:181], v[204:207], 0
	v_mfma_f32_16x16x32_bf16 v[48:51], v[186:189], v[204:207], 0
	v_mfma_f32_16x16x32_bf16 v[36:39], v[178:181], v[212:215], 0
	v_mfma_f32_16x16x32_bf16 v[32:35], v[186:189], v[212:215], 0
	v_mfma_f32_16x16x32_bf16 v[20:23], v[178:181], v[220:223], 0
	v_mfma_f32_16x16x32_bf16 v[16:19], v[186:189], v[220:223], 0
	v_mfma_f32_16x16x32_bf16 v[4:7], v[178:181], v[228:231], 0
	v_mfma_f32_16x16x32_bf16 v[0:3], v[186:189], v[228:231], 0
	v_mfma_f32_16x16x32_bf16 v[52:55], v[182:185], v[208:211], v[52:55]
	v_mfma_f32_16x16x32_bf16 v[48:51], v[200:203], v[208:211], v[48:51]
	v_mfma_f32_16x16x32_bf16 v[36:39], v[182:185], v[216:219], v[36:39]
	v_mfma_f32_16x16x32_bf16 v[32:35], v[200:203], v[216:219], v[32:35]
	v_mfma_f32_16x16x32_bf16 v[20:23], v[182:185], v[224:227], v[20:23]
	v_mfma_f32_16x16x32_bf16 v[16:19], v[200:203], v[224:227], v[16:19]
	v_mfma_f32_16x16x32_bf16 v[4:7], v[182:185], v[232:235], v[4:7]
	v_mfma_f32_16x16x32_bf16 v[0:3], v[200:203], v[232:235], v[0:3]
	s_setprio 0
	s_barrier
	s_add_i32 s71, 0, 0x18000
	s_add_i32 s72, 0, 0x1c000
	v_add_u32_e32 v174, s71, v144
	v_add_u32_e32 v199, s72, v144
	ds_read_b128 v[138:141], v174
	ds_read_b128 v[146:149], v174 offset:1024
	ds_read_b128 v[170:173], v174 offset:2048
	ds_read_b128 v[174:177], v174 offset:3072
	ds_read_b128 v[178:181], v199
	ds_read_b128 v[182:185], v199 offset:1024
	ds_read_b128 v[186:189], v199 offset:2048
	ds_read_b128 v[200:203], v199 offset:3072
	s_add_u32 s26, s26, 0x20000
	s_addc_u32 s27, s27, 0
	s_mov_b32 m0, s57
	v_lshl_add_u64 v[240:241], s[26:27], 0, v[128:129]
	ds_read_b128 v[204:207], v145 offset:32768
	ds_read_b128 v[208:211], v145 offset:33792
	ds_read_b128 v[212:215], v145 offset:34816
	ds_read_b128 v[216:219], v145 offset:35840
	ds_read_b128 v[220:223], v145 offset:36864
	ds_read_b128 v[224:227], v145 offset:37888
	ds_read_b128 v[228:231], v145 offset:38912
	ds_read_b128 v[232:235], v145 offset:39936
	global_load_lds_dwordx4 v[240:241], off
	v_lshl_add_u64 v[240:241], s[26:27], 0, v[130:131]
	s_mov_b32 m0, s58
	s_nop 0
	global_load_lds_dwordx4 v[240:241], off
	s_waitcnt vmcnt(8)
	s_waitcnt lgkmcnt(0)
	s_barrier
	s_setprio 1
	s_waitcnt lgkmcnt(0)
	v_mfma_f32_16x16x32_bf16 v[124:127], v[138:141], v[204:207], v[124:127]
	v_mfma_f32_16x16x32_bf16 v[120:123], v[170:173], v[204:207], v[120:123]
	v_mfma_f32_16x16x32_bf16 v[108:111], v[138:141], v[212:215], v[108:111]
	v_mfma_f32_16x16x32_bf16 v[104:107], v[170:173], v[212:215], v[104:107]
	v_mfma_f32_16x16x32_bf16 v[92:95], v[138:141], v[220:223], v[92:95]
	v_mfma_f32_16x16x32_bf16 v[88:91], v[170:173], v[220:223], v[88:91]
	v_mfma_f32_16x16x32_bf16 v[76:79], v[138:141], v[228:231], v[76:79]
	v_mfma_f32_16x16x32_bf16 v[72:75], v[170:173], v[228:231], v[72:75]
	v_mfma_f32_16x16x32_bf16 v[124:127], v[146:149], v[208:211], v[124:127]
	v_mfma_f32_16x16x32_bf16 v[120:123], v[174:177], v[208:211], v[120:123]
	v_mfma_f32_16x16x32_bf16 v[108:111], v[146:149], v[216:219], v[108:111]
	v_mfma_f32_16x16x32_bf16 v[104:107], v[174:177], v[216:219], v[104:107]
	v_mfma_f32_16x16x32_bf16 v[92:95], v[146:149], v[224:227], v[92:95]
	v_mfma_f32_16x16x32_bf16 v[88:91], v[174:177], v[224:227], v[88:91]
	v_mfma_f32_16x16x32_bf16 v[76:79], v[146:149], v[232:235], v[76:79]
	v_mfma_f32_16x16x32_bf16 v[72:75], v[174:177], v[232:235], v[72:75]
	v_mfma_f32_16x16x32_bf16 v[116:119], v[178:181], v[204:207], v[116:119]
	v_mfma_f32_16x16x32_bf16 v[112:115], v[186:189], v[204:207], v[112:115]
	v_mfma_f32_16x16x32_bf16 v[100:103], v[178:181], v[212:215], v[100:103]
	v_mfma_f32_16x16x32_bf16 v[96:99], v[186:189], v[212:215], v[96:99]
	v_mfma_f32_16x16x32_bf16 v[84:87], v[178:181], v[220:223], v[84:87]
	v_mfma_f32_16x16x32_bf16 v[80:83], v[186:189], v[220:223], v[80:83]
	v_mfma_f32_16x16x32_bf16 v[68:71], v[178:181], v[228:231], v[68:71]
	v_mfma_f32_16x16x32_bf16 v[64:67], v[186:189], v[228:231], v[64:67]
	v_mfma_f32_16x16x32_bf16 v[116:119], v[182:185], v[208:211], v[116:119]
	v_mfma_f32_16x16x32_bf16 v[112:115], v[200:203], v[208:211], v[112:115]
	v_mfma_f32_16x16x32_bf16 v[100:103], v[182:185], v[216:219], v[100:103]
	v_mfma_f32_16x16x32_bf16 v[96:99], v[200:203], v[216:219], v[96:99]
	v_mfma_f32_16x16x32_bf16 v[84:87], v[182:185], v[224:227], v[84:87]
	v_mfma_f32_16x16x32_bf16 v[80:83], v[200:203], v[224:227], v[80:83]
	v_mfma_f32_16x16x32_bf16 v[68:71], v[182:185], v[232:235], v[68:71]
	v_mfma_f32_16x16x32_bf16 v[64:67], v[200:203], v[232:235], v[64:67]
	s_setprio 0
	s_barrier
; #define PG8_STAGE(bufoff, gbase, voff) do { _Pragma("unroll") for (int _i = 0; _i < 2; ++_i) \
;         __builtin_amdgcn_global_load_lds((const unsigned*)((const char*)(gbase) + (voff)[_i]), (LAS unsigned*)(lds + (bufoff) + ldsw + _i * 8192), 16, 0, 0); } while (0)
; #define PG8_LDA(dst, b, h) do { _Pragma("unroll") for (int m = 0; m < 4; ++m) _Pragma("unroll") for (int k = 0; k < 2; ++k) dst[m][k] = *(const LAS bf16x8*)(lds + PG8_SA(b, h) + aoff + m * 2048 + k * 1024); } while (0)
; #define PG8_LDB(dst, b, h) do { _Pragma("unroll") for (int n = 0; n < 2; ++n) _Pragma("unroll") for (int k = 0; k < 2; ++k) dst[n][k] = *(const LAS bf16x8*)(lds + PG8_SB(b, h) + boff + n * 2048 + k * 1024); } while (0)
; #define PG8_MMA(ai, bj, At, Bt) do { __builtin_amdgcn_s_setprio(1); _Pragma("unroll") for (int m = 0; m < 4; ++m) _Pragma("unroll") for (int n = 0; n < 2; ++n) _Pragma("unroll") for (int k = 0; k < 2; ++k) \
;         acc[ai][bj][m][n] = __builtin_amdgcn_mfma_f32_16x16x32_bf16(Bt[n][k], At[m][k], acc[ai][bj][m][n], 0, 0, 0); __builtin_amdgcn_s_setprio(0); } while (0)
; #define PG8_WAIT_V(n) asm volatile("s_waitcnt vmcnt(" #n ")" ::: "memory")
; template <class Epi, class Sched>
; __device__ __forceinline__ void gemm_phase(const int tid, LAS unsigned char* lds, const Gemm g, const Sched& S, const Epi& E) {
;     ...
;             PG8_LDB(B0, 0, 0); PG8_LDB(B1, 0, 1); PG8_SCHED; PG8_LDA(At, 0, 0); PG8_STAGE(PG8_SA(1, 1), a1 + hstep, voffA);
;             PG8_WAIT_V(8); PG8_WAIT_L(0); PG8_BAR; PG8_MMA(0, 0, At, B0); PG8_MMA(0, 1, At, B1); PG8_BAR; PG8_SCHED;
;             PG8_LDA(At, 0, 1); PG8_STAGE(PG8_SB(0, 0), b2, voffB); PG8_STAGE(PG8_SB(0, 1), b2 + hstep, voffB); PG8_STAGE(PG8_SA(0, 0), a2, voffA);
;             PG8_WAIT_V(8); PG8_WAIT_L(0); PG8_BAR; PG8_MMA(1, 0, At, B0); PG8_MMA(1, 1, At, B1); PG8_BAR; PG8_SCHED;
;             PG8_LDB(B0, 1, 0); PG8_LDB(B1, 1, 1); PG8_SCHED; PG8_LDA(At, 1, 0); PG8_STAGE(PG8_SA(0, 1), a2 + hstep, voffA);
;             PG8_WAIT_V(8); PG8_WAIT_L(0); PG8_BAR; PG8_MMA(0, 0, At, B0); PG8_MMA(0, 1, At, B1); PG8_BAR; PG8_SCHED;
;             PG8_LDA(At, 1, 1); PG8_STAGE(PG8_SB(1, 0), b3, voffB); PG8_STAGE(PG8_SB(1, 1), b3 + hstep, voffB); PG8_STAGE(PG8_SA(1, 0), a3, voffA);
;             PG8_WAIT_V(8); PG8_WAIT_L(0); PG8_BAR; PG8_MMA(1, 0, At, B0); PG8_MMA(1, 1, At, B1); PG8_BAR; PG8_SCHED;
;         }
	s_add_i32 s26, s71, s55
	v_lshl_add_u64 v[150:151], v[150:151], 0, s[34:35]
	s_mov_b32 m0, s26
	ds_read_b128 v[204:207], v145 offset:49152
	ds_read_b128 v[208:211], v145 offset:50176
	ds_read_b128 v[212:215], v145 offset:51200
	ds_read_b128 v[216:219], v145 offset:52224
	ds_read_b128 v[220:223], v145 offset:53248
	ds_read_b128 v[224:227], v145 offset:54272
	ds_read_b128 v[228:231], v145 offset:55296
	ds_read_b128 v[232:235], v145 offset:56320
	global_load_lds_dwordx4 v[150:151], off
	s_add_i32 m0, s26, 0x2000
	s_add_u32 s24, s24, 0x20080
	v_lshl_add_u64 v[150:151], v[190:191], 0, s[34:35]
	s_addc_u32 s25, s25, 0
	s_add_i32 s26, s72, s55
	global_load_lds_dwordx4 v[150:151], off
	v_lshl_add_u64 v[150:151], s[24:25], 0, v[152:153]
	s_mov_b32 m0, s26
	s_nop 0
	global_load_lds_dwordx4 v[150:151], off
	v_lshl_add_u64 v[150:151], s[24:25], 0, v[132:133]
	s_add_i32 m0, s26, 0x2000
	s_nop 0
	global_load_lds_dwordx4 v[150:151], off
	v_lshl_add_u64 v[150:151], v[236:237], 0, s[34:35]
	s_mov_b32 m0, s61
	s_nop 0
	global_load_lds_dwordx4 v[150:151], off
	v_lshl_add_u64 v[150:151], v[238:239], 0, s[34:35]
	s_mov_b32 m0, s62
	s_nop 0
	global_load_lds_dwordx4 v[150:151], off
	s_waitcnt vmcnt(8)
	s_waitcnt lgkmcnt(0)
	s_barrier
	s_setprio 1
	s_waitcnt lgkmcnt(0)
	v_mfma_f32_16x16x32_bf16 v[60:63], v[138:141], v[204:207], v[60:63]
	v_mfma_f32_16x16x32_bf16 v[56:59], v[170:173], v[204:207], v[56:59]
	v_mfma_f32_16x16x32_bf16 v[44:47], v[138:141], v[212:215], v[44:47]
	v_mfma_f32_16x16x32_bf16 v[40:43], v[170:173], v[212:215], v[40:43]
	v_mfma_f32_16x16x32_bf16 v[28:31], v[138:141], v[220:223], v[28:31]
	v_mfma_f32_16x16x32_bf16 v[24:27], v[170:173], v[220:223], v[24:27]
	v_mfma_f32_16x16x32_bf16 v[12:15], v[138:141], v[228:231], v[12:15]
	v_mfma_f32_16x16x32_bf16 v[8:11], v[170:173], v[228:231], v[8:11]
	v_mfma_f32_16x16x32_bf16 v[60:63], v[146:149], v[208:211], v[60:63]
	v_mfma_f32_16x16x32_bf16 v[56:59], v[174:177], v[208:211], v[56:59]
	v_mfma_f32_16x16x32_bf16 v[44:47], v[146:149], v[216:219], v[44:47]
	v_mfma_f32_16x16x32_bf16 v[40:43], v[174:177], v[216:219], v[40:43]
	v_mfma_f32_16x16x32_bf16 v[28:31], v[146:149], v[224:227], v[28:31]
	v_mfma_f32_16x16x32_bf16 v[24:27], v[174:177], v[224:227], v[24:27]
	v_mfma_f32_16x16x32_bf16 v[12:15], v[146:149], v[232:235], v[12:15]
	v_mfma_f32_16x16x32_bf16 v[8:11], v[174:177], v[232:235], v[8:11]
	v_mfma_f32_16x16x32_bf16 v[52:55], v[178:181], v[204:207], v[52:55]
	v_mfma_f32_16x16x32_bf16 v[48:51], v[186:189], v[204:207], v[48:51]
	v_mfma_f32_16x16x32_bf16 v[36:39], v[178:181], v[212:215], v[36:39]
	v_mfma_f32_16x16x32_bf16 v[32:35], v[186:189], v[212:215], v[32:35]
	v_mfma_f32_16x16x32_bf16 v[20:23], v[178:181], v[220:223], v[20:23]
	v_mfma_f32_16x16x32_bf16 v[16:19], v[186:189], v[220:223], v[16:19]
	v_mfma_f32_16x16x32_bf16 v[4:7], v[178:181], v[228:231], v[4:7]
	v_mfma_f32_16x16x32_bf16 v[0:3], v[186:189], v[228:231], v[0:3]
	v_mfma_f32_16x16x32_bf16 v[52:55], v[182:185], v[208:211], v[52:55]
	v_mfma_f32_16x16x32_bf16 v[48:51], v[200:203], v[208:211], v[48:51]
	v_mfma_f32_16x16x32_bf16 v[36:39], v[182:185], v[216:219], v[36:39]
	v_mfma_f32_16x16x32_bf16 v[32:35], v[200:203], v[216:219], v[32:35]
	v_mfma_f32_16x16x32_bf16 v[20:23], v[182:185], v[224:227], v[20:23]
	v_mfma_f32_16x16x32_bf16 v[16:19], v[200:203], v[224:227], v[16:19]
	v_mfma_f32_16x16x32_bf16 v[4:7], v[182:185], v[232:235], v[4:7]
	v_mfma_f32_16x16x32_bf16 v[0:3], v[200:203], v[232:235], v[0:3]
	s_setprio 0
	s_barrier
	s_add_i32 s70, s70, 2
	s_add_u32 s22, s22, 0x100
	s_addc_u32 s23, s23, 0
	s_add_u32 s68, s68, 0x100
	s_addc_u32 s69, s69, 0
	s_cmp_gt_u32 s70, 5
.LBB0_395:
	s_add_u32 s24, s22, 0xfffe0080
	s_addc_u32 s25, s23, -1
	s_add_i32 s71, 0, 0x10000
	s_cmp_eq_u32 s70, 4
	s_cselect_b32 s27, s15, s25
	s_cselect_b32 s26, s66, s24
	v_add_u32_e32 v150, s71, v144
	s_cselect_b32 s25, s13, s69
	s_cselect_b32 s24, s67, s68
	s_add_i32 s74, 0, 0x14000
	ds_read_b128 v[138:141], v150
	ds_read_b128 v[146:149], v150 offset:1024
	ds_read_b128 v[170:173], v150 offset:2048
	ds_read_b128 v[174:177], v150 offset:3072
	v_add_u32_e32 v150, s74, v144
	ds_read_b128 v[178:181], v150
	ds_read_b128 v[182:185], v150 offset:1024
	ds_read_b128 v[186:189], v150 offset:2048
	ds_read_b128 v[200:203], v150 offset:3072
	v_lshl_add_u64 v[150:151], s[22:23], 0, v[134:135]
	s_add_i32 m0, s21, 0xc000
	ds_read_b128 v[204:207], v145
	ds_read_b128 v[208:211], v145 offset:1024
	ds_read_b128 v[212:215], v145 offset:2048
	ds_read_b128 v[216:219], v145 offset:3072
	ds_read_b128 v[220:223], v145 offset:4096
	ds_read_b128 v[224:227], v145 offset:5120
	ds_read_b128 v[228:231], v145 offset:6144
	ds_read_b128 v[232:235], v145 offset:7168
	global_load_lds_dwordx4 v[150:151], off
	v_lshl_add_u64 v[150:151], s[22:23], 0, v[136:137]
	s_add_i32 m0, s21, 0xe000
	s_nop 0
	global_load_lds_dwordx4 v[150:151], off
	s_waitcnt vmcnt(8)
	s_waitcnt lgkmcnt(0)
	s_barrier
; #define PG8_STAGE(bufoff, gbase, voff) do { _Pragma("unroll") for (int _i = 0; _i < 2; ++_i) \
;         __builtin_amdgcn_global_load_lds((const unsigned*)((const char*)(gbase) + (voff)[_i]), (LAS unsigned*)(lds + (bufoff) + ldsw + _i * 8192), 16, 0, 0); } while (0)
; #define PG8_LDA(dst, b, h) do { _Pragma("unroll") for (int m = 0; m < 4; ++m) _Pragma("unroll") for (int k = 0; k < 2; ++k) dst[m][k] = *(const LAS bf16x8*)(lds + PG8_SA(b, h) + aoff + m * 2048 + k * 1024); } while (0)
; #define PG8_LDB(dst, b, h) do { _Pragma("unroll") for (int n = 0; n < 2; ++n) _Pragma("unroll") for (int k = 0; k < 2; ++k) dst[n][k] = *(const LAS bf16x8*)(lds + PG8_SB(b, h) + boff + n * 2048 + k * 1024); } while (0)
; #define PG8_MMA(ai, bj, At, Bt) do { __builtin_amdgcn_s_setprio(1); _Pragma("unroll") for (int m = 0; m < 4; ++m) _Pragma("unroll") for (int n = 0; n < 2; ++n) _Pragma("unroll") for (int k = 0; k < 2; ++k) \
;         acc[ai][bj][m][n] = __builtin_amdgcn_mfma_f32_16x16x32_bf16(Bt[n][k], At[m][k], acc[ai][bj][m][n], 0, 0, 0); __builtin_amdgcn_s_setprio(0); } while (0)
; #define PG8_WAIT_V(n) asm volatile("s_waitcnt vmcnt(" #n ")" ::: "memory")
; #define PG8_WAIT_L(n) asm volatile("s_waitcnt lgkmcnt(" #n ")" ::: "memory")
; #define PG8_BAR __builtin_amdgcn_s_barrier()
; #define PG8_SCHED __builtin_amdgcn_sched_barrier(0)
; template <class Epi, class Sched>
; __device__ __forceinline__ void gemm_phase(const int tid, LAS unsigned char* lds, const Gemm g, const Sched& S, const Epi& E) {
;     ...
;             PG8_LDB(B0, 0, 0); PG8_LDB(B1, 0, 1); PG8_SCHED; PG8_LDA(At, 0, 0); PG8_STAGE(PG8_SA(1, 1), a1 + hstep, voffA);
;             PG8_WAIT_V(8); PG8_WAIT_L(0); PG8_BAR; PG8_MMA(0, 0, At, B0); PG8_MMA(0, 1, At, B1); PG8_BAR; PG8_SCHED;
;             PG8_LDA(At, 0, 1); PG8_STAGE(PG8_SB(0, 0), b2, voffB); PG8_STAGE(PG8_SB(0, 1), b2 + hstep, voffB); PG8_STAGE(PG8_SA(0, 0), a2, voffA);
;             PG8_WAIT_V(8); PG8_WAIT_L(0); PG8_BAR; PG8_MMA(1, 0, At, B0); PG8_MMA(1, 1, At, B1); PG8_BAR; PG8_SCHED;
	s_setprio 1
	s_waitcnt lgkmcnt(0)
	v_mfma_f32_16x16x32_bf16 v[124:127], v[138:141], v[204:207], v[124:127]
	v_mfma_f32_16x16x32_bf16 v[120:123], v[170:173], v[204:207], v[120:123]
	v_mfma_f32_16x16x32_bf16 v[108:111], v[138:141], v[212:215], v[108:111]
	v_mfma_f32_16x16x32_bf16 v[104:107], v[170:173], v[212:215], v[104:107]
	v_mfma_f32_16x16x32_bf16 v[92:95], v[138:141], v[220:223], v[92:95]
	v_mfma_f32_16x16x32_bf16 v[88:91], v[170:173], v[220:223], v[88:91]
	v_mfma_f32_16x16x32_bf16 v[76:79], v[138:141], v[228:231], v[76:79]
	v_mfma_f32_16x16x32_bf16 v[72:75], v[170:173], v[228:231], v[72:75]
	v_mfma_f32_16x16x32_bf16 v[124:127], v[146:149], v[208:211], v[124:127]
	v_mfma_f32_16x16x32_bf16 v[120:123], v[174:177], v[208:211], v[120:123]
	v_mfma_f32_16x16x32_bf16 v[108:111], v[146:149], v[216:219], v[108:111]
	v_mfma_f32_16x16x32_bf16 v[104:107], v[174:177], v[216:219], v[104:107]
	v_mfma_f32_16x16x32_bf16 v[92:95], v[146:149], v[224:227], v[92:95]
	v_mfma_f32_16x16x32_bf16 v[88:91], v[174:177], v[224:227], v[88:91]
	v_mfma_f32_16x16x32_bf16 v[76:79], v[146:149], v[232:235], v[76:79]
	v_mfma_f32_16x16x32_bf16 v[72:75], v[174:177], v[232:235], v[72:75]
	v_mfma_f32_16x16x32_bf16 v[116:119], v[178:181], v[204:207], v[116:119]
	v_mfma_f32_16x16x32_bf16 v[112:115], v[186:189], v[204:207], v[112:115]
	v_mfma_f32_16x16x32_bf16 v[100:103], v[178:181], v[212:215], v[100:103]
	v_mfma_f32_16x16x32_bf16 v[96:99], v[186:189], v[212:215], v[96:99]
	v_mfma_f32_16x16x32_bf16 v[84:87], v[178:181], v[220:223], v[84:87]
	v_mfma_f32_16x16x32_bf16 v[80:83], v[186:189], v[220:223], v[80:83]
	v_mfma_f32_16x16x32_bf16 v[68:71], v[178:181], v[228:231], v[68:71]
	v_mfma_f32_16x16x32_bf16 v[64:67], v[186:189], v[228:231], v[64:67]
	v_mfma_f32_16x16x32_bf16 v[116:119], v[182:185], v[208:211], v[116:119]
	v_mfma_f32_16x16x32_bf16 v[112:115], v[200:203], v[208:211], v[112:115]
	v_mfma_f32_16x16x32_bf16 v[100:103], v[182:185], v[216:219], v[100:103]
	v_mfma_f32_16x16x32_bf16 v[96:99], v[200:203], v[216:219], v[96:99]
	v_mfma_f32_16x16x32_bf16 v[84:87], v[182:185], v[224:227], v[84:87]
	v_mfma_f32_16x16x32_bf16 v[80:83], v[200:203], v[224:227], v[80:83]
	v_mfma_f32_16x16x32_bf16 v[68:71], v[182:185], v[232:235], v[68:71]
	v_mfma_f32_16x16x32_bf16 v[64:67], v[200:203], v[232:235], v[64:67]
	s_setprio 0
	s_barrier
	s_add_i32 s71, s71, s55
	v_lshl_add_u64 v[150:151], s[24:25], 0, v[152:153]
	s_mov_b32 m0, s71
	ds_read_b128 v[204:207], v145 offset:16384
	ds_read_b128 v[208:211], v145 offset:17408
	ds_read_b128 v[212:215], v145 offset:18432
	ds_read_b128 v[216:219], v145 offset:19456
	ds_read_b128 v[220:223], v145 offset:20480
	ds_read_b128 v[224:227], v145 offset:21504
	ds_read_b128 v[228:231], v145 offset:22528
	ds_read_b128 v[232:235], v145 offset:23552
	global_load_lds_dwordx4 v[150:151], off
	s_add_i32 m0, s71, 0x2000
	s_add_u32 s72, s24, 0x20000
	v_lshl_add_u64 v[190:191], s[24:25], 0, v[132:133]
	s_addc_u32 s73, s25, 0
	s_add_i32 s71, s74, s55
	global_load_lds_dwordx4 v[190:191], off
	v_lshl_add_u64 v[236:237], s[72:73], 0, v[152:153]
	s_mov_b32 m0, s71
	v_lshl_add_u64 v[238:239], s[26:27], 0, v[130:131]
	global_load_lds_dwordx4 v[236:237], off
	v_lshl_add_u64 v[236:237], s[72:73], 0, v[132:133]
	s_add_i32 m0, s71, 0x2000
	s_nop 0
	global_load_lds_dwordx4 v[236:237], off
	v_lshl_add_u64 v[236:237], s[26:27], 0, v[128:129]
	s_mov_b32 m0, s21
	s_nop 0
	global_load_lds_dwordx4 v[236:237], off
	s_mov_b32 m0, s56
	s_nop 0
	global_load_lds_dwordx4 v[238:239], off
	s_waitcnt vmcnt(8)
	s_waitcnt lgkmcnt(0)
	s_barrier
	s_setprio 1
	s_waitcnt lgkmcnt(0)
	v_mfma_f32_16x16x32_bf16 v[60:63], v[138:141], v[204:207], v[60:63]
	v_mfma_f32_16x16x32_bf16 v[56:59], v[170:173], v[204:207], v[56:59]
	v_mfma_f32_16x16x32_bf16 v[44:47], v[138:141], v[212:215], v[44:47]
	v_mfma_f32_16x16x32_bf16 v[40:43], v[170:173], v[212:215], v[40:43]
	v_mfma_f32_16x16x32_bf16 v[28:31], v[138:141], v[220:223], v[28:31]
	v_mfma_f32_16x16x32_bf16 v[24:27], v[170:173], v[220:223], v[24:27]
	v_mfma_f32_16x16x32_bf16 v[12:15], v[138:141], v[228:231], v[12:15]
	v_mfma_f32_16x16x32_bf16 v[8:11], v[170:173], v[228:231], v[8:11]
	v_mfma_f32_16x16x32_bf16 v[60:63], v[146:149], v[208:211], v[60:63]
	v_mfma_f32_16x16x32_bf16 v[56:59], v[174:177], v[208:211], v[56:59]
	v_mfma_f32_16x16x32_bf16 v[44:47], v[146:149], v[216:219], v[44:47]
	v_mfma_f32_16x16x32_bf16 v[40:43], v[174:177], v[216:219], v[40:43]
	v_mfma_f32_16x16x32_bf16 v[28:31], v[146:149], v[224:227], v[28:31]
	v_mfma_f32_16x16x32_bf16 v[24:27], v[174:177], v[224:227], v[24:27]
	v_mfma_f32_16x16x32_bf16 v[12:15], v[146:149], v[232:235], v[12:15]
	v_mfma_f32_16x16x32_bf16 v[8:11], v[174:177], v[232:235], v[8:11]
	v_mfma_f32_16x16x32_bf16 v[52:55], v[178:181], v[204:207], v[52:55]
	v_mfma_f32_16x16x32_bf16 v[48:51], v[186:189], v[204:207], v[48:51]
	v_mfma_f32_16x16x32_bf16 v[36:39], v[178:181], v[212:215], v[36:39]
	v_mfma_f32_16x16x32_bf16 v[32:35], v[186:189], v[212:215], v[32:35]
	v_mfma_f32_16x16x32_bf16 v[20:23], v[178:181], v[220:223], v[20:23]
	v_mfma_f32_16x16x32_bf16 v[16:19], v[186:189], v[220:223], v[16:19]
	v_mfma_f32_16x16x32_bf16 v[4:7], v[178:181], v[228:231], v[4:7]
	v_mfma_f32_16x16x32_bf16 v[0:3], v[186:189], v[228:231], v[0:3]
	v_mfma_f32_16x16x32_bf16 v[52:55], v[182:185], v[208:211], v[52:55]
	v_mfma_f32_16x16x32_bf16 v[48:51], v[200:203], v[208:211], v[48:51]
	v_mfma_f32_16x16x32_bf16 v[36:39], v[182:185], v[216:219], v[36:39]
	v_mfma_f32_16x16x32_bf16 v[32:35], v[200:203], v[216:219], v[32:35]
	v_mfma_f32_16x16x32_bf16 v[20:23], v[182:185], v[224:227], v[20:23]
	v_mfma_f32_16x16x32_bf16 v[16:19], v[200:203], v[224:227], v[16:19]
	v_mfma_f32_16x16x32_bf16 v[4:7], v[182:185], v[232:235], v[4:7]
	v_mfma_f32_16x16x32_bf16 v[0:3], v[200:203], v[232:235], v[0:3]
	s_setprio 0
	s_barrier
; #define PG8_STAGE(bufoff, gbase, voff) do { _Pragma("unroll") for (int _i = 0; _i < 2; ++_i) \
;         __builtin_amdgcn_global_load_lds((const unsigned*)((const char*)(gbase) + (voff)[_i]), (LAS unsigned*)(lds + (bufoff) + ldsw + _i * 8192), 16, 0, 0); } while (0)
; #define PG8_LDA(dst, b, h) do { _Pragma("unroll") for (int m = 0; m < 4; ++m) _Pragma("unroll") for (int k = 0; k < 2; ++k) dst[m][k] = *(const LAS bf16x8*)(lds + PG8_SA(b, h) + aoff + m * 2048 + k * 1024); } while (0)
; #define PG8_LDB(dst, b, h) do { _Pragma("unroll") for (int n = 0; n < 2; ++n) _Pragma("unroll") for (int k = 0; k < 2; ++k) dst[n][k] = *(const LAS bf16x8*)(lds + PG8_SB(b, h) + boff + n * 2048 + k * 1024); } while (0)
; #define PG8_MMA(ai, bj, At, Bt) do { __builtin_amdgcn_s_setprio(1); _Pragma("unroll") for (int m = 0; m < 4; ++m) _Pragma("unroll") for (int n = 0; n < 2; ++n) _Pragma("unroll") for (int k = 0; k < 2; ++k) \
;         acc[ai][bj][m][n] = __builtin_amdgcn_mfma_f32_16x16x32_bf16(Bt[n][k], At[m][k], acc[ai][bj][m][n], 0, 0, 0); __builtin_amdgcn_s_setprio(0); } while (0)
; #define PG8_WAIT_V(n) asm volatile("s_waitcnt vmcnt(" #n ")" ::: "memory")
; #define PG8_WAIT_L(n) asm volatile("s_waitcnt lgkmcnt(" #n ")" ::: "memory")
; #define PG8_BAR __builtin_amdgcn_s_barrier()
; #define PG8_SCHED __builtin_amdgcn_sched_barrier(0)
; template <class Epi, class Sched>
; __device__ __forceinline__ void gemm_phase(const int tid, LAS unsigned char* lds, const Gemm g, const Sched& S, const Epi& E) {
;     ...
;             PG8_LDB(B0, 1, 0); PG8_LDB(B1, 1, 1); PG8_SCHED; PG8_LDA(At, 1, 0); PG8_STAGE(PG8_SA(0, 1), a2 + hstep, voffA);
;             PG8_WAIT_V(8); PG8_WAIT_L(0); PG8_BAR; PG8_MMA(0, 0, At, B0); PG8_MMA(0, 1, At, B1); PG8_BAR; PG8_SCHED;
	s_add_i32 s71, 0, 0x18000
	s_add_i32 s72, 0, 0x1c000
	v_add_u32_e32 v174, s71, v144
	v_add_u32_e32 v199, s72, v144
	ds_read_b128 v[138:141], v174
	ds_read_b128 v[146:149], v174 offset:1024
	ds_read_b128 v[170:173], v174 offset:2048
	ds_read_b128 v[174:177], v174 offset:3072
	ds_read_b128 v[178:181], v199
	ds_read_b128 v[182:185], v199 offset:1024
	ds_read_b128 v[186:189], v199 offset:2048
	ds_read_b128 v[200:203], v199 offset:3072
	s_add_u32 s26, s26, 0x20000
	s_addc_u32 s27, s27, 0
	s_mov_b32 m0, s57
	v_lshl_add_u64 v[240:241], s[26:27], 0, v[128:129]
	ds_read_b128 v[204:207], v145 offset:32768
	ds_read_b128 v[208:211], v145 offset:33792
	ds_read_b128 v[212:215], v145 offset:34816
	ds_read_b128 v[216:219], v145 offset:35840
	ds_read_b128 v[220:223], v145 offset:36864
	ds_read_b128 v[224:227], v145 offset:37888
	ds_read_b128 v[228:231], v145 offset:38912
	ds_read_b128 v[232:235], v145 offset:39936
	global_load_lds_dwordx4 v[240:241], off
	v_lshl_add_u64 v[240:241], s[26:27], 0, v[130:131]
	s_mov_b32 m0, s58
	s_nop 0
	global_load_lds_dwordx4 v[240:241], off
	s_waitcnt vmcnt(8)
	s_waitcnt lgkmcnt(0)
	s_barrier
	s_setprio 1
	s_waitcnt lgkmcnt(0)
	v_mfma_f32_16x16x32_bf16 v[124:127], v[138:141], v[204:207], v[124:127]
	v_mfma_f32_16x16x32_bf16 v[120:123], v[170:173], v[204:207], v[120:123]
	v_mfma_f32_16x16x32_bf16 v[108:111], v[138:141], v[212:215], v[108:111]
	v_mfma_f32_16x16x32_bf16 v[104:107], v[170:173], v[212:215], v[104:107]
	v_mfma_f32_16x16x32_bf16 v[92:95], v[138:141], v[220:223], v[92:95]
	v_mfma_f32_16x16x32_bf16 v[88:91], v[170:173], v[220:223], v[88:91]
	v_mfma_f32_16x16x32_bf16 v[76:79], v[138:141], v[228:231], v[76:79]
	v_mfma_f32_16x16x32_bf16 v[72:75], v[170:173], v[228:231], v[72:75]
	v_mfma_f32_16x16x32_bf16 v[124:127], v[146:149], v[208:211], v[124:127]
	v_mfma_f32_16x16x32_bf16 v[120:123], v[174:177], v[208:211], v[120:123]
	v_mfma_f32_16x16x32_bf16 v[108:111], v[146:149], v[216:219], v[108:111]
	v_mfma_f32_16x16x32_bf16 v[104:107], v[174:177], v[216:219], v[104:107]
	v_mfma_f32_16x16x32_bf16 v[92:95], v[146:149], v[224:227], v[92:95]
	v_mfma_f32_16x16x32_bf16 v[88:91], v[174:177], v[224:227], v[88:91]
	v_mfma_f32_16x16x32_bf16 v[76:79], v[146:149], v[232:235], v[76:79]
	v_mfma_f32_16x16x32_bf16 v[72:75], v[174:177], v[232:235], v[72:75]
	v_mfma_f32_16x16x32_bf16 v[116:119], v[178:181], v[204:207], v[116:119]
	v_mfma_f32_16x16x32_bf16 v[112:115], v[186:189], v[204:207], v[112:115]
	v_mfma_f32_16x16x32_bf16 v[100:103], v[178:181], v[212:215], v[100:103]
	v_mfma_f32_16x16x32_bf16 v[96:99], v[186:189], v[212:215], v[96:99]
	v_mfma_f32_16x16x32_bf16 v[84:87], v[178:181], v[220:223], v[84:87]
	v_mfma_f32_16x16x32_bf16 v[80:83], v[186:189], v[220:223], v[80:83]
	v_mfma_f32_16x16x32_bf16 v[68:71], v[178:181], v[228:231], v[68:71]
	v_mfma_f32_16x16x32_bf16 v[64:67], v[186:189], v[228:231], v[64:67]
	v_mfma_f32_16x16x32_bf16 v[116:119], v[182:185], v[208:211], v[116:119]
	v_mfma_f32_16x16x32_bf16 v[112:115], v[200:203], v[208:211], v[112:115]
	v_mfma_f32_16x16x32_bf16 v[100:103], v[182:185], v[216:219], v[100:103]
	v_mfma_f32_16x16x32_bf16 v[96:99], v[200:203], v[216:219], v[96:99]
	v_mfma_f32_16x16x32_bf16 v[84:87], v[182:185], v[224:227], v[84:87]
	v_mfma_f32_16x16x32_bf16 v[80:83], v[200:203], v[224:227], v[80:83]
	v_mfma_f32_16x16x32_bf16 v[68:71], v[182:185], v[232:235], v[68:71]
	v_mfma_f32_16x16x32_bf16 v[64:67], v[200:203], v[232:235], v[64:67]
	s_setprio 0
	s_barrier
; #define PG8_STAGE(bufoff, gbase, voff) do { _Pragma("unroll") for (int _i = 0; _i < 2; ++_i) \
;         __builtin_amdgcn_global_load_lds((const unsigned*)((const char*)(gbase) + (voff)[_i]), (LAS unsigned*)(lds + (bufoff) + ldsw + _i * 8192), 16, 0, 0); } while (0)
; #define PG8_LDA(dst, b, h) do { _Pragma("unroll") for (int m = 0; m < 4; ++m) _Pragma("unroll") for (int k = 0; k < 2; ++k) dst[m][k] = *(const LAS bf16x8*)(lds + PG8_SA(b, h) + aoff + m * 2048 + k * 1024); } while (0)
; #define PG8_MMA(ai, bj, At, Bt) do { __builtin_amdgcn_s_setprio(1); _Pragma("unroll") for (int m = 0; m < 4; ++m) _Pragma("unroll") for (int n = 0; n < 2; ++n) _Pragma("unroll") for (int k = 0; k < 2; ++k) \
;         acc[ai][bj][m][n] = __builtin_amdgcn_mfma_f32_16x16x32_bf16(Bt[n][k], At[m][k], acc[ai][bj][m][n], 0, 0, 0); __builtin_amdgcn_s_setprio(0); } while (0)
; #define PG8_WAIT_V(n) asm volatile("s_waitcnt vmcnt(" #n ")" ::: "memory")
; #define PG8_WAIT_L(n) asm volatile("s_waitcnt lgkmcnt(" #n ")" ::: "memory")
; #define PG8_BAR __builtin_amdgcn_s_barrier()
; #define PG8_SCHED __builtin_amdgcn_sched_barrier(0)
; template <class Epi, class Sched>
; __device__ __forceinline__ void gemm_phase(const int tid, LAS unsigned char* lds, const Gemm g, const Sched& S, const Epi& E) {
;     ...
;             PG8_LDA(At, 1, 1); PG8_STAGE(PG8_SB(1, 0), b3, voffB); PG8_STAGE(PG8_SB(1, 1), b3 + hstep, voffB); PG8_STAGE(PG8_SA(1, 0), a3, voffA);
;             PG8_WAIT_V(8); PG8_WAIT_L(0); PG8_BAR; PG8_MMA(1, 0, At, B0); PG8_MMA(1, 1, At, B1); PG8_BAR; PG8_SCHED;
;         }
;         if (wr == 0) PG8_BAR;
	s_add_i32 s26, s71, s55
	v_lshl_add_u64 v[150:151], v[150:151], 0, s[34:35]
	s_mov_b32 m0, s26
	ds_read_b128 v[204:207], v145 offset:49152
	ds_read_b128 v[208:211], v145 offset:50176
	ds_read_b128 v[212:215], v145 offset:51200
	ds_read_b128 v[216:219], v145 offset:52224
	ds_read_b128 v[220:223], v145 offset:53248
	ds_read_b128 v[224:227], v145 offset:54272
	ds_read_b128 v[228:231], v145 offset:55296
	ds_read_b128 v[232:235], v145 offset:56320
	global_load_lds_dwordx4 v[150:151], off
	s_add_i32 m0, s26, 0x2000
	s_add_u32 s24, s24, 0x20080
	v_lshl_add_u64 v[150:151], v[190:191], 0, s[34:35]
	s_addc_u32 s25, s25, 0
	s_add_i32 s26, s72, s55
	global_load_lds_dwordx4 v[150:151], off
	v_lshl_add_u64 v[150:151], s[24:25], 0, v[152:153]
	s_mov_b32 m0, s26
	s_nop 0
	global_load_lds_dwordx4 v[150:151], off
	v_lshl_add_u64 v[150:151], s[24:25], 0, v[132:133]
	s_add_i32 m0, s26, 0x2000
	s_nop 0
	global_load_lds_dwordx4 v[150:151], off
	v_lshl_add_u64 v[150:151], v[236:237], 0, s[34:35]
	s_mov_b32 m0, s61
	s_nop 0
	global_load_lds_dwordx4 v[150:151], off
	v_lshl_add_u64 v[150:151], v[238:239], 0, s[34:35]
	s_mov_b32 m0, s62
	s_nop 0
	global_load_lds_dwordx4 v[150:151], off
	s_waitcnt vmcnt(8)
	s_waitcnt lgkmcnt(0)
	s_barrier
	s_setprio 1
	s_waitcnt lgkmcnt(0)
	v_mfma_f32_16x16x32_bf16 v[60:63], v[138:141], v[204:207], v[60:63]
	v_mfma_f32_16x16x32_bf16 v[56:59], v[170:173], v[204:207], v[56:59]
	v_mfma_f32_16x16x32_bf16 v[44:47], v[138:141], v[212:215], v[44:47]
	v_mfma_f32_16x16x32_bf16 v[40:43], v[170:173], v[212:215], v[40:43]
	v_mfma_f32_16x16x32_bf16 v[28:31], v[138:141], v[220:223], v[28:31]
	v_mfma_f32_16x16x32_bf16 v[24:27], v[170:173], v[220:223], v[24:27]
	v_mfma_f32_16x16x32_bf16 v[12:15], v[138:141], v[228:231], v[12:15]
	v_mfma_f32_16x16x32_bf16 v[8:11], v[170:173], v[228:231], v[8:11]
	v_mfma_f32_16x16x32_bf16 v[60:63], v[146:149], v[208:211], v[60:63]
	v_mfma_f32_16x16x32_bf16 v[56:59], v[174:177], v[208:211], v[56:59]
	v_mfma_f32_16x16x32_bf16 v[44:47], v[146:149], v[216:219], v[44:47]
	v_mfma_f32_16x16x32_bf16 v[40:43], v[174:177], v[216:219], v[40:43]
	v_mfma_f32_16x16x32_bf16 v[28:31], v[146:149], v[224:227], v[28:31]
	v_mfma_f32_16x16x32_bf16 v[24:27], v[174:177], v[224:227], v[24:27]
	v_mfma_f32_16x16x32_bf16 v[12:15], v[146:149], v[232:235], v[12:15]
	v_mfma_f32_16x16x32_bf16 v[8:11], v[174:177], v[232:235], v[8:11]
	v_mfma_f32_16x16x32_bf16 v[52:55], v[178:181], v[204:207], v[52:55]
	v_mfma_f32_16x16x32_bf16 v[48:51], v[186:189], v[204:207], v[48:51]
	v_mfma_f32_16x16x32_bf16 v[36:39], v[178:181], v[212:215], v[36:39]
	v_mfma_f32_16x16x32_bf16 v[32:35], v[186:189], v[212:215], v[32:35]
	v_mfma_f32_16x16x32_bf16 v[20:23], v[178:181], v[220:223], v[20:23]
	v_mfma_f32_16x16x32_bf16 v[16:19], v[186:189], v[220:223], v[16:19]
	v_mfma_f32_16x16x32_bf16 v[4:7], v[178:181], v[228:231], v[4:7]
	v_mfma_f32_16x16x32_bf16 v[0:3], v[186:189], v[228:231], v[0:3]
	v_mfma_f32_16x16x32_bf16 v[52:55], v[182:185], v[208:211], v[52:55]
	v_mfma_f32_16x16x32_bf16 v[48:51], v[200:203], v[208:211], v[48:51]
	v_mfma_f32_16x16x32_bf16 v[36:39], v[182:185], v[216:219], v[36:39]
	v_mfma_f32_16x16x32_bf16 v[32:35], v[200:203], v[216:219], v[32:35]
	v_mfma_f32_16x16x32_bf16 v[20:23], v[182:185], v[224:227], v[20:23]
	v_mfma_f32_16x16x32_bf16 v[16:19], v[200:203], v[224:227], v[16:19]
	v_mfma_f32_16x16x32_bf16 v[4:7], v[182:185], v[232:235], v[4:7]
	v_mfma_f32_16x16x32_bf16 v[0:3], v[200:203], v[232:235], v[0:3]
	s_setprio 0
	s_barrier
	s_add_i32 s70, s70, 2
	s_add_u32 s22, s22, 0x100
	s_addc_u32 s23, s23, 0
	s_add_u32 s68, s68, 0x100
	s_addc_u32 s69, s69, 0
	s_cmp_gt_u32 s70, 5
	s_cbranch_scc0 .LBB0_395
	s_and_b64 vcc, exec, s[10:11]
	s_cbranch_vccz .LBB0_398
	s_barrier

; #define PG8_STAGE(bufoff, gbase, voff) do { _Pragma("unroll") for (int _i = 0; _i < 2; ++_i) \
;         __builtin_amdgcn_global_load_lds((const unsigned*)((const char*)(gbase) + (voff)[_i]), (LAS unsigned*)(lds + (bufoff) + ldsw + _i * 8192), 16, 0, 0); } while (0)
; #define PG8_LDA(dst, b, h) do { _Pragma("unroll") for (int m = 0; m < 4; ++m) _Pragma("unroll") for (int k = 0; k < 2; ++k) dst[m][k] = *(const LAS bf16x8*)(lds + PG8_SA(b, h) + aoff + m * 2048 + k * 1024); } while (0)
; #define PG8_LDB(dst, b, h) do { _Pragma("unroll") for (int n = 0; n < 2; ++n) _Pragma("unroll") for (int k = 0; k < 2; ++k) dst[n][k] = *(const LAS bf16x8*)(lds + PG8_SB(b, h) + boff + n * 2048 + k * 1024); } while (0)
; #define PG8_MMA(ai, bj, At, Bt) do { __builtin_amdgcn_s_setprio(1); _Pragma("unroll") for (int m = 0; m < 4; ++m) _Pragma("unroll") for (int n = 0; n < 2; ++n) _Pragma("unroll") for (int k = 0; k < 2; ++k) \
;         acc[ai][bj][m][n] = __builtin_amdgcn_mfma_f32_16x16x32_bf16(Bt[n][k], At[m][k], acc[ai][bj][m][n], 0, 0, 0); __builtin_amdgcn_s_setprio(0); } while (0)
; template <class Epi, class Sched>
; __device__ __forceinline__ void gemm_phase(const int tid, LAS unsigned char* lds, const Gemm g, const Sched& S, const Epi& E) {
;     ...
;         const bool has_next = S.next(ui + 1, nxt);
;         const char* nA = has_next ? (const char*)g.A + (size_t)nxt.pm * tstep : cA; const char* nB = has_next ? (const char*)g.Bt + (size_t)nxt.pn * tstep : cB;
;         for (int t = 0; t < nt; t += 2) {
;             const bool last = (t == nt - 2);
;             const char* a1 = cA + (size_t)(t + 1) * kstep;
;             const char* a2 = last ? nA : cA + (size_t)(t + 2) * kstep; const char* b2 = last ? nB : cB + (size_t)(t + 2) * kstep;
;             const char* a3 = a2 + kstep; const char* b3 = b2 + kstep;
;             if (last && has_next) S.a_ready(nxt);
;             PG8_LDB(B0, 0, 0); PG8_LDB(B1, 0, 1); PG8_SCHED; PG8_LDA(At, 0, 0); PG8_STAGE(PG8_SA(1, 1), a1 + hstep, voffA);
;             PG8_WAIT_V(8); PG8_WAIT_L(0); PG8_BAR; PG8_MMA(0, 0, At, B0); PG8_MMA(0, 1, At, B1); PG8_BAR; PG8_SCHED;
;             PG8_LDA(At, 0, 1); PG8_STAGE(PG8_SB(0, 0), b2, voffB); PG8_STAGE(PG8_SB(0, 1), b2 + hstep, voffB); PG8_STAGE(PG8_SA(0, 0), a2, voffA);
;             PG8_WAIT_V(8); PG8_WAIT_L(0); PG8_BAR; PG8_MMA(1, 0, At, B0); PG8_MMA(1, 1, At, B1); PG8_BAR; PG8_SCHED;
.LBB0_549:
	s_ashr_i32 s17, s16, 31
	s_lshl_b64 s[18:19], s[16:17], 20
	s_add_u32 s18, s41, s18
	s_addc_u32 s19, s55, s19
	s_and_b64 s[20:21], s[0:1], exec
	s_cselect_b32 s5, s19, s25
	s_cselect_b32 s17, s18, s24
	s_ashr_i32 s15, s14, 31
	s_lshl_b64 s[20:21], s[14:15], 20
	s_add_u32 s20, s39, s20
	s_addc_u32 s21, s40, s21
	s_and_b64 s[28:29], s[0:1], exec
	s_cselect_b32 s15, s21, s27
	s_cselect_b32 s23, s20, s26
	s_add_u32 s24, s24, 0x80080
	s_addc_u32 s25, s25, 0
	s_add_u32 s69, s26, 0x100
	v_mov_b32_e32 v0, 0
	s_addc_u32 s70, s27, 0
	s_mov_b32 s71, -2
	s_waitcnt lgkmcnt(0)
	s_add_u32 s26, s24, 0xfff80080
	s_addc_u32 s27, s25, -1
	s_add_i32 s72, 0, 0x10000
	s_cmp_eq_u32 s71, 28
	s_cselect_b32 s29, s5, s27
	s_cselect_b32 s28, s17, s26
	s_cselect_b32 s27, s15, s70
	s_cselect_b32 s26, s23, s69
	s_add_i32 s74, 0, 0x14000
	v_add_u32_e32 v140, s72, v201
	v_add_u32_e32 v184, s74, v201
	ds_read_b128 v[128:131], v140
	ds_read_b128 v[132:135], v140 offset:1024
	ds_read_b128 v[136:139], v140 offset:2048
	ds_read_b128 v[140:143], v140 offset:3072
	ds_read_b128 v[144:147], v184
	ds_read_b128 v[148:151], v184 offset:1024
	ds_read_b128 v[180:183], v184 offset:2048
	ds_read_b128 v[184:187], v184 offset:3072
	v_lshl_add_u64 v[232:233], s[24:25], 0, v[176:177]
	s_add_i32 m0, s57, 0xc000
	ds_read_b128 v[188:191], v202
	ds_read_b128 v[204:207], v202 offset:1024
	ds_read_b128 v[208:211], v202 offset:2048
	ds_read_b128 v[212:215], v202 offset:3072
	ds_read_b128 v[216:219], v202 offset:4096
	ds_read_b128 v[220:223], v202 offset:5120
	ds_read_b128 v[224:227], v202 offset:6144
	ds_read_b128 v[228:231], v202 offset:7168
	global_load_lds_dwordx4 v[232:233], off
	v_lshl_add_u64 v[232:233], s[24:25], 0, v[178:179]
	s_add_i32 m0, s57, 0xe000
	s_nop 0
	global_load_lds_dwordx4 v[232:233], off
	s_waitcnt vmcnt(8)
	s_waitcnt lgkmcnt(0)
	s_barrier
	s_setprio 1
	s_waitcnt lgkmcnt(0)
	v_mfma_f32_16x16x32_bf16 v[124:127], v[128:131], v[188:191], 0
	v_mfma_f32_16x16x32_bf16 v[120:123], v[136:139], v[188:191], 0
	v_mfma_f32_16x16x32_bf16 v[108:111], v[128:131], v[208:211], 0
	v_mfma_f32_16x16x32_bf16 v[104:107], v[136:139], v[208:211], 0
	v_mfma_f32_16x16x32_bf16 v[92:95], v[128:131], v[216:219], 0
	v_mfma_f32_16x16x32_bf16 v[88:91], v[136:139], v[216:219], 0
	v_mfma_f32_16x16x32_bf16 v[76:79], v[128:131], v[224:227], 0
	v_mfma_f32_16x16x32_bf16 v[72:75], v[136:139], v[224:227], 0
	v_mfma_f32_16x16x32_bf16 v[124:127], v[132:135], v[204:207], v[124:127]
	v_mfma_f32_16x16x32_bf16 v[120:123], v[140:143], v[204:207], v[120:123]
	v_mfma_f32_16x16x32_bf16 v[108:111], v[132:135], v[212:215], v[108:111]
	v_mfma_f32_16x16x32_bf16 v[104:107], v[140:143], v[212:215], v[104:107]
	v_mfma_f32_16x16x32_bf16 v[92:95], v[132:135], v[220:223], v[92:95]
	v_mfma_f32_16x16x32_bf16 v[88:91], v[140:143], v[220:223], v[88:91]
	v_mfma_f32_16x16x32_bf16 v[76:79], v[132:135], v[228:231], v[76:79]
	v_mfma_f32_16x16x32_bf16 v[72:75], v[140:143], v[228:231], v[72:75]
	v_mfma_f32_16x16x32_bf16 v[116:119], v[144:147], v[188:191], 0
	v_mfma_f32_16x16x32_bf16 v[112:115], v[180:183], v[188:191], 0
	v_mfma_f32_16x16x32_bf16 v[100:103], v[144:147], v[208:211], 0
	v_mfma_f32_16x16x32_bf16 v[96:99], v[180:183], v[208:211], 0
	v_mfma_f32_16x16x32_bf16 v[84:87], v[144:147], v[216:219], 0
	v_mfma_f32_16x16x32_bf16 v[80:83], v[180:183], v[216:219], 0
	v_mfma_f32_16x16x32_bf16 v[68:71], v[144:147], v[224:227], 0
	v_mfma_f32_16x16x32_bf16 v[64:67], v[180:183], v[224:227], 0
	v_mfma_f32_16x16x32_bf16 v[116:119], v[148:151], v[204:207], v[116:119]
	v_mfma_f32_16x16x32_bf16 v[112:115], v[184:187], v[204:207], v[112:115]
	v_mfma_f32_16x16x32_bf16 v[100:103], v[148:151], v[212:215], v[100:103]
	v_mfma_f32_16x16x32_bf16 v[96:99], v[184:187], v[212:215], v[96:99]
	v_mfma_f32_16x16x32_bf16 v[84:87], v[148:151], v[220:223], v[84:87]
	v_mfma_f32_16x16x32_bf16 v[80:83], v[184:187], v[220:223], v[80:83]
	v_mfma_f32_16x16x32_bf16 v[68:71], v[148:151], v[228:231], v[68:71]
	v_mfma_f32_16x16x32_bf16 v[64:67], v[184:187], v[228:231], v[64:67]
	s_setprio 0
	s_barrier
	s_add_i32 s72, s72, s56
	v_lshl_add_u64 v[232:233], s[26:27], 0, v[152:153]
	s_mov_b32 m0, s72
	ds_read_b128 v[188:191], v202 offset:16384
	ds_read_b128 v[204:207], v202 offset:17408
	ds_read_b128 v[208:211], v202 offset:18432
	ds_read_b128 v[212:215], v202 offset:19456
	ds_read_b128 v[216:219], v202 offset:20480
	ds_read_b128 v[220:223], v202 offset:21504
	ds_read_b128 v[224:227], v202 offset:22528
	ds_read_b128 v[228:231], v202 offset:23552
	global_load_lds_dwordx4 v[232:233], off
	s_add_i32 m0, s72, 0x2000
	s_add_u32 s72, s26, 0x80000
	v_lshl_add_u64 v[234:235], s[26:27], 0, v[174:175]
	s_addc_u32 s73, s27, 0
	s_add_i32 s74, s74, s56
	global_load_lds_dwordx4 v[234:235], off
	v_lshl_add_u64 v[236:237], s[72:73], 0, v[152:153]
	s_mov_b32 m0, s74
	v_lshl_add_u64 v[238:239], s[28:29], 0, v[172:173]
	global_load_lds_dwordx4 v[236:237], off
	v_lshl_add_u64 v[236:237], s[72:73], 0, v[174:175]
	s_add_i32 m0, s74, 0x2000
	s_nop 0
	global_load_lds_dwordx4 v[236:237], off
	v_lshl_add_u64 v[236:237], s[28:29], 0, v[170:171]
	s_mov_b32 m0, s57
	s_nop 0
	global_load_lds_dwordx4 v[236:237], off
	s_mov_b32 m0, s58
	s_nop 0
	global_load_lds_dwordx4 v[238:239], off
	s_waitcnt vmcnt(8)
	s_waitcnt lgkmcnt(0)
	s_barrier
; #define PG8_STAGE(bufoff, gbase, voff) do { _Pragma("unroll") for (int _i = 0; _i < 2; ++_i) \
;         __builtin_amdgcn_global_load_lds((const unsigned*)((const char*)(gbase) + (voff)[_i]), (LAS unsigned*)(lds + (bufoff) + ldsw + _i * 8192), 16, 0, 0); } while (0)
; #define PG8_LDA(dst, b, h) do { _Pragma("unroll") for (int m = 0; m < 4; ++m) _Pragma("unroll") for (int k = 0; k < 2; ++k) dst[m][k] = *(const LAS bf16x8*)(lds + PG8_SA(b, h) + aoff + m * 2048 + k * 1024); } while (0)
; #define PG8_LDB(dst, b, h) do { _Pragma("unroll") for (int n = 0; n < 2; ++n) _Pragma("unroll") for (int k = 0; k < 2; ++k) dst[n][k] = *(const LAS bf16x8*)(lds + PG8_SB(b, h) + boff + n * 2048 + k * 1024); } while (0)
; #define PG8_MMA(ai, bj, At, Bt) do { __builtin_amdgcn_s_setprio(1); _Pragma("unroll") for (int m = 0; m < 4; ++m) _Pragma("unroll") for (int n = 0; n < 2; ++n) _Pragma("unroll") for (int k = 0; k < 2; ++k) \
;         acc[ai][bj][m][n] = __builtin_amdgcn_mfma_f32_16x16x32_bf16(Bt[n][k], At[m][k], acc[ai][bj][m][n], 0, 0, 0); __builtin_amdgcn_s_setprio(0); } while (0)
; #define PG8_WAIT_V(n) asm volatile("s_waitcnt vmcnt(" #n ")" ::: "memory")
; #define PG8_WAIT_L(n) asm volatile("s_waitcnt lgkmcnt(" #n ")" ::: "memory")
; #define PG8_BAR __builtin_amdgcn_s_barrier()
; #define PG8_SCHED __builtin_amdgcn_sched_barrier(0)
; template <class Epi, class Sched>
; __device__ __forceinline__ void gemm_phase(const int tid, LAS unsigned char* lds, const Gemm g, const Sched& S, const Epi& E) {
;     ...
;             PG8_WAIT_V(8); PG8_WAIT_L(0); PG8_BAR; PG8_MMA(1, 0, At, B0); PG8_MMA(1, 1, At, B1); PG8_BAR; PG8_SCHED;
;             PG8_LDB(B0, 1, 0); PG8_LDB(B1, 1, 1); PG8_SCHED; PG8_LDA(At, 1, 0); PG8_STAGE(PG8_SA(0, 1), a2 + hstep, voffA);
;             PG8_WAIT_V(8); PG8_WAIT_L(0); PG8_BAR; PG8_MMA(0, 0, At, B0); PG8_MMA(0, 1, At, B1); PG8_BAR; PG8_SCHED;
	s_setprio 1
	s_waitcnt lgkmcnt(0)
	v_mfma_f32_16x16x32_bf16 v[60:63], v[128:131], v[188:191], 0
	v_mfma_f32_16x16x32_bf16 v[56:59], v[136:139], v[188:191], 0
	v_mfma_f32_16x16x32_bf16 v[44:47], v[128:131], v[208:211], 0
	v_mfma_f32_16x16x32_bf16 v[40:43], v[136:139], v[208:211], 0
	v_mfma_f32_16x16x32_bf16 v[28:31], v[128:131], v[216:219], 0
	v_mfma_f32_16x16x32_bf16 v[24:27], v[136:139], v[216:219], 0
	v_mfma_f32_16x16x32_bf16 v[12:15], v[128:131], v[224:227], 0
	v_mfma_f32_16x16x32_bf16 v[8:11], v[136:139], v[224:227], 0
	v_mfma_f32_16x16x32_bf16 v[60:63], v[132:135], v[204:207], v[60:63]
	v_mfma_f32_16x16x32_bf16 v[56:59], v[140:143], v[204:207], v[56:59]
	v_mfma_f32_16x16x32_bf16 v[44:47], v[132:135], v[212:215], v[44:47]
	v_mfma_f32_16x16x32_bf16 v[40:43], v[140:143], v[212:215], v[40:43]
	v_mfma_f32_16x16x32_bf16 v[28:31], v[132:135], v[220:223], v[28:31]
	v_mfma_f32_16x16x32_bf16 v[24:27], v[140:143], v[220:223], v[24:27]
	v_mfma_f32_16x16x32_bf16 v[12:15], v[132:135], v[228:231], v[12:15]
	v_mfma_f32_16x16x32_bf16 v[8:11], v[140:143], v[228:231], v[8:11]
	v_mfma_f32_16x16x32_bf16 v[52:55], v[144:147], v[188:191], 0
	v_mfma_f32_16x16x32_bf16 v[48:51], v[180:183], v[188:191], 0
	v_mfma_f32_16x16x32_bf16 v[36:39], v[144:147], v[208:211], 0
	v_mfma_f32_16x16x32_bf16 v[32:35], v[180:183], v[208:211], 0
	v_mfma_f32_16x16x32_bf16 v[20:23], v[144:147], v[216:219], 0
	v_mfma_f32_16x16x32_bf16 v[16:19], v[180:183], v[216:219], 0
	v_mfma_f32_16x16x32_bf16 v[4:7], v[144:147], v[224:227], 0
	v_mfma_f32_16x16x32_bf16 v[0:3], v[180:183], v[224:227], 0
	v_mfma_f32_16x16x32_bf16 v[52:55], v[148:151], v[204:207], v[52:55]
	v_mfma_f32_16x16x32_bf16 v[48:51], v[184:187], v[204:207], v[48:51]
	v_mfma_f32_16x16x32_bf16 v[36:39], v[148:151], v[212:215], v[36:39]
	v_mfma_f32_16x16x32_bf16 v[32:35], v[184:187], v[212:215], v[32:35]
	v_mfma_f32_16x16x32_bf16 v[20:23], v[148:151], v[220:223], v[20:23]
	v_mfma_f32_16x16x32_bf16 v[16:19], v[184:187], v[220:223], v[16:19]
	v_mfma_f32_16x16x32_bf16 v[4:7], v[148:151], v[228:231], v[4:7]
	v_mfma_f32_16x16x32_bf16 v[0:3], v[184:187], v[228:231], v[0:3]
	s_setprio 0
	s_barrier
	s_add_i32 s72, 0, 0x18000
	s_add_i32 s73, 0, 0x1c000
	v_add_u32_e32 v140, s72, v201
	v_add_u32_e32 v184, s73, v201
	ds_read_b128 v[128:131], v140
	ds_read_b128 v[132:135], v140 offset:1024
	ds_read_b128 v[136:139], v140 offset:2048
	ds_read_b128 v[140:143], v140 offset:3072
	ds_read_b128 v[144:147], v184
	ds_read_b128 v[148:151], v184 offset:1024
	ds_read_b128 v[180:183], v184 offset:2048
	ds_read_b128 v[184:187], v184 offset:3072
	s_add_u32 s28, s28, 0x80000
	s_addc_u32 s29, s29, 0
	s_mov_b32 m0, s59
	v_lshl_add_u64 v[240:241], s[28:29], 0, v[170:171]
	ds_read_b128 v[188:191], v202 offset:32768
	ds_read_b128 v[204:207], v202 offset:33792
	ds_read_b128 v[208:211], v202 offset:34816
	ds_read_b128 v[212:215], v202 offset:35840
	ds_read_b128 v[216:219], v202 offset:36864
	ds_read_b128 v[220:223], v202 offset:37888
	ds_read_b128 v[224:227], v202 offset:38912
	ds_read_b128 v[228:231], v202 offset:39936
	global_load_lds_dwordx4 v[240:241], off
	v_lshl_add_u64 v[240:241], s[28:29], 0, v[172:173]
	s_mov_b32 m0, s60
	s_nop 0
	global_load_lds_dwordx4 v[240:241], off
	s_waitcnt vmcnt(8)
	s_waitcnt lgkmcnt(0)
	s_barrier
	s_setprio 1
	s_waitcnt lgkmcnt(0)
	v_mfma_f32_16x16x32_bf16 v[124:127], v[128:131], v[188:191], v[124:127]
	v_mfma_f32_16x16x32_bf16 v[120:123], v[136:139], v[188:191], v[120:123]
	v_mfma_f32_16x16x32_bf16 v[108:111], v[128:131], v[208:211], v[108:111]
	v_mfma_f32_16x16x32_bf16 v[104:107], v[136:139], v[208:211], v[104:107]
	v_mfma_f32_16x16x32_bf16 v[92:95], v[128:131], v[216:219], v[92:95]
	v_mfma_f32_16x16x32_bf16 v[88:91], v[136:139], v[216:219], v[88:91]
	v_mfma_f32_16x16x32_bf16 v[76:79], v[128:131], v[224:227], v[76:79]
	v_mfma_f32_16x16x32_bf16 v[72:75], v[136:139], v[224:227], v[72:75]
	v_mfma_f32_16x16x32_bf16 v[124:127], v[132:135], v[204:207], v[124:127]
	v_mfma_f32_16x16x32_bf16 v[120:123], v[140:143], v[204:207], v[120:123]
	v_mfma_f32_16x16x32_bf16 v[108:111], v[132:135], v[212:215], v[108:111]
	v_mfma_f32_16x16x32_bf16 v[104:107], v[140:143], v[212:215], v[104:107]
	v_mfma_f32_16x16x32_bf16 v[92:95], v[132:135], v[220:223], v[92:95]
	v_mfma_f32_16x16x32_bf16 v[88:91], v[140:143], v[220:223], v[88:91]
	v_mfma_f32_16x16x32_bf16 v[76:79], v[132:135], v[228:231], v[76:79]
	v_mfma_f32_16x16x32_bf16 v[72:75], v[140:143], v[228:231], v[72:75]
	v_mfma_f32_16x16x32_bf16 v[116:119], v[144:147], v[188:191], v[116:119]
	v_mfma_f32_16x16x32_bf16 v[112:115], v[180:183], v[188:191], v[112:115]
	v_mfma_f32_16x16x32_bf16 v[100:103], v[144:147], v[208:211], v[100:103]
	v_mfma_f32_16x16x32_bf16 v[96:99], v[180:183], v[208:211], v[96:99]
	v_mfma_f32_16x16x32_bf16 v[84:87], v[144:147], v[216:219], v[84:87]
	v_mfma_f32_16x16x32_bf16 v[80:83], v[180:183], v[216:219], v[80:83]
	v_mfma_f32_16x16x32_bf16 v[68:71], v[144:147], v[224:227], v[68:71]
	v_mfma_f32_16x16x32_bf16 v[64:67], v[180:183], v[224:227], v[64:67]
	v_mfma_f32_16x16x32_bf16 v[116:119], v[148:151], v[204:207], v[116:119]
	v_mfma_f32_16x16x32_bf16 v[112:115], v[184:187], v[204:207], v[112:115]
	v_mfma_f32_16x16x32_bf16 v[100:103], v[148:151], v[212:215], v[100:103]
	v_mfma_f32_16x16x32_bf16 v[96:99], v[184:187], v[212:215], v[96:99]
	v_mfma_f32_16x16x32_bf16 v[84:87], v[148:151], v[220:223], v[84:87]
	v_mfma_f32_16x16x32_bf16 v[80:83], v[184:187], v[220:223], v[80:83]
	v_mfma_f32_16x16x32_bf16 v[68:71], v[148:151], v[228:231], v[68:71]
	v_mfma_f32_16x16x32_bf16 v[64:67], v[184:187], v[228:231], v[64:67]
	s_setprio 0
	s_barrier
; #define PG8_STAGE(bufoff, gbase, voff) do { _Pragma("unroll") for (int _i = 0; _i < 2; ++_i) \
;         __builtin_amdgcn_global_load_lds((const unsigned*)((const char*)(gbase) + (voff)[_i]), (LAS unsigned*)(lds + (bufoff) + ldsw + _i * 8192), 16, 0, 0); } while (0)
; #define PG8_LDA(dst, b, h) do { _Pragma("unroll") for (int m = 0; m < 4; ++m) _Pragma("unroll") for (int k = 0; k < 2; ++k) dst[m][k] = *(const LAS bf16x8*)(lds + PG8_SA(b, h) + aoff + m * 2048 + k * 1024); } while (0)
; #define PG8_LDB(dst, b, h) do { _Pragma("unroll") for (int n = 0; n < 2; ++n) _Pragma("unroll") for (int k = 0; k < 2; ++k) dst[n][k] = *(const LAS bf16x8*)(lds + PG8_SB(b, h) + boff + n * 2048 + k * 1024); } while (0)
; #define PG8_WAIT_V(n) asm volatile("s_waitcnt vmcnt(" #n ")" ::: "memory")
; template <class Epi, class Sched>
; __device__ __forceinline__ void gemm_phase(const int tid, LAS unsigned char* lds, const Gemm g, const Sched& S, const Epi& E) {
;     ...
;         for (int t = 0; t < nt; t += 2) {
;             const bool last = (t == nt - 2);
;             const char* a1 = cA + (size_t)(t + 1) * kstep;
;             const char* a2 = last ? nA : cA + (size_t)(t + 2) * kstep; const char* b2 = last ? nB : cB + (size_t)(t + 2) * kstep;
;             const char* a3 = a2 + kstep; const char* b3 = b2 + kstep;
;             if (last && has_next) S.a_ready(nxt);
;             PG8_LDB(B0, 0, 0); PG8_LDB(B1, 0, 1); PG8_SCHED; PG8_LDA(At, 0, 0); PG8_STAGE(PG8_SA(1, 1), a1 + hstep, voffA);
;             PG8_WAIT_V(8); PG8_WAIT_L(0); PG8_BAR; PG8_MMA(0, 0, At, B0); PG8_MMA(0, 1, At, B1); PG8_BAR; PG8_SCHED;
;             PG8_LDA(At, 0, 1); PG8_STAGE(PG8_SB(0, 0), b2, voffB); PG8_STAGE(PG8_SB(0, 1), b2 + hstep, voffB); PG8_STAGE(PG8_SA(0, 0), a2, voffA);
;             PG8_WAIT_V(8); PG8_WAIT_L(0); PG8_BAR; PG8_MMA(1, 0, At, B0); PG8_MMA(1, 1, At, B1); PG8_BAR; PG8_SCHED;
;             PG8_LDB(B0, 1, 0); PG8_LDB(B1, 1, 1); PG8_SCHED; PG8_LDA(At, 1, 0); PG8_STAGE(PG8_SA(0, 1), a2 + hstep, voffA);
;             PG8_WAIT_V(8); PG8_WAIT_L(0); PG8_BAR; PG8_MMA(0, 0, At, B0); PG8_MMA(0, 1, At, B1); PG8_BAR; PG8_SCHED;
;             PG8_LDA(At, 1, 1); PG8_STAGE(PG8_SB(1, 0), b3, voffB); PG8_STAGE(PG8_SB(1, 1), b3 + hstep, voffB); PG8_STAGE(PG8_SA(1, 0), a3, voffA);
;             PG8_WAIT_V(8); PG8_WAIT_L(0); PG8_BAR; PG8_MMA(1, 0, At, B0); PG8_MMA(1, 1, At, B1); PG8_BAR; PG8_SCHED;
	s_add_i32 s28, s72, s56
	v_lshl_add_u64 v[232:233], v[232:233], 0, s[34:35]
	s_mov_b32 m0, s28
	ds_read_b128 v[188:191], v202 offset:49152
	ds_read_b128 v[204:207], v202 offset:50176
	ds_read_b128 v[208:211], v202 offset:51200
	ds_read_b128 v[212:215], v202 offset:52224
	ds_read_b128 v[216:219], v202 offset:53248
	ds_read_b128 v[220:223], v202 offset:54272
	ds_read_b128 v[224:227], v202 offset:55296
	ds_read_b128 v[228:231], v202 offset:56320
	global_load_lds_dwordx4 v[232:233], off
	s_add_i32 m0, s28, 0x2000
	s_add_u32 s26, s26, 0x80080
	v_lshl_add_u64 v[232:233], v[234:235], 0, s[34:35]
	s_addc_u32 s27, s27, 0
	s_add_i32 s28, s73, s56
	global_load_lds_dwordx4 v[232:233], off
	v_lshl_add_u64 v[232:233], s[26:27], 0, v[152:153]
	s_mov_b32 m0, s28
	s_nop 0
	global_load_lds_dwordx4 v[232:233], off
	v_lshl_add_u64 v[232:233], s[26:27], 0, v[174:175]
	s_add_i32 m0, s28, 0x2000
	s_nop 0
	global_load_lds_dwordx4 v[232:233], off
	v_lshl_add_u64 v[232:233], v[236:237], 0, s[34:35]
	s_mov_b32 m0, s64
	s_nop 0
	global_load_lds_dwordx4 v[232:233], off
	v_lshl_add_u64 v[232:233], v[238:239], 0, s[34:35]
	s_mov_b32 m0, s65
	s_nop 0
	global_load_lds_dwordx4 v[232:233], off
	s_waitcnt vmcnt(8)
	s_waitcnt lgkmcnt(0)
	s_barrier
	s_setprio 1
	s_waitcnt lgkmcnt(0)
	v_mfma_f32_16x16x32_bf16 v[60:63], v[128:131], v[188:191], v[60:63]
	v_mfma_f32_16x16x32_bf16 v[56:59], v[136:139], v[188:191], v[56:59]
	v_mfma_f32_16x16x32_bf16 v[44:47], v[128:131], v[208:211], v[44:47]
	v_mfma_f32_16x16x32_bf16 v[40:43], v[136:139], v[208:211], v[40:43]
	v_mfma_f32_16x16x32_bf16 v[28:31], v[128:131], v[216:219], v[28:31]
	v_mfma_f32_16x16x32_bf16 v[24:27], v[136:139], v[216:219], v[24:27]
	v_mfma_f32_16x16x32_bf16 v[12:15], v[128:131], v[224:227], v[12:15]
	v_mfma_f32_16x16x32_bf16 v[8:11], v[136:139], v[224:227], v[8:11]
	v_mfma_f32_16x16x32_bf16 v[60:63], v[132:135], v[204:207], v[60:63]
	v_mfma_f32_16x16x32_bf16 v[56:59], v[140:143], v[204:207], v[56:59]
	v_mfma_f32_16x16x32_bf16 v[44:47], v[132:135], v[212:215], v[44:47]
	v_mfma_f32_16x16x32_bf16 v[40:43], v[140:143], v[212:215], v[40:43]
	v_mfma_f32_16x16x32_bf16 v[28:31], v[132:135], v[220:223], v[28:31]
	v_mfma_f32_16x16x32_bf16 v[24:27], v[140:143], v[220:223], v[24:27]
	v_mfma_f32_16x16x32_bf16 v[12:15], v[132:135], v[228:231], v[12:15]
	v_mfma_f32_16x16x32_bf16 v[8:11], v[140:143], v[228:231], v[8:11]
	v_mfma_f32_16x16x32_bf16 v[52:55], v[144:147], v[188:191], v[52:55]
	v_mfma_f32_16x16x32_bf16 v[48:51], v[180:183], v[188:191], v[48:51]
	v_mfma_f32_16x16x32_bf16 v[36:39], v[144:147], v[208:211], v[36:39]
	v_mfma_f32_16x16x32_bf16 v[32:35], v[180:183], v[208:211], v[32:35]
	v_mfma_f32_16x16x32_bf16 v[20:23], v[144:147], v[216:219], v[20:23]
	v_mfma_f32_16x16x32_bf16 v[16:19], v[180:183], v[216:219], v[16:19]
	v_mfma_f32_16x16x32_bf16 v[4:7], v[144:147], v[224:227], v[4:7]
	v_mfma_f32_16x16x32_bf16 v[0:3], v[180:183], v[224:227], v[0:3]
	v_mfma_f32_16x16x32_bf16 v[52:55], v[148:151], v[204:207], v[52:55]
	v_mfma_f32_16x16x32_bf16 v[48:51], v[184:187], v[204:207], v[48:51]
	v_mfma_f32_16x16x32_bf16 v[36:39], v[148:151], v[212:215], v[36:39]
	v_mfma_f32_16x16x32_bf16 v[32:35], v[184:187], v[212:215], v[32:35]
	v_mfma_f32_16x16x32_bf16 v[20:23], v[148:151], v[220:223], v[20:23]
	v_mfma_f32_16x16x32_bf16 v[16:19], v[184:187], v[220:223], v[16:19]
	v_mfma_f32_16x16x32_bf16 v[4:7], v[148:151], v[228:231], v[4:7]
	v_mfma_f32_16x16x32_bf16 v[0:3], v[184:187], v[228:231], v[0:3]
	s_setprio 0
	s_barrier
	s_add_i32 s71, s71, 2
	s_add_u32 s24, s24, 0x100
	s_addc_u32 s25, s25, 0
	s_add_u32 s69, s69, 0x100
	s_addc_u32 s70, s70, 0
	s_cmp_gt_u32 s71, 29
.LBB0_550:
	s_add_u32 s26, s24, 0xfff80080
	s_addc_u32 s27, s25, -1
	s_add_i32 s72, 0, 0x10000
	s_cmp_eq_u32 s71, 28
	s_cselect_b32 s29, s5, s27
	s_cselect_b32 s28, s17, s26
	s_cselect_b32 s27, s15, s70
	s_cselect_b32 s26, s23, s69
	s_add_i32 s74, 0, 0x14000
	v_add_u32_e32 v140, s72, v201
	v_add_u32_e32 v184, s74, v201
	ds_read_b128 v[128:131], v140
	ds_read_b128 v[132:135], v140 offset:1024
	ds_read_b128 v[136:139], v140 offset:2048
	ds_read_b128 v[140:143], v140 offset:3072
	ds_read_b128 v[144:147], v184
	ds_read_b128 v[148:151], v184 offset:1024
	ds_read_b128 v[180:183], v184 offset:2048
	ds_read_b128 v[184:187], v184 offset:3072
	v_lshl_add_u64 v[232:233], s[24:25], 0, v[176:177]
	s_add_i32 m0, s57, 0xc000
	ds_read_b128 v[188:191], v202
	ds_read_b128 v[204:207], v202 offset:1024
	ds_read_b128 v[208:211], v202 offset:2048
	ds_read_b128 v[212:215], v202 offset:3072
	ds_read_b128 v[216:219], v202 offset:4096
	ds_read_b128 v[220:223], v202 offset:5120
	ds_read_b128 v[224:227], v202 offset:6144
	ds_read_b128 v[228:231], v202 offset:7168
	global_load_lds_dwordx4 v[232:233], off
	v_lshl_add_u64 v[232:233], s[24:25], 0, v[178:179]
	s_add_i32 m0, s57, 0xe000
	s_nop 0
	global_load_lds_dwordx4 v[232:233], off
	s_waitcnt vmcnt(8)
	s_waitcnt lgkmcnt(0)
	s_barrier
; #define PG8_STAGE(bufoff, gbase, voff) do { _Pragma("unroll") for (int _i = 0; _i < 2; ++_i) \
;         __builtin_amdgcn_global_load_lds((const unsigned*)((const char*)(gbase) + (voff)[_i]), (LAS unsigned*)(lds + (bufoff) + ldsw + _i * 8192), 16, 0, 0); } while (0)
; #define PG8_LDA(dst, b, h) do { _Pragma("unroll") for (int m = 0; m < 4; ++m) _Pragma("unroll") for (int k = 0; k < 2; ++k) dst[m][k] = *(const LAS bf16x8*)(lds + PG8_SA(b, h) + aoff + m * 2048 + k * 1024); } while (0)
; #define PG8_MMA(ai, bj, At, Bt) do { __builtin_amdgcn_s_setprio(1); _Pragma("unroll") for (int m = 0; m < 4; ++m) _Pragma("unroll") for (int n = 0; n < 2; ++n) _Pragma("unroll") for (int k = 0; k < 2; ++k) \
;         acc[ai][bj][m][n] = __builtin_amdgcn_mfma_f32_16x16x32_bf16(Bt[n][k], At[m][k], acc[ai][bj][m][n], 0, 0, 0); __builtin_amdgcn_s_setprio(0); } while (0)
; #define PG8_WAIT_V(n) asm volatile("s_waitcnt vmcnt(" #n ")" ::: "memory")
; #define PG8_WAIT_L(n) asm volatile("s_waitcnt lgkmcnt(" #n ")" ::: "memory")
; #define PG8_BAR __builtin_amdgcn_s_barrier()
; #define PG8_SCHED __builtin_amdgcn_sched_barrier(0)
; template <class Epi, class Sched>
; __device__ __forceinline__ void gemm_phase(const int tid, LAS unsigned char* lds, const Gemm g, const Sched& S, const Epi& E) {
;     ...
;             PG8_WAIT_V(8); PG8_WAIT_L(0); PG8_BAR; PG8_MMA(0, 0, At, B0); PG8_MMA(0, 1, At, B1); PG8_BAR; PG8_SCHED;
;             PG8_LDA(At, 0, 1); PG8_STAGE(PG8_SB(0, 0), b2, voffB); PG8_STAGE(PG8_SB(0, 1), b2 + hstep, voffB); PG8_STAGE(PG8_SA(0, 0), a2, voffA);
;             PG8_WAIT_V(8); PG8_WAIT_L(0); PG8_BAR; PG8_MMA(1, 0, At, B0); PG8_MMA(1, 1, At, B1); PG8_BAR; PG8_SCHED;
	s_setprio 1
	s_waitcnt lgkmcnt(0)
	v_mfma_f32_16x16x32_bf16 v[124:127], v[128:131], v[188:191], v[124:127]
	v_mfma_f32_16x16x32_bf16 v[120:123], v[136:139], v[188:191], v[120:123]
	v_mfma_f32_16x16x32_bf16 v[108:111], v[128:131], v[208:211], v[108:111]
	v_mfma_f32_16x16x32_bf16 v[104:107], v[136:139], v[208:211], v[104:107]
	v_mfma_f32_16x16x32_bf16 v[92:95], v[128:131], v[216:219], v[92:95]
	v_mfma_f32_16x16x32_bf16 v[88:91], v[136:139], v[216:219], v[88:91]
	v_mfma_f32_16x16x32_bf16 v[76:79], v[128:131], v[224:227], v[76:79]
	v_mfma_f32_16x16x32_bf16 v[72:75], v[136:139], v[224:227], v[72:75]
	v_mfma_f32_16x16x32_bf16 v[124:127], v[132:135], v[204:207], v[124:127]
	v_mfma_f32_16x16x32_bf16 v[120:123], v[140:143], v[204:207], v[120:123]
	v_mfma_f32_16x16x32_bf16 v[108:111], v[132:135], v[212:215], v[108:111]
	v_mfma_f32_16x16x32_bf16 v[104:107], v[140:143], v[212:215], v[104:107]
	v_mfma_f32_16x16x32_bf16 v[92:95], v[132:135], v[220:223], v[92:95]
	v_mfma_f32_16x16x32_bf16 v[88:91], v[140:143], v[220:223], v[88:91]
	v_mfma_f32_16x16x32_bf16 v[76:79], v[132:135], v[228:231], v[76:79]
	v_mfma_f32_16x16x32_bf16 v[72:75], v[140:143], v[228:231], v[72:75]
	v_mfma_f32_16x16x32_bf16 v[116:119], v[144:147], v[188:191], v[116:119]
	v_mfma_f32_16x16x32_bf16 v[112:115], v[180:183], v[188:191], v[112:115]
	v_mfma_f32_16x16x32_bf16 v[100:103], v[144:147], v[208:211], v[100:103]
	v_mfma_f32_16x16x32_bf16 v[96:99], v[180:183], v[208:211], v[96:99]
	v_mfma_f32_16x16x32_bf16 v[84:87], v[144:147], v[216:219], v[84:87]
	v_mfma_f32_16x16x32_bf16 v[80:83], v[180:183], v[216:219], v[80:83]
	v_mfma_f32_16x16x32_bf16 v[68:71], v[144:147], v[224:227], v[68:71]
	v_mfma_f32_16x16x32_bf16 v[64:67], v[180:183], v[224:227], v[64:67]
	v_mfma_f32_16x16x32_bf16 v[116:119], v[148:151], v[204:207], v[116:119]
	v_mfma_f32_16x16x32_bf16 v[112:115], v[184:187], v[204:207], v[112:115]
	v_mfma_f32_16x16x32_bf16 v[100:103], v[148:151], v[212:215], v[100:103]
	v_mfma_f32_16x16x32_bf16 v[96:99], v[184:187], v[212:215], v[96:99]
	v_mfma_f32_16x16x32_bf16 v[84:87], v[148:151], v[220:223], v[84:87]
	v_mfma_f32_16x16x32_bf16 v[80:83], v[184:187], v[220:223], v[80:83]
	v_mfma_f32_16x16x32_bf16 v[68:71], v[148:151], v[228:231], v[68:71]
	v_mfma_f32_16x16x32_bf16 v[64:67], v[184:187], v[228:231], v[64:67]
	s_setprio 0
	s_barrier
	s_add_i32 s72, s72, s56
	v_lshl_add_u64 v[232:233], s[26:27], 0, v[152:153]
	s_mov_b32 m0, s72
	ds_read_b128 v[188:191], v202 offset:16384
	ds_read_b128 v[204:207], v202 offset:17408
	ds_read_b128 v[208:211], v202 offset:18432
	ds_read_b128 v[212:215], v202 offset:19456
	ds_read_b128 v[216:219], v202 offset:20480
	ds_read_b128 v[220:223], v202 offset:21504
	ds_read_b128 v[224:227], v202 offset:22528
	ds_read_b128 v[228:231], v202 offset:23552
	global_load_lds_dwordx4 v[232:233], off
	s_add_i32 m0, s72, 0x2000
	s_add_u32 s72, s26, 0x80000
	v_lshl_add_u64 v[234:235], s[26:27], 0, v[174:175]
	s_addc_u32 s73, s27, 0
	s_add_i32 s74, s74, s56
	global_load_lds_dwordx4 v[234:235], off
	v_lshl_add_u64 v[236:237], s[72:73], 0, v[152:153]
	s_mov_b32 m0, s74
	v_lshl_add_u64 v[238:239], s[28:29], 0, v[172:173]
	global_load_lds_dwordx4 v[236:237], off
	v_lshl_add_u64 v[236:237], s[72:73], 0, v[174:175]
	s_add_i32 m0, s74, 0x2000
	s_nop 0
	global_load_lds_dwordx4 v[236:237], off
	v_lshl_add_u64 v[236:237], s[28:29], 0, v[170:171]
	s_mov_b32 m0, s57
	s_nop 0
	global_load_lds_dwordx4 v[236:237], off
	s_mov_b32 m0, s58
	s_nop 0
	global_load_lds_dwordx4 v[238:239], off
	s_waitcnt vmcnt(8)
	s_waitcnt lgkmcnt(0)
	s_barrier
	s_setprio 1
	s_waitcnt lgkmcnt(0)
	v_mfma_f32_16x16x32_bf16 v[60:63], v[128:131], v[188:191], v[60:63]
	v_mfma_f32_16x16x32_bf16 v[56:59], v[136:139], v[188:191], v[56:59]
	v_mfma_f32_16x16x32_bf16 v[44:47], v[128:131], v[208:211], v[44:47]
	v_mfma_f32_16x16x32_bf16 v[40:43], v[136:139], v[208:211], v[40:43]
	v_mfma_f32_16x16x32_bf16 v[28:31], v[128:131], v[216:219], v[28:31]
	v_mfma_f32_16x16x32_bf16 v[24:27], v[136:139], v[216:219], v[24:27]
	v_mfma_f32_16x16x32_bf16 v[12:15], v[128:131], v[224:227], v[12:15]
	v_mfma_f32_16x16x32_bf16 v[8:11], v[136:139], v[224:227], v[8:11]
	v_mfma_f32_16x16x32_bf16 v[60:63], v[132:135], v[204:207], v[60:63]
	v_mfma_f32_16x16x32_bf16 v[56:59], v[140:143], v[204:207], v[56:59]
	v_mfma_f32_16x16x32_bf16 v[44:47], v[132:135], v[212:215], v[44:47]
	v_mfma_f32_16x16x32_bf16 v[40:43], v[140:143], v[212:215], v[40:43]
	v_mfma_f32_16x16x32_bf16 v[28:31], v[132:135], v[220:223], v[28:31]
	v_mfma_f32_16x16x32_bf16 v[24:27], v[140:143], v[220:223], v[24:27]
	v_mfma_f32_16x16x32_bf16 v[12:15], v[132:135], v[228:231], v[12:15]
	v_mfma_f32_16x16x32_bf16 v[8:11], v[140:143], v[228:231], v[8:11]
	v_mfma_f32_16x16x32_bf16 v[52:55], v[144:147], v[188:191], v[52:55]
	v_mfma_f32_16x16x32_bf16 v[48:51], v[180:183], v[188:191], v[48:51]
	v_mfma_f32_16x16x32_bf16 v[36:39], v[144:147], v[208:211], v[36:39]
	v_mfma_f32_16x16x32_bf16 v[32:35], v[180:183], v[208:211], v[32:35]
	v_mfma_f32_16x16x32_bf16 v[20:23], v[144:147], v[216:219], v[20:23]
	v_mfma_f32_16x16x32_bf16 v[16:19], v[180:183], v[216:219], v[16:19]
	v_mfma_f32_16x16x32_bf16 v[4:7], v[144:147], v[224:227], v[4:7]
	v_mfma_f32_16x16x32_bf16 v[0:3], v[180:183], v[224:227], v[0:3]
	v_mfma_f32_16x16x32_bf16 v[52:55], v[148:151], v[204:207], v[52:55]
	v_mfma_f32_16x16x32_bf16 v[48:51], v[184:187], v[204:207], v[48:51]
	v_mfma_f32_16x16x32_bf16 v[36:39], v[148:151], v[212:215], v[36:39]
	v_mfma_f32_16x16x32_bf16 v[32:35], v[184:187], v[212:215], v[32:35]
	v_mfma_f32_16x16x32_bf16 v[20:23], v[148:151], v[220:223], v[20:23]
	v_mfma_f32_16x16x32_bf16 v[16:19], v[184:187], v[220:223], v[16:19]
	v_mfma_f32_16x16x32_bf16 v[4:7], v[148:151], v[228:231], v[4:7]
	v_mfma_f32_16x16x32_bf16 v[0:3], v[184:187], v[228:231], v[0:3]
	s_setprio 0
	s_barrier
; #define PG8_STAGE(bufoff, gbase, voff) do { _Pragma("unroll") for (int _i = 0; _i < 2; ++_i) \
;         __builtin_amdgcn_global_load_lds((const unsigned*)((const char*)(gbase) + (voff)[_i]), (LAS unsigned*)(lds + (bufoff) + ldsw + _i * 8192), 16, 0, 0); } while (0)
; #define PG8_LDA(dst, b, h) do { _Pragma("unroll") for (int m = 0; m < 4; ++m) _Pragma("unroll") for (int k = 0; k < 2; ++k) dst[m][k] = *(const LAS bf16x8*)(lds + PG8_SA(b, h) + aoff + m * 2048 + k * 1024); } while (0)
; #define PG8_LDB(dst, b, h) do { _Pragma("unroll") for (int n = 0; n < 2; ++n) _Pragma("unroll") for (int k = 0; k < 2; ++k) dst[n][k] = *(const LAS bf16x8*)(lds + PG8_SB(b, h) + boff + n * 2048 + k * 1024); } while (0)
; #define PG8_MMA(ai, bj, At, Bt) do { __builtin_amdgcn_s_setprio(1); _Pragma("unroll") for (int m = 0; m < 4; ++m) _Pragma("unroll") for (int n = 0; n < 2; ++n) _Pragma("unroll") for (int k = 0; k < 2; ++k) \
;         acc[ai][bj][m][n] = __builtin_amdgcn_mfma_f32_16x16x32_bf16(Bt[n][k], At[m][k], acc[ai][bj][m][n], 0, 0, 0); __builtin_amdgcn_s_setprio(0); } while (0)
; #define PG8_WAIT_V(n) asm volatile("s_waitcnt vmcnt(" #n ")" ::: "memory")
; #define PG8_WAIT_L(n) asm volatile("s_waitcnt lgkmcnt(" #n ")" ::: "memory")
; #define PG8_BAR __builtin_amdgcn_s_barrier()
; #define PG8_SCHED __builtin_amdgcn_sched_barrier(0)
; template <class Epi, class Sched>
; __device__ __forceinline__ void gemm_phase(const int tid, LAS unsigned char* lds, const Gemm g, const Sched& S, const Epi& E) {
;     ...
;             PG8_LDB(B0, 1, 0); PG8_LDB(B1, 1, 1); PG8_SCHED; PG8_LDA(At, 1, 0); PG8_STAGE(PG8_SA(0, 1), a2 + hstep, voffA);
;             PG8_WAIT_V(8); PG8_WAIT_L(0); PG8_BAR; PG8_MMA(0, 0, At, B0); PG8_MMA(0, 1, At, B1); PG8_BAR; PG8_SCHED;
	s_add_i32 s72, 0, 0x18000
	s_add_i32 s73, 0, 0x1c000
	v_add_u32_e32 v140, s72, v201
	v_add_u32_e32 v184, s73, v201
	ds_read_b128 v[128:131], v140
	ds_read_b128 v[132:135], v140 offset:1024
	ds_read_b128 v[136:139], v140 offset:2048
	ds_read_b128 v[140:143], v140 offset:3072
	ds_read_b128 v[144:147], v184
	ds_read_b128 v[148:151], v184 offset:1024
	ds_read_b128 v[180:183], v184 offset:2048
	ds_read_b128 v[184:187], v184 offset:3072
	s_add_u32 s28, s28, 0x80000
	s_addc_u32 s29, s29, 0
	s_mov_b32 m0, s59
	v_lshl_add_u64 v[240:241], s[28:29], 0, v[170:171]
	ds_read_b128 v[188:191], v202 offset:32768
	ds_read_b128 v[204:207], v202 offset:33792
	ds_read_b128 v[208:211], v202 offset:34816
	ds_read_b128 v[212:215], v202 offset:35840
	ds_read_b128 v[216:219], v202 offset:36864
	ds_read_b128 v[220:223], v202 offset:37888
	ds_read_b128 v[224:227], v202 offset:38912
	ds_read_b128 v[228:231], v202 offset:39936
	global_load_lds_dwordx4 v[240:241], off
	v_lshl_add_u64 v[240:241], s[28:29], 0, v[172:173]
	s_mov_b32 m0, s60
	s_nop 0
	global_load_lds_dwordx4 v[240:241], off
	s_waitcnt vmcnt(8)
	s_waitcnt lgkmcnt(0)
	s_barrier
	s_setprio 1
	s_waitcnt lgkmcnt(0)
	v_mfma_f32_16x16x32_bf16 v[124:127], v[128:131], v[188:191], v[124:127]
	v_mfma_f32_16x16x32_bf16 v[120:123], v[136:139], v[188:191], v[120:123]
	v_mfma_f32_16x16x32_bf16 v[108:111], v[128:131], v[208:211], v[108:111]
	v_mfma_f32_16x16x32_bf16 v[104:107], v[136:139], v[208:211], v[104:107]
	v_mfma_f32_16x16x32_bf16 v[92:95], v[128:131], v[216:219], v[92:95]
	v_mfma_f32_16x16x32_bf16 v[88:91], v[136:139], v[216:219], v[88:91]
	v_mfma_f32_16x16x32_bf16 v[76:79], v[128:131], v[224:227], v[76:79]
	v_mfma_f32_16x16x32_bf16 v[72:75], v[136:139], v[224:227], v[72:75]
	v_mfma_f32_16x16x32_bf16 v[124:127], v[132:135], v[204:207], v[124:127]
	v_mfma_f32_16x16x32_bf16 v[120:123], v[140:143], v[204:207], v[120:123]
	v_mfma_f32_16x16x32_bf16 v[108:111], v[132:135], v[212:215], v[108:111]
	v_mfma_f32_16x16x32_bf16 v[104:107], v[140:143], v[212:215], v[104:107]
	v_mfma_f32_16x16x32_bf16 v[92:95], v[132:135], v[220:223], v[92:95]
	v_mfma_f32_16x16x32_bf16 v[88:91], v[140:143], v[220:223], v[88:91]
	v_mfma_f32_16x16x32_bf16 v[76:79], v[132:135], v[228:231], v[76:79]
	v_mfma_f32_16x16x32_bf16 v[72:75], v[140:143], v[228:231], v[72:75]
	v_mfma_f32_16x16x32_bf16 v[116:119], v[144:147], v[188:191], v[116:119]
	v_mfma_f32_16x16x32_bf16 v[112:115], v[180:183], v[188:191], v[112:115]
	v_mfma_f32_16x16x32_bf16 v[100:103], v[144:147], v[208:211], v[100:103]
	v_mfma_f32_16x16x32_bf16 v[96:99], v[180:183], v[208:211], v[96:99]
	v_mfma_f32_16x16x32_bf16 v[84:87], v[144:147], v[216:219], v[84:87]
	v_mfma_f32_16x16x32_bf16 v[80:83], v[180:183], v[216:219], v[80:83]
	v_mfma_f32_16x16x32_bf16 v[68:71], v[144:147], v[224:227], v[68:71]
	v_mfma_f32_16x16x32_bf16 v[64:67], v[180:183], v[224:227], v[64:67]
	v_mfma_f32_16x16x32_bf16 v[116:119], v[148:151], v[204:207], v[116:119]
	v_mfma_f32_16x16x32_bf16 v[112:115], v[184:187], v[204:207], v[112:115]
	v_mfma_f32_16x16x32_bf16 v[100:103], v[148:151], v[212:215], v[100:103]
	v_mfma_f32_16x16x32_bf16 v[96:99], v[184:187], v[212:215], v[96:99]
	v_mfma_f32_16x16x32_bf16 v[84:87], v[148:151], v[220:223], v[84:87]
	v_mfma_f32_16x16x32_bf16 v[80:83], v[184:187], v[220:223], v[80:83]
	v_mfma_f32_16x16x32_bf16 v[68:71], v[148:151], v[228:231], v[68:71]
	v_mfma_f32_16x16x32_bf16 v[64:67], v[184:187], v[228:231], v[64:67]
	s_setprio 0
	s_barrier
; #define PG8_STAGE(bufoff, gbase, voff) do { _Pragma("unroll") for (int _i = 0; _i < 2; ++_i) \
;         __builtin_amdgcn_global_load_lds((const unsigned*)((const char*)(gbase) + (voff)[_i]), (LAS unsigned*)(lds + (bufoff) + ldsw + _i * 8192), 16, 0, 0); } while (0)
; #define PG8_LDA(dst, b, h) do { _Pragma("unroll") for (int m = 0; m < 4; ++m) _Pragma("unroll") for (int k = 0; k < 2; ++k) dst[m][k] = *(const LAS bf16x8*)(lds + PG8_SA(b, h) + aoff + m * 2048 + k * 1024); } while (0)
; #define PG8_MMA(ai, bj, At, Bt) do { __builtin_amdgcn_s_setprio(1); _Pragma("unroll") for (int m = 0; m < 4; ++m) _Pragma("unroll") for (int n = 0; n < 2; ++n) _Pragma("unroll") for (int k = 0; k < 2; ++k) \
;         acc[ai][bj][m][n] = __builtin_amdgcn_mfma_f32_16x16x32_bf16(Bt[n][k], At[m][k], acc[ai][bj][m][n], 0, 0, 0); __builtin_amdgcn_s_setprio(0); } while (0)
; #define PG8_WAIT_V(n) asm volatile("s_waitcnt vmcnt(" #n ")" ::: "memory")
; #define PG8_WAIT_L(n) asm volatile("s_waitcnt lgkmcnt(" #n ")" ::: "memory")
; #define PG8_BAR __builtin_amdgcn_s_barrier()
; #define PG8_SCHED __builtin_amdgcn_sched_barrier(0)
; template <class Epi, class Sched>
; __device__ __forceinline__ void gemm_phase(const int tid, LAS unsigned char* lds, const Gemm g, const Sched& S, const Epi& E) {
;     ...
;             PG8_LDA(At, 1, 1); PG8_STAGE(PG8_SB(1, 0), b3, voffB); PG8_STAGE(PG8_SB(1, 1), b3 + hstep, voffB); PG8_STAGE(PG8_SA(1, 0), a3, voffA);
;             PG8_WAIT_V(8); PG8_WAIT_L(0); PG8_BAR; PG8_MMA(1, 0, At, B0); PG8_MMA(1, 1, At, B1); PG8_BAR; PG8_SCHED;
;         }
;         if (wr == 0) PG8_BAR;
	s_add_i32 s28, s72, s56
	v_lshl_add_u64 v[232:233], v[232:233], 0, s[34:35]
	s_mov_b32 m0, s28
	ds_read_b128 v[188:191], v202 offset:49152
	ds_read_b128 v[204:207], v202 offset:50176
	ds_read_b128 v[208:211], v202 offset:51200
	ds_read_b128 v[212:215], v202 offset:52224
	ds_read_b128 v[216:219], v202 offset:53248
	ds_read_b128 v[220:223], v202 offset:54272
	ds_read_b128 v[224:227], v202 offset:55296
	ds_read_b128 v[228:231], v202 offset:56320
	global_load_lds_dwordx4 v[232:233], off
	s_add_i32 m0, s28, 0x2000
	s_add_u32 s26, s26, 0x80080
	v_lshl_add_u64 v[232:233], v[234:235], 0, s[34:35]
	s_addc_u32 s27, s27, 0
	s_add_i32 s28, s73, s56
	global_load_lds_dwordx4 v[232:233], off
	v_lshl_add_u64 v[232:233], s[26:27], 0, v[152:153]
	s_mov_b32 m0, s28
	s_nop 0
	global_load_lds_dwordx4 v[232:233], off
	v_lshl_add_u64 v[232:233], s[26:27], 0, v[174:175]
	s_add_i32 m0, s28, 0x2000
	s_nop 0
	global_load_lds_dwordx4 v[232:233], off
	v_lshl_add_u64 v[232:233], v[236:237], 0, s[34:35]
	s_mov_b32 m0, s64
	s_nop 0
	global_load_lds_dwordx4 v[232:233], off
	v_lshl_add_u64 v[232:233], v[238:239], 0, s[34:35]
	s_mov_b32 m0, s65
	s_nop 0
	global_load_lds_dwordx4 v[232:233], off
	s_waitcnt vmcnt(8)
	s_waitcnt lgkmcnt(0)
	s_barrier
	s_setprio 1
	s_waitcnt lgkmcnt(0)
	v_mfma_f32_16x16x32_bf16 v[60:63], v[128:131], v[188:191], v[60:63]
	v_mfma_f32_16x16x32_bf16 v[56:59], v[136:139], v[188:191], v[56:59]
	v_mfma_f32_16x16x32_bf16 v[44:47], v[128:131], v[208:211], v[44:47]
	v_mfma_f32_16x16x32_bf16 v[40:43], v[136:139], v[208:211], v[40:43]
	v_mfma_f32_16x16x32_bf16 v[28:31], v[128:131], v[216:219], v[28:31]
	v_mfma_f32_16x16x32_bf16 v[24:27], v[136:139], v[216:219], v[24:27]
	v_mfma_f32_16x16x32_bf16 v[12:15], v[128:131], v[224:227], v[12:15]
	v_mfma_f32_16x16x32_bf16 v[8:11], v[136:139], v[224:227], v[8:11]
	v_mfma_f32_16x16x32_bf16 v[60:63], v[132:135], v[204:207], v[60:63]
	v_mfma_f32_16x16x32_bf16 v[56:59], v[140:143], v[204:207], v[56:59]
	v_mfma_f32_16x16x32_bf16 v[44:47], v[132:135], v[212:215], v[44:47]
	v_mfma_f32_16x16x32_bf16 v[40:43], v[140:143], v[212:215], v[40:43]
	v_mfma_f32_16x16x32_bf16 v[28:31], v[132:135], v[220:223], v[28:31]
	v_mfma_f32_16x16x32_bf16 v[24:27], v[140:143], v[220:223], v[24:27]
	v_mfma_f32_16x16x32_bf16 v[12:15], v[132:135], v[228:231], v[12:15]
	v_mfma_f32_16x16x32_bf16 v[8:11], v[140:143], v[228:231], v[8:11]
	v_mfma_f32_16x16x32_bf16 v[52:55], v[144:147], v[188:191], v[52:55]
	v_mfma_f32_16x16x32_bf16 v[48:51], v[180:183], v[188:191], v[48:51]
	v_mfma_f32_16x16x32_bf16 v[36:39], v[144:147], v[208:211], v[36:39]
	v_mfma_f32_16x16x32_bf16 v[32:35], v[180:183], v[208:211], v[32:35]
	v_mfma_f32_16x16x32_bf16 v[20:23], v[144:147], v[216:219], v[20:23]
	v_mfma_f32_16x16x32_bf16 v[16:19], v[180:183], v[216:219], v[16:19]
	v_mfma_f32_16x16x32_bf16 v[4:7], v[144:147], v[224:227], v[4:7]
	v_mfma_f32_16x16x32_bf16 v[0:3], v[180:183], v[224:227], v[0:3]
	v_mfma_f32_16x16x32_bf16 v[52:55], v[148:151], v[204:207], v[52:55]
	v_mfma_f32_16x16x32_bf16 v[48:51], v[184:187], v[204:207], v[48:51]
	v_mfma_f32_16x16x32_bf16 v[36:39], v[148:151], v[212:215], v[36:39]
	v_mfma_f32_16x16x32_bf16 v[32:35], v[184:187], v[212:215], v[32:35]
	v_mfma_f32_16x16x32_bf16 v[20:23], v[148:151], v[220:223], v[20:23]
	v_mfma_f32_16x16x32_bf16 v[16:19], v[184:187], v[220:223], v[16:19]
	v_mfma_f32_16x16x32_bf16 v[4:7], v[148:151], v[228:231], v[4:7]
	v_mfma_f32_16x16x32_bf16 v[0:3], v[184:187], v[228:231], v[0:3]
	s_setprio 0
	s_barrier
	s_add_i32 s71, s71, 2
	s_add_u32 s24, s24, 0x100
	s_addc_u32 s25, s25, 0
	s_add_u32 s69, s69, 0x100
	s_addc_u32 s70, s70, 0
	s_cmp_gt_u32 s71, 29
	s_cbranch_scc0 .LBB0_550
	s_and_b64 vcc, exec, s[12:13]
	s_cbranch_vccz .LBB0_553
	s_barrier

; #define PG8_STAGE(bufoff, gbase, voff) do { _Pragma("unroll") for (int _i = 0; _i < 2; ++_i) \
;         __builtin_amdgcn_global_load_lds((const unsigned*)((const char*)(gbase) + (voff)[_i]), (LAS unsigned*)(lds + (bufoff) + ldsw + _i * 8192), 16, 0, 0); } while (0)
; #define PG8_LDA(dst, b, h) do { _Pragma("unroll") for (int m = 0; m < 4; ++m) _Pragma("unroll") for (int k = 0; k < 2; ++k) dst[m][k] = *(const LAS bf16x8*)(lds + PG8_SA(b, h) + aoff + m * 2048 + k * 1024); } while (0)
; #define PG8_LDB(dst, b, h) do { _Pragma("unroll") for (int n = 0; n < 2; ++n) _Pragma("unroll") for (int k = 0; k < 2; ++k) dst[n][k] = *(const LAS bf16x8*)(lds + PG8_SB(b, h) + boff + n * 2048 + k * 1024); } while (0)
; #define PG8_MMA(ai, bj, At, Bt) do { __builtin_amdgcn_s_setprio(1); _Pragma("unroll") for (int m = 0; m < 4; ++m) _Pragma("unroll") for (int n = 0; n < 2; ++n) _Pragma("unroll") for (int k = 0; k < 2; ++k) \
;         acc[ai][bj][m][n] = __builtin_amdgcn_mfma_f32_16x16x32_bf16(Bt[n][k], At[m][k], acc[ai][bj][m][n], 0, 0, 0); __builtin_amdgcn_s_setprio(0); } while (0)
; template <class Epi, class Sched>
; __device__ __forceinline__ void gemm_phase(const int tid, LAS unsigned char* lds, const Gemm g, const Sched& S, const Epi& E) {
;     ...
;         const bool has_next = S.next(ui + 1, nxt);
;         const char* nA = has_next ? (const char*)g.A + (size_t)nxt.pm * tstep : cA; const char* nB = has_next ? (const char*)g.Bt + (size_t)nxt.pn * tstep : cB;
;         for (int t = 0; t < nt; t += 2) {
;             const bool last = (t == nt - 2);
;             const char* a1 = cA + (size_t)(t + 1) * kstep;
;             const char* a2 = last ? nA : cA + (size_t)(t + 2) * kstep; const char* b2 = last ? nB : cB + (size_t)(t + 2) * kstep;
;             const char* a3 = a2 + kstep; const char* b3 = b2 + kstep;
;             if (last && has_next) S.a_ready(nxt);
;             PG8_LDB(B0, 0, 0); PG8_LDB(B1, 0, 1); PG8_SCHED; PG8_LDA(At, 0, 0); PG8_STAGE(PG8_SA(1, 1), a1 + hstep, voffA);
;             PG8_WAIT_V(8); PG8_WAIT_L(0); PG8_BAR; PG8_MMA(0, 0, At, B0); PG8_MMA(0, 1, At, B1); PG8_BAR; PG8_SCHED;
;             PG8_LDA(At, 0, 1); PG8_STAGE(PG8_SB(0, 0), b2, voffB); PG8_STAGE(PG8_SB(0, 1), b2 + hstep, voffB); PG8_STAGE(PG8_SA(0, 0), a2, voffA);
;             PG8_WAIT_V(8); PG8_WAIT_L(0); PG8_BAR; PG8_MMA(1, 0, At, B0); PG8_MMA(1, 1, At, B1); PG8_BAR; PG8_SCHED;
.LBB0_669:
	s_ashr_i32 s15, s14, 31
	s_lshl_b64 s[16:17], s[14:15], 20
	s_add_u32 s16, s56, s16
	s_addc_u32 s17, s57, s17
	s_and_b64 s[18:19], s[0:1], exec
	s_cselect_b32 s15, s17, s87
	s_cselect_b32 s68, s16, s86
	s_ashr_i32 s13, s12, 31
	s_lshl_b64 s[18:19], s[12:13], 20
	s_add_u32 s18, s41, s18
	s_addc_u32 s19, s55, s19
	s_and_b64 s[90:91], s[0:1], exec
	s_cselect_b32 s13, s19, s89
	s_cselect_b32 s69, s18, s88
	s_waitcnt vmcnt(8)
	s_waitcnt lgkmcnt(0)
	s_barrier
	s_setprio 1
	s_waitcnt lgkmcnt(0)
	v_mfma_f32_16x16x32_bf16 v[124:127], v[138:141], v[200:203], 0
	v_mfma_f32_16x16x32_bf16 v[116:119], v[146:149], v[200:203], 0
	v_mfma_f32_16x16x32_bf16 v[108:111], v[138:141], v[208:211], 0
	v_mfma_f32_16x16x32_bf16 v[100:103], v[146:149], v[208:211], 0
	v_mfma_f32_16x16x32_bf16 v[92:95], v[138:141], v[216:219], 0
	v_mfma_f32_16x16x32_bf16 v[84:87], v[146:149], v[216:219], 0
	v_mfma_f32_16x16x32_bf16 v[76:79], v[138:141], v[224:227], 0
	v_mfma_f32_16x16x32_bf16 v[68:71], v[146:149], v[224:227], 0
	v_mfma_f32_16x16x32_bf16 v[124:127], v[142:145], v[204:207], v[124:127]
	v_mfma_f32_16x16x32_bf16 v[116:119], v[172:175], v[204:207], v[116:119]
	v_mfma_f32_16x16x32_bf16 v[108:111], v[142:145], v[212:215], v[108:111]
	v_mfma_f32_16x16x32_bf16 v[100:103], v[172:175], v[212:215], v[100:103]
	v_mfma_f32_16x16x32_bf16 v[92:95], v[142:145], v[220:223], v[92:95]
	v_mfma_f32_16x16x32_bf16 v[84:87], v[172:175], v[220:223], v[84:87]
	v_mfma_f32_16x16x32_bf16 v[76:79], v[142:145], v[228:231], v[76:79]
	v_mfma_f32_16x16x32_bf16 v[68:71], v[172:175], v[228:231], v[68:71]
	v_mfma_f32_16x16x32_bf16 v[120:123], v[176:179], v[200:203], 0
	v_mfma_f32_16x16x32_bf16 v[112:115], v[184:187], v[200:203], 0
	v_mfma_f32_16x16x32_bf16 v[104:107], v[176:179], v[208:211], 0
	v_mfma_f32_16x16x32_bf16 v[96:99], v[184:187], v[208:211], 0
	v_mfma_f32_16x16x32_bf16 v[88:91], v[176:179], v[216:219], 0
	v_mfma_f32_16x16x32_bf16 v[80:83], v[184:187], v[216:219], 0
	v_mfma_f32_16x16x32_bf16 v[72:75], v[176:179], v[224:227], 0
	v_mfma_f32_16x16x32_bf16 v[64:67], v[184:187], v[224:227], 0
	v_mfma_f32_16x16x32_bf16 v[120:123], v[180:183], v[204:207], v[120:123]
	v_mfma_f32_16x16x32_bf16 v[112:115], v[188:191], v[204:207], v[112:115]
	v_mfma_f32_16x16x32_bf16 v[104:107], v[180:183], v[212:215], v[104:107]
	v_mfma_f32_16x16x32_bf16 v[96:99], v[188:191], v[212:215], v[96:99]
	v_mfma_f32_16x16x32_bf16 v[88:91], v[180:183], v[220:223], v[88:91]
	v_mfma_f32_16x16x32_bf16 v[80:83], v[188:191], v[220:223], v[80:83]
	v_mfma_f32_16x16x32_bf16 v[72:75], v[180:183], v[228:231], v[72:75]
	v_mfma_f32_16x16x32_bf16 v[64:67], v[188:191], v[228:231], v[64:67]
	s_setprio 0
	s_barrier
	s_add_i32 s73, s73, s40
	v_lshl_add_u64 v[232:233], s[24:25], 0, v[152:153]
	s_mov_b32 m0, s73
	ds_read_b128 v[200:203], v171 offset:16384
	ds_read_b128 v[204:207], v171 offset:17408
	ds_read_b128 v[208:211], v171 offset:18432
	ds_read_b128 v[212:215], v171 offset:19456
	ds_read_b128 v[216:219], v171 offset:20480
	ds_read_b128 v[220:223], v171 offset:21504
	ds_read_b128 v[224:227], v171 offset:22528
	ds_read_b128 v[228:231], v171 offset:23552
	global_load_lds_dwordx4 v[232:233], off
	s_add_i32 m0, s73, 0x2000
	s_add_u32 s74, s24, 0x80000
	v_lshl_add_u64 v[234:235], s[24:25], 0, v[128:129]
	s_addc_u32 s75, s25, 0
	s_add_i32 s73, s76, s40
	global_load_lds_dwordx4 v[234:235], off
	v_lshl_add_u64 v[236:237], s[74:75], 0, v[152:153]
	s_mov_b32 m0, s73
	v_lshl_add_u64 v[238:239], s[26:27], 0, v[130:131]
	global_load_lds_dwordx4 v[236:237], off
	v_lshl_add_u64 v[236:237], s[74:75], 0, v[128:129]
	s_add_i32 m0, s73, 0x2000
	s_nop 0
	global_load_lds_dwordx4 v[236:237], off
	v_lshl_add_u64 v[236:237], s[26:27], 0, v[132:133]
	s_mov_b32 m0, s58
	s_nop 0
	global_load_lds_dwordx4 v[236:237], off
	s_mov_b32 m0, s59
	s_nop 0
	global_load_lds_dwordx4 v[238:239], off
	s_waitcnt vmcnt(8)
	s_waitcnt lgkmcnt(0)
	s_barrier
	s_setprio 1
	s_waitcnt lgkmcnt(0)
	v_mfma_f32_16x16x32_bf16 v[60:63], v[138:141], v[200:203], 0
	v_mfma_f32_16x16x32_bf16 v[52:55], v[146:149], v[200:203], 0
	v_mfma_f32_16x16x32_bf16 v[44:47], v[138:141], v[208:211], 0
	v_mfma_f32_16x16x32_bf16 v[36:39], v[146:149], v[208:211], 0
	v_mfma_f32_16x16x32_bf16 v[28:31], v[138:141], v[216:219], 0
	v_mfma_f32_16x16x32_bf16 v[20:23], v[146:149], v[216:219], 0
	v_mfma_f32_16x16x32_bf16 v[12:15], v[138:141], v[224:227], 0
	v_mfma_f32_16x16x32_bf16 v[4:7], v[146:149], v[224:227], 0
	v_mfma_f32_16x16x32_bf16 v[60:63], v[142:145], v[204:207], v[60:63]
	v_mfma_f32_16x16x32_bf16 v[52:55], v[172:175], v[204:207], v[52:55]
	v_mfma_f32_16x16x32_bf16 v[44:47], v[142:145], v[212:215], v[44:47]
	v_mfma_f32_16x16x32_bf16 v[36:39], v[172:175], v[212:215], v[36:39]
	v_mfma_f32_16x16x32_bf16 v[28:31], v[142:145], v[220:223], v[28:31]
	v_mfma_f32_16x16x32_bf16 v[20:23], v[172:175], v[220:223], v[20:23]
	v_mfma_f32_16x16x32_bf16 v[12:15], v[142:145], v[228:231], v[12:15]
	v_mfma_f32_16x16x32_bf16 v[4:7], v[172:175], v[228:231], v[4:7]
	v_mfma_f32_16x16x32_bf16 v[56:59], v[176:179], v[200:203], 0
	v_mfma_f32_16x16x32_bf16 v[48:51], v[184:187], v[200:203], 0
	v_mfma_f32_16x16x32_bf16 v[40:43], v[176:179], v[208:211], 0
	v_mfma_f32_16x16x32_bf16 v[32:35], v[184:187], v[208:211], 0
	v_mfma_f32_16x16x32_bf16 v[24:27], v[176:179], v[216:219], 0
	v_mfma_f32_16x16x32_bf16 v[16:19], v[184:187], v[216:219], 0
	v_mfma_f32_16x16x32_bf16 v[8:11], v[176:179], v[224:227], 0
	v_mfma_f32_16x16x32_bf16 v[0:3], v[184:187], v[224:227], 0
	v_mfma_f32_16x16x32_bf16 v[56:59], v[180:183], v[204:207], v[56:59]
	v_mfma_f32_16x16x32_bf16 v[48:51], v[188:191], v[204:207], v[48:51]
	v_mfma_f32_16x16x32_bf16 v[40:43], v[180:183], v[212:215], v[40:43]
	v_mfma_f32_16x16x32_bf16 v[32:35], v[188:191], v[212:215], v[32:35]
	v_mfma_f32_16x16x32_bf16 v[24:27], v[180:183], v[220:223], v[24:27]
	v_mfma_f32_16x16x32_bf16 v[16:19], v[188:191], v[220:223], v[16:19]
	v_mfma_f32_16x16x32_bf16 v[8:11], v[180:183], v[228:231], v[8:11]
	v_mfma_f32_16x16x32_bf16 v[0:3], v[188:191], v[228:231], v[0:3]
	s_setprio 0
	s_barrier
; #define PG8_STAGE(bufoff, gbase, voff) do { _Pragma("unroll") for (int _i = 0; _i < 2; ++_i) \
;         __builtin_amdgcn_global_load_lds((const unsigned*)((const char*)(gbase) + (voff)[_i]), (LAS unsigned*)(lds + (bufoff) + ldsw + _i * 8192), 16, 0, 0); } while (0)
; #define PG8_LDA(dst, b, h) do { _Pragma("unroll") for (int m = 0; m < 4; ++m) _Pragma("unroll") for (int k = 0; k < 2; ++k) dst[m][k] = *(const LAS bf16x8*)(lds + PG8_SA(b, h) + aoff + m * 2048 + k * 1024); } while (0)
; #define PG8_LDB(dst, b, h) do { _Pragma("unroll") for (int n = 0; n < 2; ++n) _Pragma("unroll") for (int k = 0; k < 2; ++k) dst[n][k] = *(const LAS bf16x8*)(lds + PG8_SB(b, h) + boff + n * 2048 + k * 1024); } while (0)
; #define PG8_MMA(ai, bj, At, Bt) do { __builtin_amdgcn_s_setprio(1); _Pragma("unroll") for (int m = 0; m < 4; ++m) _Pragma("unroll") for (int n = 0; n < 2; ++n) _Pragma("unroll") for (int k = 0; k < 2; ++k) \
;         acc[ai][bj][m][n] = __builtin_amdgcn_mfma_f32_16x16x32_bf16(Bt[n][k], At[m][k], acc[ai][bj][m][n], 0, 0, 0); __builtin_amdgcn_s_setprio(0); } while (0)
; #define PG8_WAIT_V(n) asm volatile("s_waitcnt vmcnt(" #n ")" ::: "memory")
; #define PG8_WAIT_L(n) asm volatile("s_waitcnt lgkmcnt(" #n ")" ::: "memory")
; #define PG8_BAR __builtin_amdgcn_s_barrier()
; #define PG8_SCHED __builtin_amdgcn_sched_barrier(0)
; template <class Epi, class Sched>
; __device__ __forceinline__ void gemm_phase(const int tid, LAS unsigned char* lds, const Gemm g, const Sched& S, const Epi& E) {
;     ...
;             PG8_LDB(B0, 1, 0); PG8_LDB(B1, 1, 1); PG8_SCHED; PG8_LDA(At, 1, 0); PG8_STAGE(PG8_SA(0, 1), a2 + hstep, voffA);
;             PG8_WAIT_V(8); PG8_WAIT_L(0); PG8_BAR; PG8_MMA(0, 0, At, B0); PG8_MMA(0, 1, At, B1); PG8_BAR; PG8_SCHED;
;             PG8_LDA(At, 1, 1); PG8_STAGE(PG8_SB(1, 0), b3, voffB); PG8_STAGE(PG8_SB(1, 1), b3 + hstep, voffB); PG8_STAGE(PG8_SA(1, 0), a3, voffA);
	s_add_i32 s73, 0, 0x18000
	s_add_i32 s74, 0, 0x1c000
	v_add_u32_e32 v172, s73, v170
	v_add_u32_e32 v188, s74, v170
	ds_read_b128 v[138:141], v172
	ds_read_b128 v[142:145], v172 offset:1024
	ds_read_b128 v[146:149], v172 offset:2048
	ds_read_b128 v[172:175], v172 offset:3072
	ds_read_b128 v[176:179], v188
	ds_read_b128 v[180:183], v188 offset:1024
	ds_read_b128 v[184:187], v188 offset:2048
	ds_read_b128 v[188:191], v188 offset:3072
	s_add_u32 s26, s26, 0x80000
	s_addc_u32 s27, s27, 0
	s_mov_b32 m0, s60
	v_lshl_add_u64 v[240:241], s[26:27], 0, v[132:133]
	ds_read_b128 v[200:203], v171 offset:32768
	ds_read_b128 v[204:207], v171 offset:33792
	ds_read_b128 v[208:211], v171 offset:34816
	ds_read_b128 v[212:215], v171 offset:35840
	ds_read_b128 v[216:219], v171 offset:36864
	ds_read_b128 v[220:223], v171 offset:37888
	ds_read_b128 v[224:227], v171 offset:38912
	ds_read_b128 v[228:231], v171 offset:39936
	global_load_lds_dwordx4 v[240:241], off
	v_lshl_add_u64 v[240:241], s[26:27], 0, v[130:131]
	s_mov_b32 m0, s61
	s_nop 0
	global_load_lds_dwordx4 v[240:241], off
	s_waitcnt vmcnt(8)
	s_waitcnt lgkmcnt(0)
	s_barrier
	s_setprio 1
	s_waitcnt lgkmcnt(0)
	v_mfma_f32_16x16x32_bf16 v[124:127], v[138:141], v[200:203], v[124:127]
	v_mfma_f32_16x16x32_bf16 v[116:119], v[146:149], v[200:203], v[116:119]
	v_mfma_f32_16x16x32_bf16 v[108:111], v[138:141], v[208:211], v[108:111]
	v_mfma_f32_16x16x32_bf16 v[100:103], v[146:149], v[208:211], v[100:103]
	v_mfma_f32_16x16x32_bf16 v[92:95], v[138:141], v[216:219], v[92:95]
	v_mfma_f32_16x16x32_bf16 v[84:87], v[146:149], v[216:219], v[84:87]
	v_mfma_f32_16x16x32_bf16 v[76:79], v[138:141], v[224:227], v[76:79]
	v_mfma_f32_16x16x32_bf16 v[68:71], v[146:149], v[224:227], v[68:71]
	v_mfma_f32_16x16x32_bf16 v[124:127], v[142:145], v[204:207], v[124:127]
	v_mfma_f32_16x16x32_bf16 v[116:119], v[172:175], v[204:207], v[116:119]
	v_mfma_f32_16x16x32_bf16 v[108:111], v[142:145], v[212:215], v[108:111]
	v_mfma_f32_16x16x32_bf16 v[100:103], v[172:175], v[212:215], v[100:103]
	v_mfma_f32_16x16x32_bf16 v[92:95], v[142:145], v[220:223], v[92:95]
	v_mfma_f32_16x16x32_bf16 v[84:87], v[172:175], v[220:223], v[84:87]
	v_mfma_f32_16x16x32_bf16 v[76:79], v[142:145], v[228:231], v[76:79]
	v_mfma_f32_16x16x32_bf16 v[68:71], v[172:175], v[228:231], v[68:71]
	v_mfma_f32_16x16x32_bf16 v[120:123], v[176:179], v[200:203], v[120:123]
	v_mfma_f32_16x16x32_bf16 v[112:115], v[184:187], v[200:203], v[112:115]
	v_mfma_f32_16x16x32_bf16 v[104:107], v[176:179], v[208:211], v[104:107]
	v_mfma_f32_16x16x32_bf16 v[96:99], v[184:187], v[208:211], v[96:99]
	v_mfma_f32_16x16x32_bf16 v[88:91], v[176:179], v[216:219], v[88:91]
	v_mfma_f32_16x16x32_bf16 v[80:83], v[184:187], v[216:219], v[80:83]
	v_mfma_f32_16x16x32_bf16 v[72:75], v[176:179], v[224:227], v[72:75]
	v_mfma_f32_16x16x32_bf16 v[64:67], v[184:187], v[224:227], v[64:67]
	v_mfma_f32_16x16x32_bf16 v[120:123], v[180:183], v[204:207], v[120:123]
	v_mfma_f32_16x16x32_bf16 v[112:115], v[188:191], v[204:207], v[112:115]
	v_mfma_f32_16x16x32_bf16 v[104:107], v[180:183], v[212:215], v[104:107]
	v_mfma_f32_16x16x32_bf16 v[96:99], v[188:191], v[212:215], v[96:99]
	v_mfma_f32_16x16x32_bf16 v[88:91], v[180:183], v[220:223], v[88:91]
	v_mfma_f32_16x16x32_bf16 v[80:83], v[188:191], v[220:223], v[80:83]
	v_mfma_f32_16x16x32_bf16 v[72:75], v[180:183], v[228:231], v[72:75]
	v_mfma_f32_16x16x32_bf16 v[64:67], v[188:191], v[228:231], v[64:67]
	s_setprio 0
	s_barrier
	s_add_i32 s26, s73, s40
	v_lshl_add_u64 v[232:233], v[232:233], 0, s[34:35]
	s_mov_b32 m0, s26
	ds_read_b128 v[200:203], v171 offset:49152
	ds_read_b128 v[204:207], v171 offset:50176
	ds_read_b128 v[208:211], v171 offset:51200
	ds_read_b128 v[212:215], v171 offset:52224
	ds_read_b128 v[216:219], v171 offset:53248
	ds_read_b128 v[220:223], v171 offset:54272
	ds_read_b128 v[224:227], v171 offset:55296
	ds_read_b128 v[228:231], v171 offset:56320
	global_load_lds_dwordx4 v[232:233], off
	s_add_i32 m0, s26, 0x2000
	s_add_u32 s24, s24, 0x80080
	v_lshl_add_u64 v[232:233], v[234:235], 0, s[34:35]
	s_addc_u32 s25, s25, 0
	s_add_i32 s26, s74, s40
	global_load_lds_dwordx4 v[232:233], off
	v_lshl_add_u64 v[232:233], s[24:25], 0, v[152:153]
	s_mov_b32 m0, s26
	s_nop 0
	global_load_lds_dwordx4 v[232:233], off
	v_lshl_add_u64 v[232:233], s[24:25], 0, v[128:129]
	s_add_i32 m0, s26, 0x2000
	s_nop 0
	global_load_lds_dwordx4 v[232:233], off
	v_lshl_add_u64 v[232:233], v[236:237], 0, s[34:35]
	s_mov_b32 m0, s64
	s_nop 0
	global_load_lds_dwordx4 v[232:233], off
	v_lshl_add_u64 v[232:233], v[238:239], 0, s[34:35]
	s_mov_b32 m0, s65
	s_nop 0
	global_load_lds_dwordx4 v[232:233], off
	s_waitcnt vmcnt(8)
	s_waitcnt lgkmcnt(0)
	s_barrier
; #define PG8_STAGE(bufoff, gbase, voff) do { _Pragma("unroll") for (int _i = 0; _i < 2; ++_i) \
;         __builtin_amdgcn_global_load_lds((const unsigned*)((const char*)(gbase) + (voff)[_i]), (LAS unsigned*)(lds + (bufoff) + ldsw + _i * 8192), 16, 0, 0); } while (0)
; #define PG8_LDA(dst, b, h) do { _Pragma("unroll") for (int m = 0; m < 4; ++m) _Pragma("unroll") for (int k = 0; k < 2; ++k) dst[m][k] = *(const LAS bf16x8*)(lds + PG8_SA(b, h) + aoff + m * 2048 + k * 1024); } while (0)
; #define PG8_LDB(dst, b, h) do { _Pragma("unroll") for (int n = 0; n < 2; ++n) _Pragma("unroll") for (int k = 0; k < 2; ++k) dst[n][k] = *(const LAS bf16x8*)(lds + PG8_SB(b, h) + boff + n * 2048 + k * 1024); } while (0)
; #define PG8_WAIT_V(n) asm volatile("s_waitcnt vmcnt(" #n ")" ::: "memory")
; template <class Epi, class Sched>
; __device__ __forceinline__ void gemm_phase(const int tid, LAS unsigned char* lds, const Gemm g, const Sched& S, const Epi& E) {
;     ...
;         for (int t = 0; t < nt; t += 2) {
;             const bool last = (t == nt - 2);
;             const char* a1 = cA + (size_t)(t + 1) * kstep;
;             const char* a2 = last ? nA : cA + (size_t)(t + 2) * kstep; const char* b2 = last ? nB : cB + (size_t)(t + 2) * kstep;
;             const char* a3 = a2 + kstep; const char* b3 = b2 + kstep;
;             if (last && has_next) S.a_ready(nxt);
;             PG8_LDB(B0, 0, 0); PG8_LDB(B1, 0, 1); PG8_SCHED; PG8_LDA(At, 0, 0); PG8_STAGE(PG8_SA(1, 1), a1 + hstep, voffA);
;             PG8_WAIT_V(8); PG8_WAIT_L(0); PG8_BAR; PG8_MMA(0, 0, At, B0); PG8_MMA(0, 1, At, B1); PG8_BAR; PG8_SCHED;
;             PG8_LDA(At, 0, 1); PG8_STAGE(PG8_SB(0, 0), b2, voffB); PG8_STAGE(PG8_SB(0, 1), b2 + hstep, voffB); PG8_STAGE(PG8_SA(0, 0), a2, voffA);
;             PG8_WAIT_V(8); PG8_WAIT_L(0); PG8_BAR; PG8_MMA(1, 0, At, B0); PG8_MMA(1, 1, At, B1); PG8_BAR; PG8_SCHED;
;             PG8_LDB(B0, 1, 0); PG8_LDB(B1, 1, 1); PG8_SCHED; PG8_LDA(At, 1, 0); PG8_STAGE(PG8_SA(0, 1), a2 + hstep, voffA);
;             PG8_WAIT_V(8); PG8_WAIT_L(0); PG8_BAR; PG8_MMA(0, 0, At, B0); PG8_MMA(0, 1, At, B1); PG8_BAR; PG8_SCHED;
;             PG8_LDA(At, 1, 1); PG8_STAGE(PG8_SB(1, 0), b3, voffB); PG8_STAGE(PG8_SB(1, 1), b3 + hstep, voffB); PG8_STAGE(PG8_SA(1, 0), a3, voffA);
;             PG8_WAIT_V(8); PG8_WAIT_L(0); PG8_BAR; PG8_MMA(1, 0, At, B0); PG8_MMA(1, 1, At, B1); PG8_BAR; PG8_SCHED;
	s_setprio 1
	s_waitcnt lgkmcnt(0)
	v_mfma_f32_16x16x32_bf16 v[60:63], v[138:141], v[200:203], v[60:63]
	v_mfma_f32_16x16x32_bf16 v[52:55], v[146:149], v[200:203], v[52:55]
	v_mfma_f32_16x16x32_bf16 v[44:47], v[138:141], v[208:211], v[44:47]
	v_mfma_f32_16x16x32_bf16 v[36:39], v[146:149], v[208:211], v[36:39]
	v_mfma_f32_16x16x32_bf16 v[28:31], v[138:141], v[216:219], v[28:31]
	v_mfma_f32_16x16x32_bf16 v[20:23], v[146:149], v[216:219], v[20:23]
	v_mfma_f32_16x16x32_bf16 v[12:15], v[138:141], v[224:227], v[12:15]
	v_mfma_f32_16x16x32_bf16 v[4:7], v[146:149], v[224:227], v[4:7]
	v_mfma_f32_16x16x32_bf16 v[60:63], v[142:145], v[204:207], v[60:63]
	v_mfma_f32_16x16x32_bf16 v[52:55], v[172:175], v[204:207], v[52:55]
	v_mfma_f32_16x16x32_bf16 v[44:47], v[142:145], v[212:215], v[44:47]
	v_mfma_f32_16x16x32_bf16 v[36:39], v[172:175], v[212:215], v[36:39]
	v_mfma_f32_16x16x32_bf16 v[28:31], v[142:145], v[220:223], v[28:31]
	v_mfma_f32_16x16x32_bf16 v[20:23], v[172:175], v[220:223], v[20:23]
	v_mfma_f32_16x16x32_bf16 v[12:15], v[142:145], v[228:231], v[12:15]
	v_mfma_f32_16x16x32_bf16 v[4:7], v[172:175], v[228:231], v[4:7]
	v_mfma_f32_16x16x32_bf16 v[56:59], v[176:179], v[200:203], v[56:59]
	v_mfma_f32_16x16x32_bf16 v[48:51], v[184:187], v[200:203], v[48:51]
	v_mfma_f32_16x16x32_bf16 v[40:43], v[176:179], v[208:211], v[40:43]
	v_mfma_f32_16x16x32_bf16 v[32:35], v[184:187], v[208:211], v[32:35]
	v_mfma_f32_16x16x32_bf16 v[24:27], v[176:179], v[216:219], v[24:27]
	v_mfma_f32_16x16x32_bf16 v[16:19], v[184:187], v[216:219], v[16:19]
	v_mfma_f32_16x16x32_bf16 v[8:11], v[176:179], v[224:227], v[8:11]
	v_mfma_f32_16x16x32_bf16 v[0:3], v[184:187], v[224:227], v[0:3]
	v_mfma_f32_16x16x32_bf16 v[56:59], v[180:183], v[204:207], v[56:59]
	v_mfma_f32_16x16x32_bf16 v[48:51], v[188:191], v[204:207], v[48:51]
	v_mfma_f32_16x16x32_bf16 v[40:43], v[180:183], v[212:215], v[40:43]
	v_mfma_f32_16x16x32_bf16 v[32:35], v[188:191], v[212:215], v[32:35]
	v_mfma_f32_16x16x32_bf16 v[24:27], v[180:183], v[220:223], v[24:27]
	v_mfma_f32_16x16x32_bf16 v[16:19], v[188:191], v[220:223], v[16:19]
	v_mfma_f32_16x16x32_bf16 v[8:11], v[180:183], v[228:231], v[8:11]
	v_mfma_f32_16x16x32_bf16 v[0:3], v[188:191], v[228:231], v[0:3]
	s_setprio 0
	s_barrier
	s_add_i32 s72, s72, 2
	s_add_u32 s22, s22, 0x100
	s_addc_u32 s23, s23, 0
	s_add_u32 s70, s70, 0x100
	s_addc_u32 s71, s71, 0
	s_cmp_gt_u32 s72, 29
.LBB0_670:
	s_add_u32 s24, s22, 0xfff80080
	s_addc_u32 s25, s23, -1
	s_add_i32 s73, 0, 0x10000
	s_cmp_eq_u32 s72, 28
	s_cselect_b32 s27, s15, s25
	s_cselect_b32 s26, s68, s24
	s_cselect_b32 s25, s13, s71
	s_cselect_b32 s24, s69, s70
	s_add_i32 s76, 0, 0x14000
	v_add_u32_e32 v172, s73, v170
	v_add_u32_e32 v188, s76, v170
	ds_read_b128 v[138:141], v172
	ds_read_b128 v[142:145], v172 offset:1024
	ds_read_b128 v[146:149], v172 offset:2048
	ds_read_b128 v[172:175], v172 offset:3072
	ds_read_b128 v[176:179], v188
	ds_read_b128 v[180:183], v188 offset:1024
	ds_read_b128 v[184:187], v188 offset:2048
	ds_read_b128 v[188:191], v188 offset:3072
	v_lshl_add_u64 v[232:233], s[22:23], 0, v[134:135]
	s_add_i32 m0, s58, 0xc000
	ds_read_b128 v[200:203], v171
	ds_read_b128 v[204:207], v171 offset:1024
	ds_read_b128 v[208:211], v171 offset:2048
	ds_read_b128 v[212:215], v171 offset:3072
	ds_read_b128 v[216:219], v171 offset:4096
	ds_read_b128 v[220:223], v171 offset:5120
	ds_read_b128 v[224:227], v171 offset:6144
	ds_read_b128 v[228:231], v171 offset:7168
	global_load_lds_dwordx4 v[232:233], off
	v_lshl_add_u64 v[232:233], s[22:23], 0, v[136:137]
	s_add_i32 m0, s58, 0xe000
	s_nop 0
	global_load_lds_dwordx4 v[232:233], off
	s_waitcnt vmcnt(8)
	s_waitcnt lgkmcnt(0)
	s_barrier
	s_setprio 1
	s_waitcnt lgkmcnt(0)
	v_mfma_f32_16x16x32_bf16 v[124:127], v[138:141], v[200:203], v[124:127]
	v_mfma_f32_16x16x32_bf16 v[116:119], v[146:149], v[200:203], v[116:119]
	v_mfma_f32_16x16x32_bf16 v[108:111], v[138:141], v[208:211], v[108:111]
	v_mfma_f32_16x16x32_bf16 v[100:103], v[146:149], v[208:211], v[100:103]
	v_mfma_f32_16x16x32_bf16 v[92:95], v[138:141], v[216:219], v[92:95]
	v_mfma_f32_16x16x32_bf16 v[84:87], v[146:149], v[216:219], v[84:87]
	v_mfma_f32_16x16x32_bf16 v[76:79], v[138:141], v[224:227], v[76:79]
	v_mfma_f32_16x16x32_bf16 v[68:71], v[146:149], v[224:227], v[68:71]
	v_mfma_f32_16x16x32_bf16 v[124:127], v[142:145], v[204:207], v[124:127]
	v_mfma_f32_16x16x32_bf16 v[116:119], v[172:175], v[204:207], v[116:119]
	v_mfma_f32_16x16x32_bf16 v[108:111], v[142:145], v[212:215], v[108:111]
	v_mfma_f32_16x16x32_bf16 v[100:103], v[172:175], v[212:215], v[100:103]
	v_mfma_f32_16x16x32_bf16 v[92:95], v[142:145], v[220:223], v[92:95]
	v_mfma_f32_16x16x32_bf16 v[84:87], v[172:175], v[220:223], v[84:87]
	v_mfma_f32_16x16x32_bf16 v[76:79], v[142:145], v[228:231], v[76:79]
	v_mfma_f32_16x16x32_bf16 v[68:71], v[172:175], v[228:231], v[68:71]
	v_mfma_f32_16x16x32_bf16 v[120:123], v[176:179], v[200:203], v[120:123]
	v_mfma_f32_16x16x32_bf16 v[112:115], v[184:187], v[200:203], v[112:115]
	v_mfma_f32_16x16x32_bf16 v[104:107], v[176:179], v[208:211], v[104:107]
	v_mfma_f32_16x16x32_bf16 v[96:99], v[184:187], v[208:211], v[96:99]
	v_mfma_f32_16x16x32_bf16 v[88:91], v[176:179], v[216:219], v[88:91]
	v_mfma_f32_16x16x32_bf16 v[80:83], v[184:187], v[216:219], v[80:83]
	v_mfma_f32_16x16x32_bf16 v[72:75], v[176:179], v[224:227], v[72:75]
	v_mfma_f32_16x16x32_bf16 v[64:67], v[184:187], v[224:227], v[64:67]
	v_mfma_f32_16x16x32_bf16 v[120:123], v[180:183], v[204:207], v[120:123]
	v_mfma_f32_16x16x32_bf16 v[112:115], v[188:191], v[204:207], v[112:115]
	v_mfma_f32_16x16x32_bf16 v[104:107], v[180:183], v[212:215], v[104:107]
	v_mfma_f32_16x16x32_bf16 v[96:99], v[188:191], v[212:215], v[96:99]
	v_mfma_f32_16x16x32_bf16 v[88:91], v[180:183], v[220:223], v[88:91]
	v_mfma_f32_16x16x32_bf16 v[80:83], v[188:191], v[220:223], v[80:83]
	v_mfma_f32_16x16x32_bf16 v[72:75], v[180:183], v[228:231], v[72:75]
	v_mfma_f32_16x16x32_bf16 v[64:67], v[188:191], v[228:231], v[64:67]
	s_setprio 0
	s_barrier
; #define PG8_STAGE(bufoff, gbase, voff) do { _Pragma("unroll") for (int _i = 0; _i < 2; ++_i) \
;         __builtin_amdgcn_global_load_lds((const unsigned*)((const char*)(gbase) + (voff)[_i]), (LAS unsigned*)(lds + (bufoff) + ldsw + _i * 8192), 16, 0, 0); } while (0)
; #define PG8_LDA(dst, b, h) do { _Pragma("unroll") for (int m = 0; m < 4; ++m) _Pragma("unroll") for (int k = 0; k < 2; ++k) dst[m][k] = *(const LAS bf16x8*)(lds + PG8_SA(b, h) + aoff + m * 2048 + k * 1024); } while (0)
; #define PG8_LDB(dst, b, h) do { _Pragma("unroll") for (int n = 0; n < 2; ++n) _Pragma("unroll") for (int k = 0; k < 2; ++k) dst[n][k] = *(const LAS bf16x8*)(lds + PG8_SB(b, h) + boff + n * 2048 + k * 1024); } while (0)
; #define PG8_MMA(ai, bj, At, Bt) do { __builtin_amdgcn_s_setprio(1); _Pragma("unroll") for (int m = 0; m < 4; ++m) _Pragma("unroll") for (int n = 0; n < 2; ++n) _Pragma("unroll") for (int k = 0; k < 2; ++k) \
;         acc[ai][bj][m][n] = __builtin_amdgcn_mfma_f32_16x16x32_bf16(Bt[n][k], At[m][k], acc[ai][bj][m][n], 0, 0, 0); __builtin_amdgcn_s_setprio(0); } while (0)
; #define PG8_WAIT_V(n) asm volatile("s_waitcnt vmcnt(" #n ")" ::: "memory")
; #define PG8_WAIT_L(n) asm volatile("s_waitcnt lgkmcnt(" #n ")" ::: "memory")
; #define PG8_BAR __builtin_amdgcn_s_barrier()
; #define PG8_SCHED __builtin_amdgcn_sched_barrier(0)
; template <class Epi, class Sched>
; __device__ __forceinline__ void gemm_phase(const int tid, LAS unsigned char* lds, const Gemm g, const Sched& S, const Epi& E) {
;     ...
;             PG8_LDA(At, 0, 1); PG8_STAGE(PG8_SB(0, 0), b2, voffB); PG8_STAGE(PG8_SB(0, 1), b2 + hstep, voffB); PG8_STAGE(PG8_SA(0, 0), a2, voffA);
;             PG8_WAIT_V(8); PG8_WAIT_L(0); PG8_BAR; PG8_MMA(1, 0, At, B0); PG8_MMA(1, 1, At, B1); PG8_BAR; PG8_SCHED;
;             PG8_LDB(B0, 1, 0); PG8_LDB(B1, 1, 1); PG8_SCHED; PG8_LDA(At, 1, 0); PG8_STAGE(PG8_SA(0, 1), a2 + hstep, voffA);
;             PG8_WAIT_V(8); PG8_WAIT_L(0); PG8_BAR; PG8_MMA(0, 0, At, B0); PG8_MMA(0, 1, At, B1); PG8_BAR; PG8_SCHED;
	s_add_i32 s73, s73, s40
	v_lshl_add_u64 v[232:233], s[24:25], 0, v[152:153]
	s_mov_b32 m0, s73
	ds_read_b128 v[200:203], v171 offset:16384
	ds_read_b128 v[204:207], v171 offset:17408
	ds_read_b128 v[208:211], v171 offset:18432
	ds_read_b128 v[212:215], v171 offset:19456
	ds_read_b128 v[216:219], v171 offset:20480
	ds_read_b128 v[220:223], v171 offset:21504
	ds_read_b128 v[224:227], v171 offset:22528
	ds_read_b128 v[228:231], v171 offset:23552
	global_load_lds_dwordx4 v[232:233], off
	s_add_i32 m0, s73, 0x2000
	s_add_u32 s74, s24, 0x80000
	v_lshl_add_u64 v[234:235], s[24:25], 0, v[128:129]
	s_addc_u32 s75, s25, 0
	s_add_i32 s73, s76, s40
	global_load_lds_dwordx4 v[234:235], off
	v_lshl_add_u64 v[236:237], s[74:75], 0, v[152:153]
	s_mov_b32 m0, s73
	v_lshl_add_u64 v[238:239], s[26:27], 0, v[130:131]
	global_load_lds_dwordx4 v[236:237], off
	v_lshl_add_u64 v[236:237], s[74:75], 0, v[128:129]
	s_add_i32 m0, s73, 0x2000
	s_nop 0
	global_load_lds_dwordx4 v[236:237], off
	v_lshl_add_u64 v[236:237], s[26:27], 0, v[132:133]
	s_mov_b32 m0, s58
	s_nop 0
	global_load_lds_dwordx4 v[236:237], off
	s_mov_b32 m0, s59
	s_nop 0
	global_load_lds_dwordx4 v[238:239], off
	s_waitcnt vmcnt(8)
	s_waitcnt lgkmcnt(0)
	s_barrier
	s_setprio 1
	s_waitcnt lgkmcnt(0)
	v_mfma_f32_16x16x32_bf16 v[60:63], v[138:141], v[200:203], v[60:63]
	v_mfma_f32_16x16x32_bf16 v[52:55], v[146:149], v[200:203], v[52:55]
	v_mfma_f32_16x16x32_bf16 v[44:47], v[138:141], v[208:211], v[44:47]
	v_mfma_f32_16x16x32_bf16 v[36:39], v[146:149], v[208:211], v[36:39]
	v_mfma_f32_16x16x32_bf16 v[28:31], v[138:141], v[216:219], v[28:31]
	v_mfma_f32_16x16x32_bf16 v[20:23], v[146:149], v[216:219], v[20:23]
	v_mfma_f32_16x16x32_bf16 v[12:15], v[138:141], v[224:227], v[12:15]
	v_mfma_f32_16x16x32_bf16 v[4:7], v[146:149], v[224:227], v[4:7]
	v_mfma_f32_16x16x32_bf16 v[60:63], v[142:145], v[204:207], v[60:63]
	v_mfma_f32_16x16x32_bf16 v[52:55], v[172:175], v[204:207], v[52:55]
	v_mfma_f32_16x16x32_bf16 v[44:47], v[142:145], v[212:215], v[44:47]
	v_mfma_f32_16x16x32_bf16 v[36:39], v[172:175], v[212:215], v[36:39]
	v_mfma_f32_16x16x32_bf16 v[28:31], v[142:145], v[220:223], v[28:31]
	v_mfma_f32_16x16x32_bf16 v[20:23], v[172:175], v[220:223], v[20:23]
	v_mfma_f32_16x16x32_bf16 v[12:15], v[142:145], v[228:231], v[12:15]
	v_mfma_f32_16x16x32_bf16 v[4:7], v[172:175], v[228:231], v[4:7]
	v_mfma_f32_16x16x32_bf16 v[56:59], v[176:179], v[200:203], v[56:59]
	v_mfma_f32_16x16x32_bf16 v[48:51], v[184:187], v[200:203], v[48:51]
	v_mfma_f32_16x16x32_bf16 v[40:43], v[176:179], v[208:211], v[40:43]
	v_mfma_f32_16x16x32_bf16 v[32:35], v[184:187], v[208:211], v[32:35]
	v_mfma_f32_16x16x32_bf16 v[24:27], v[176:179], v[216:219], v[24:27]
	v_mfma_f32_16x16x32_bf16 v[16:19], v[184:187], v[216:219], v[16:19]
	v_mfma_f32_16x16x32_bf16 v[8:11], v[176:179], v[224:227], v[8:11]
	v_mfma_f32_16x16x32_bf16 v[0:3], v[184:187], v[224:227], v[0:3]
	v_mfma_f32_16x16x32_bf16 v[56:59], v[180:183], v[204:207], v[56:59]
	v_mfma_f32_16x16x32_bf16 v[48:51], v[188:191], v[204:207], v[48:51]
	v_mfma_f32_16x16x32_bf16 v[40:43], v[180:183], v[212:215], v[40:43]
	v_mfma_f32_16x16x32_bf16 v[32:35], v[188:191], v[212:215], v[32:35]
	v_mfma_f32_16x16x32_bf16 v[24:27], v[180:183], v[220:223], v[24:27]
	v_mfma_f32_16x16x32_bf16 v[16:19], v[188:191], v[220:223], v[16:19]
	v_mfma_f32_16x16x32_bf16 v[8:11], v[180:183], v[228:231], v[8:11]
	v_mfma_f32_16x16x32_bf16 v[0:3], v[188:191], v[228:231], v[0:3]
	s_setprio 0
	s_barrier
	s_add_i32 s73, 0, 0x18000
	s_add_i32 s74, 0, 0x1c000
	v_add_u32_e32 v172, s73, v170
	v_add_u32_e32 v188, s74, v170
	ds_read_b128 v[138:141], v172
	ds_read_b128 v[142:145], v172 offset:1024
	ds_read_b128 v[146:149], v172 offset:2048
	ds_read_b128 v[172:175], v172 offset:3072
	ds_read_b128 v[176:179], v188
	ds_read_b128 v[180:183], v188 offset:1024
	ds_read_b128 v[184:187], v188 offset:2048
	ds_read_b128 v[188:191], v188 offset:3072
	s_add_u32 s26, s26, 0x80000
	s_addc_u32 s27, s27, 0
	s_mov_b32 m0, s60
	v_lshl_add_u64 v[240:241], s[26:27], 0, v[132:133]
	ds_read_b128 v[200:203], v171 offset:32768
	ds_read_b128 v[204:207], v171 offset:33792
	ds_read_b128 v[208:211], v171 offset:34816
	ds_read_b128 v[212:215], v171 offset:35840
	ds_read_b128 v[216:219], v171 offset:36864
	ds_read_b128 v[220:223], v171 offset:37888
	ds_read_b128 v[224:227], v171 offset:38912
	ds_read_b128 v[228:231], v171 offset:39936
	global_load_lds_dwordx4 v[240:241], off
	v_lshl_add_u64 v[240:241], s[26:27], 0, v[130:131]
	s_mov_b32 m0, s61
	s_nop 0
	global_load_lds_dwordx4 v[240:241], off
	s_waitcnt vmcnt(8)
	s_waitcnt lgkmcnt(0)
	s_barrier
; #define PG8_STAGE(bufoff, gbase, voff) do { _Pragma("unroll") for (int _i = 0; _i < 2; ++_i) \
;         __builtin_amdgcn_global_load_lds((const unsigned*)((const char*)(gbase) + (voff)[_i]), (LAS unsigned*)(lds + (bufoff) + ldsw + _i * 8192), 16, 0, 0); } while (0)
; #define PG8_LDA(dst, b, h) do { _Pragma("unroll") for (int m = 0; m < 4; ++m) _Pragma("unroll") for (int k = 0; k < 2; ++k) dst[m][k] = *(const LAS bf16x8*)(lds + PG8_SA(b, h) + aoff + m * 2048 + k * 1024); } while (0)
; #define PG8_MMA(ai, bj, At, Bt) do { __builtin_amdgcn_s_setprio(1); _Pragma("unroll") for (int m = 0; m < 4; ++m) _Pragma("unroll") for (int n = 0; n < 2; ++n) _Pragma("unroll") for (int k = 0; k < 2; ++k) \
;         acc[ai][bj][m][n] = __builtin_amdgcn_mfma_f32_16x16x32_bf16(Bt[n][k], At[m][k], acc[ai][bj][m][n], 0, 0, 0); __builtin_amdgcn_s_setprio(0); } while (0)
; #define PG8_WAIT_V(n) asm volatile("s_waitcnt vmcnt(" #n ")" ::: "memory")
; #define PG8_WAIT_L(n) asm volatile("s_waitcnt lgkmcnt(" #n ")" ::: "memory")
; #define PG8_BAR __builtin_amdgcn_s_barrier()
; #define PG8_SCHED __builtin_amdgcn_sched_barrier(0)
; template <class Epi, class Sched>
; __device__ __forceinline__ void gemm_phase(const int tid, LAS unsigned char* lds, const Gemm g, const Sched& S, const Epi& E) {
;     ...
;             PG8_LDA(At, 1, 1); PG8_STAGE(PG8_SB(1, 0), b3, voffB); PG8_STAGE(PG8_SB(1, 1), b3 + hstep, voffB); PG8_STAGE(PG8_SA(1, 0), a3, voffA);
;             PG8_WAIT_V(8); PG8_WAIT_L(0); PG8_BAR; PG8_MMA(1, 0, At, B0); PG8_MMA(1, 1, At, B1); PG8_BAR; PG8_SCHED;
;         }
;         if (wr == 0) PG8_BAR;
	s_setprio 1
	s_waitcnt lgkmcnt(0)
	v_mfma_f32_16x16x32_bf16 v[124:127], v[138:141], v[200:203], v[124:127]
	v_mfma_f32_16x16x32_bf16 v[116:119], v[146:149], v[200:203], v[116:119]
	v_mfma_f32_16x16x32_bf16 v[108:111], v[138:141], v[208:211], v[108:111]
	v_mfma_f32_16x16x32_bf16 v[100:103], v[146:149], v[208:211], v[100:103]
	v_mfma_f32_16x16x32_bf16 v[92:95], v[138:141], v[216:219], v[92:95]
	v_mfma_f32_16x16x32_bf16 v[84:87], v[146:149], v[216:219], v[84:87]
	v_mfma_f32_16x16x32_bf16 v[76:79], v[138:141], v[224:227], v[76:79]
	v_mfma_f32_16x16x32_bf16 v[68:71], v[146:149], v[224:227], v[68:71]
	v_mfma_f32_16x16x32_bf16 v[124:127], v[142:145], v[204:207], v[124:127]
	v_mfma_f32_16x16x32_bf16 v[116:119], v[172:175], v[204:207], v[116:119]
	v_mfma_f32_16x16x32_bf16 v[108:111], v[142:145], v[212:215], v[108:111]
	v_mfma_f32_16x16x32_bf16 v[100:103], v[172:175], v[212:215], v[100:103]
	v_mfma_f32_16x16x32_bf16 v[92:95], v[142:145], v[220:223], v[92:95]
	v_mfma_f32_16x16x32_bf16 v[84:87], v[172:175], v[220:223], v[84:87]
	v_mfma_f32_16x16x32_bf16 v[76:79], v[142:145], v[228:231], v[76:79]
	v_mfma_f32_16x16x32_bf16 v[68:71], v[172:175], v[228:231], v[68:71]
	v_mfma_f32_16x16x32_bf16 v[120:123], v[176:179], v[200:203], v[120:123]
	v_mfma_f32_16x16x32_bf16 v[112:115], v[184:187], v[200:203], v[112:115]
	v_mfma_f32_16x16x32_bf16 v[104:107], v[176:179], v[208:211], v[104:107]
	v_mfma_f32_16x16x32_bf16 v[96:99], v[184:187], v[208:211], v[96:99]
	v_mfma_f32_16x16x32_bf16 v[88:91], v[176:179], v[216:219], v[88:91]
	v_mfma_f32_16x16x32_bf16 v[80:83], v[184:187], v[216:219], v[80:83]
	v_mfma_f32_16x16x32_bf16 v[72:75], v[176:179], v[224:227], v[72:75]
	v_mfma_f32_16x16x32_bf16 v[64:67], v[184:187], v[224:227], v[64:67]
	v_mfma_f32_16x16x32_bf16 v[120:123], v[180:183], v[204:207], v[120:123]
	v_mfma_f32_16x16x32_bf16 v[112:115], v[188:191], v[204:207], v[112:115]
	v_mfma_f32_16x16x32_bf16 v[104:107], v[180:183], v[212:215], v[104:107]
	v_mfma_f32_16x16x32_bf16 v[96:99], v[188:191], v[212:215], v[96:99]
	v_mfma_f32_16x16x32_bf16 v[88:91], v[180:183], v[220:223], v[88:91]
	v_mfma_f32_16x16x32_bf16 v[80:83], v[188:191], v[220:223], v[80:83]
	v_mfma_f32_16x16x32_bf16 v[72:75], v[180:183], v[228:231], v[72:75]
	v_mfma_f32_16x16x32_bf16 v[64:67], v[188:191], v[228:231], v[64:67]
	s_setprio 0
	s_barrier
	s_add_i32 s26, s73, s40
	v_lshl_add_u64 v[232:233], v[232:233], 0, s[34:35]
	s_mov_b32 m0, s26
	ds_read_b128 v[200:203], v171 offset:49152
	ds_read_b128 v[204:207], v171 offset:50176
	ds_read_b128 v[208:211], v171 offset:51200
	ds_read_b128 v[212:215], v171 offset:52224
	ds_read_b128 v[216:219], v171 offset:53248
	ds_read_b128 v[220:223], v171 offset:54272
	ds_read_b128 v[224:227], v171 offset:55296
	ds_read_b128 v[228:231], v171 offset:56320
	global_load_lds_dwordx4 v[232:233], off
	s_add_i32 m0, s26, 0x2000
	s_add_u32 s24, s24, 0x80080
	v_lshl_add_u64 v[232:233], v[234:235], 0, s[34:35]
	s_addc_u32 s25, s25, 0
	s_add_i32 s26, s74, s40
	global_load_lds_dwordx4 v[232:233], off
	v_lshl_add_u64 v[232:233], s[24:25], 0, v[152:153]
	s_mov_b32 m0, s26
	s_nop 0
	global_load_lds_dwordx4 v[232:233], off
	v_lshl_add_u64 v[232:233], s[24:25], 0, v[128:129]
	s_add_i32 m0, s26, 0x2000
	s_nop 0
	global_load_lds_dwordx4 v[232:233], off
	v_lshl_add_u64 v[232:233], v[236:237], 0, s[34:35]
	s_mov_b32 m0, s64
	s_nop 0
	global_load_lds_dwordx4 v[232:233], off
	v_lshl_add_u64 v[232:233], v[238:239], 0, s[34:35]
	s_mov_b32 m0, s65
	s_nop 0
	global_load_lds_dwordx4 v[232:233], off
	s_waitcnt vmcnt(8)
	s_waitcnt lgkmcnt(0)
	s_barrier
	s_setprio 1
	s_waitcnt lgkmcnt(0)
	v_mfma_f32_16x16x32_bf16 v[60:63], v[138:141], v[200:203], v[60:63]
	v_mfma_f32_16x16x32_bf16 v[52:55], v[146:149], v[200:203], v[52:55]
	v_mfma_f32_16x16x32_bf16 v[44:47], v[138:141], v[208:211], v[44:47]
	v_mfma_f32_16x16x32_bf16 v[36:39], v[146:149], v[208:211], v[36:39]
	v_mfma_f32_16x16x32_bf16 v[28:31], v[138:141], v[216:219], v[28:31]
	v_mfma_f32_16x16x32_bf16 v[20:23], v[146:149], v[216:219], v[20:23]
	v_mfma_f32_16x16x32_bf16 v[12:15], v[138:141], v[224:227], v[12:15]
	v_mfma_f32_16x16x32_bf16 v[4:7], v[146:149], v[224:227], v[4:7]
	v_mfma_f32_16x16x32_bf16 v[60:63], v[142:145], v[204:207], v[60:63]
	v_mfma_f32_16x16x32_bf16 v[52:55], v[172:175], v[204:207], v[52:55]
	v_mfma_f32_16x16x32_bf16 v[44:47], v[142:145], v[212:215], v[44:47]
	v_mfma_f32_16x16x32_bf16 v[36:39], v[172:175], v[212:215], v[36:39]
	v_mfma_f32_16x16x32_bf16 v[28:31], v[142:145], v[220:223], v[28:31]
	v_mfma_f32_16x16x32_bf16 v[20:23], v[172:175], v[220:223], v[20:23]
	v_mfma_f32_16x16x32_bf16 v[12:15], v[142:145], v[228:231], v[12:15]
	v_mfma_f32_16x16x32_bf16 v[4:7], v[172:175], v[228:231], v[4:7]
	v_mfma_f32_16x16x32_bf16 v[56:59], v[176:179], v[200:203], v[56:59]
	v_mfma_f32_16x16x32_bf16 v[48:51], v[184:187], v[200:203], v[48:51]
	v_mfma_f32_16x16x32_bf16 v[40:43], v[176:179], v[208:211], v[40:43]
	v_mfma_f32_16x16x32_bf16 v[32:35], v[184:187], v[208:211], v[32:35]
	v_mfma_f32_16x16x32_bf16 v[24:27], v[176:179], v[216:219], v[24:27]
	v_mfma_f32_16x16x32_bf16 v[16:19], v[184:187], v[216:219], v[16:19]
	v_mfma_f32_16x16x32_bf16 v[8:11], v[176:179], v[224:227], v[8:11]
	v_mfma_f32_16x16x32_bf16 v[0:3], v[184:187], v[224:227], v[0:3]
	v_mfma_f32_16x16x32_bf16 v[56:59], v[180:183], v[204:207], v[56:59]
	v_mfma_f32_16x16x32_bf16 v[48:51], v[188:191], v[204:207], v[48:51]
	v_mfma_f32_16x16x32_bf16 v[40:43], v[180:183], v[212:215], v[40:43]
	v_mfma_f32_16x16x32_bf16 v[32:35], v[188:191], v[212:215], v[32:35]
	v_mfma_f32_16x16x32_bf16 v[24:27], v[180:183], v[220:223], v[24:27]
	v_mfma_f32_16x16x32_bf16 v[16:19], v[188:191], v[220:223], v[16:19]
	v_mfma_f32_16x16x32_bf16 v[8:11], v[180:183], v[228:231], v[8:11]
	v_mfma_f32_16x16x32_bf16 v[0:3], v[188:191], v[228:231], v[0:3]
	s_setprio 0
	s_barrier
	s_add_i32 s72, s72, 2
	s_add_u32 s22, s22, 0x100
	s_addc_u32 s23, s23, 0
	s_add_u32 s70, s70, 0x100
	s_addc_u32 s71, s71, 0
	s_cmp_gt_u32 s72, 29
	s_cbranch_scc0 .LBB0_670
	s_and_b64 vcc, exec, s[10:11]
	s_cbranch_vccz .LBB0_673
	s_barrier

; #define PG8_STAGE(bufoff, gbase, voff) do { _Pragma("unroll") for (int _i = 0; _i < 2; ++_i) \
;         __builtin_amdgcn_global_load_lds((const unsigned*)((const char*)(gbase) + (voff)[_i]), (LAS unsigned*)(lds + (bufoff) + ldsw + _i * 8192), 16, 0, 0); } while (0)
; #define PG8_LDA(dst, b, h) do { _Pragma("unroll") for (int m = 0; m < 4; ++m) _Pragma("unroll") for (int k = 0; k < 2; ++k) dst[m][k] = *(const LAS bf16x8*)(lds + PG8_SA(b, h) + aoff + m * 2048 + k * 1024); } while (0)
; #define PG8_LDB(dst, b, h) do { _Pragma("unroll") for (int n = 0; n < 2; ++n) _Pragma("unroll") for (int k = 0; k < 2; ++k) dst[n][k] = *(const LAS bf16x8*)(lds + PG8_SB(b, h) + boff + n * 2048 + k * 1024); } while (0)
; #define PG8_MMA(ai, bj, At, Bt) do { __builtin_amdgcn_s_setprio(1); _Pragma("unroll") for (int m = 0; m < 4; ++m) _Pragma("unroll") for (int n = 0; n < 2; ++n) _Pragma("unroll") for (int k = 0; k < 2; ++k) \
;         acc[ai][bj][m][n] = __builtin_amdgcn_mfma_f32_16x16x32_bf16(Bt[n][k], At[m][k], acc[ai][bj][m][n], 0, 0, 0); __builtin_amdgcn_s_setprio(0); } while (0)
; #define PG8_WAIT_V(n) asm volatile("s_waitcnt vmcnt(" #n ")" ::: "memory")
; #define PG8_BAR __builtin_amdgcn_s_barrier()
; template <class Epi, class Sched>
; __device__ __forceinline__ void gemm_phase(const int tid, LAS unsigned char* lds, const Gemm g, const Sched& S, const Epi& E) {
;     ...
;         const bool has_next = S.next(ui + 1, nxt);
;         const char* nA = has_next ? (const char*)g.A + (size_t)nxt.pm * tstep : cA; const char* nB = has_next ? (const char*)g.Bt + (size_t)nxt.pn * tstep : cB;
;         for (int t = 0; t < nt; t += 2) {
;             const bool last = (t == nt - 2);
;             const char* a1 = cA + (size_t)(t + 1) * kstep;
;             const char* a2 = last ? nA : cA + (size_t)(t + 2) * kstep; const char* b2 = last ? nB : cB + (size_t)(t + 2) * kstep;
;             const char* a3 = a2 + kstep; const char* b3 = b2 + kstep;
;             if (last && has_next) S.a_ready(nxt);
;             PG8_LDB(B0, 0, 0); PG8_LDB(B1, 0, 1); PG8_SCHED; PG8_LDA(At, 0, 0); PG8_STAGE(PG8_SA(1, 1), a1 + hstep, voffA);
;             PG8_WAIT_V(8); PG8_WAIT_L(0); PG8_BAR; PG8_MMA(0, 0, At, B0); PG8_MMA(0, 1, At, B1); PG8_BAR; PG8_SCHED;
;             PG8_LDA(At, 0, 1); PG8_STAGE(PG8_SB(0, 0), b2, voffB); PG8_STAGE(PG8_SB(0, 1), b2 + hstep, voffB); PG8_STAGE(PG8_SA(0, 0), a2, voffA);
.LBB0_762:
	s_add_u32 s67, s20, 0x100
	v_mov_b32_e32 v0, 0
	s_addc_u32 s68, s21, 0
	s_mov_b32 s69, -2
	s_waitcnt lgkmcnt(0)
	s_add_u32 s4, s18, 0x100
	s_addc_u32 s5, s19, 0
	s_add_i32 s70, 0, 0x10000
	s_cmpk_eq_i32 s69, 0x54
	s_cselect_b32 s23, s15, s5
	s_cselect_b32 s22, s14, s4
	s_cselect_b32 s21, s17, s68
	s_cselect_b32 s20, s16, s67
	s_add_i32 s71, 0, 0x14000
	v_add_u32_e32 v140, s70, v201
	v_add_u32_e32 v184, s71, v201
	ds_read_b128 v[128:131], v140
	ds_read_b128 v[132:135], v140 offset:1024
	ds_read_b128 v[136:139], v140 offset:2048
	ds_read_b128 v[140:143], v140 offset:3072
	ds_read_b128 v[144:147], v184
	ds_read_b128 v[148:151], v184 offset:1024
	ds_read_b128 v[180:183], v184 offset:2048
	ds_read_b128 v[184:187], v184 offset:3072
	v_lshl_add_u64 v[232:233], s[18:19], 0, v[176:177]
	s_add_i32 m0, s38, 0xc000
	ds_read_b128 v[188:191], v202
	ds_read_b128 v[204:207], v202 offset:1024
	ds_read_b128 v[208:211], v202 offset:2048
	ds_read_b128 v[212:215], v202 offset:3072
	ds_read_b128 v[216:219], v202 offset:4096
	ds_read_b128 v[220:223], v202 offset:5120
	ds_read_b128 v[224:227], v202 offset:6144
	ds_read_b128 v[228:231], v202 offset:7168
	global_load_lds_dwordx4 v[232:233], off
	v_lshl_add_u64 v[232:233], s[18:19], 0, v[178:179]
	s_add_i32 m0, s38, 0xe000
	s_nop 0
	global_load_lds_dwordx4 v[232:233], off
	s_waitcnt vmcnt(8)
	s_waitcnt lgkmcnt(0)
	s_barrier
	s_setprio 1
	s_waitcnt lgkmcnt(0)
	v_mfma_f32_16x16x32_bf16 v[124:127], v[128:131], v[188:191], 0
	v_mfma_f32_16x16x32_bf16 v[120:123], v[136:139], v[188:191], 0
	v_mfma_f32_16x16x32_bf16 v[108:111], v[128:131], v[208:211], 0
	v_mfma_f32_16x16x32_bf16 v[104:107], v[136:139], v[208:211], 0
	v_mfma_f32_16x16x32_bf16 v[92:95], v[128:131], v[216:219], 0
	v_mfma_f32_16x16x32_bf16 v[88:91], v[136:139], v[216:219], 0
	v_mfma_f32_16x16x32_bf16 v[76:79], v[128:131], v[224:227], 0
	v_mfma_f32_16x16x32_bf16 v[72:75], v[136:139], v[224:227], 0
	v_mfma_f32_16x16x32_bf16 v[124:127], v[132:135], v[204:207], v[124:127]
	v_mfma_f32_16x16x32_bf16 v[120:123], v[140:143], v[204:207], v[120:123]
	v_mfma_f32_16x16x32_bf16 v[108:111], v[132:135], v[212:215], v[108:111]
	v_mfma_f32_16x16x32_bf16 v[104:107], v[140:143], v[212:215], v[104:107]
	v_mfma_f32_16x16x32_bf16 v[92:95], v[132:135], v[220:223], v[92:95]
	v_mfma_f32_16x16x32_bf16 v[88:91], v[140:143], v[220:223], v[88:91]
	v_mfma_f32_16x16x32_bf16 v[76:79], v[132:135], v[228:231], v[76:79]
	v_mfma_f32_16x16x32_bf16 v[72:75], v[140:143], v[228:231], v[72:75]
	v_mfma_f32_16x16x32_bf16 v[116:119], v[144:147], v[188:191], 0
	v_mfma_f32_16x16x32_bf16 v[112:115], v[180:183], v[188:191], 0
	v_mfma_f32_16x16x32_bf16 v[100:103], v[144:147], v[208:211], 0
	v_mfma_f32_16x16x32_bf16 v[96:99], v[180:183], v[208:211], 0
	v_mfma_f32_16x16x32_bf16 v[84:87], v[144:147], v[216:219], 0
	v_mfma_f32_16x16x32_bf16 v[80:83], v[180:183], v[216:219], 0
	v_mfma_f32_16x16x32_bf16 v[68:71], v[144:147], v[224:227], 0
	v_mfma_f32_16x16x32_bf16 v[64:67], v[180:183], v[224:227], 0
	v_mfma_f32_16x16x32_bf16 v[116:119], v[148:151], v[204:207], v[116:119]
	v_mfma_f32_16x16x32_bf16 v[112:115], v[184:187], v[204:207], v[112:115]
	v_mfma_f32_16x16x32_bf16 v[100:103], v[148:151], v[212:215], v[100:103]
	v_mfma_f32_16x16x32_bf16 v[96:99], v[184:187], v[212:215], v[96:99]
	v_mfma_f32_16x16x32_bf16 v[84:87], v[148:151], v[220:223], v[84:87]
	v_mfma_f32_16x16x32_bf16 v[80:83], v[184:187], v[220:223], v[80:83]
	v_mfma_f32_16x16x32_bf16 v[68:71], v[148:151], v[228:231], v[68:71]
	v_mfma_f32_16x16x32_bf16 v[64:67], v[184:187], v[228:231], v[64:67]
	s_setprio 0
	s_barrier
	s_add_i32 s18, s70, s31
	v_lshl_add_u64 v[232:233], s[20:21], 0, v[152:153]
	s_mov_b32 m0, s18
	ds_read_b128 v[188:191], v202 offset:16384
	ds_read_b128 v[204:207], v202 offset:17408
	ds_read_b128 v[208:211], v202 offset:18432
	ds_read_b128 v[212:215], v202 offset:19456
	ds_read_b128 v[216:219], v202 offset:20480
	ds_read_b128 v[220:223], v202 offset:21504
	ds_read_b128 v[224:227], v202 offset:22528
	ds_read_b128 v[228:231], v202 offset:23552
	global_load_lds_dwordx4 v[232:233], off
	s_add_i32 m0, s18, 0x2000
	s_add_u32 s18, s20, 0x160000
	v_lshl_add_u64 v[234:235], s[20:21], 0, v[174:175]
	s_addc_u32 s19, s21, 0
	s_add_i32 s70, s71, s31
	global_load_lds_dwordx4 v[234:235], off
	v_lshl_add_u64 v[236:237], s[18:19], 0, v[152:153]
	s_mov_b32 m0, s70
	v_lshl_add_u64 v[238:239], s[22:23], 0, v[172:173]
	global_load_lds_dwordx4 v[236:237], off
	v_lshl_add_u64 v[236:237], s[18:19], 0, v[174:175]
	s_add_i32 m0, s70, 0x2000
	s_nop 0
	global_load_lds_dwordx4 v[236:237], off
	v_lshl_add_u64 v[236:237], s[22:23], 0, v[170:171]
	s_mov_b32 m0, s38
	s_nop 0
	global_load_lds_dwordx4 v[236:237], off
	s_mov_b32 m0, s39
	s_nop 0
	global_load_lds_dwordx4 v[238:239], off
	s_waitcnt vmcnt(8)
	s_waitcnt lgkmcnt(0)
	s_barrier
; #define PG8_STAGE(bufoff, gbase, voff) do { _Pragma("unroll") for (int _i = 0; _i < 2; ++_i) \
;         __builtin_amdgcn_global_load_lds((const unsigned*)((const char*)(gbase) + (voff)[_i]), (LAS unsigned*)(lds + (bufoff) + ldsw + _i * 8192), 16, 0, 0); } while (0)
; #define PG8_LDA(dst, b, h) do { _Pragma("unroll") for (int m = 0; m < 4; ++m) _Pragma("unroll") for (int k = 0; k < 2; ++k) dst[m][k] = *(const LAS bf16x8*)(lds + PG8_SA(b, h) + aoff + m * 2048 + k * 1024); } while (0)
; #define PG8_LDB(dst, b, h) do { _Pragma("unroll") for (int n = 0; n < 2; ++n) _Pragma("unroll") for (int k = 0; k < 2; ++k) dst[n][k] = *(const LAS bf16x8*)(lds + PG8_SB(b, h) + boff + n * 2048 + k * 1024); } while (0)
; #define PG8_MMA(ai, bj, At, Bt) do { __builtin_amdgcn_s_setprio(1); _Pragma("unroll") for (int m = 0; m < 4; ++m) _Pragma("unroll") for (int n = 0; n < 2; ++n) _Pragma("unroll") for (int k = 0; k < 2; ++k) \
;         acc[ai][bj][m][n] = __builtin_amdgcn_mfma_f32_16x16x32_bf16(Bt[n][k], At[m][k], acc[ai][bj][m][n], 0, 0, 0); __builtin_amdgcn_s_setprio(0); } while (0)
; #define PG8_WAIT_V(n) asm volatile("s_waitcnt vmcnt(" #n ")" ::: "memory")
; #define PG8_WAIT_L(n) asm volatile("s_waitcnt lgkmcnt(" #n ")" ::: "memory")
; #define PG8_BAR __builtin_amdgcn_s_barrier()
; #define PG8_SCHED __builtin_amdgcn_sched_barrier(0)
; template <class Epi, class Sched>
; __device__ __forceinline__ void gemm_phase(const int tid, LAS unsigned char* lds, const Gemm g, const Sched& S, const Epi& E) {
;     ...
;             PG8_WAIT_V(8); PG8_WAIT_L(0); PG8_BAR; PG8_MMA(1, 0, At, B0); PG8_MMA(1, 1, At, B1); PG8_BAR; PG8_SCHED;
;             PG8_LDB(B0, 1, 0); PG8_LDB(B1, 1, 1); PG8_SCHED; PG8_LDA(At, 1, 0); PG8_STAGE(PG8_SA(0, 1), a2 + hstep, voffA);
;             PG8_WAIT_V(8); PG8_WAIT_L(0); PG8_BAR; PG8_MMA(0, 0, At, B0); PG8_MMA(0, 1, At, B1); PG8_BAR; PG8_SCHED;
	s_setprio 1
	s_waitcnt lgkmcnt(0)
	v_mfma_f32_16x16x32_bf16 v[60:63], v[128:131], v[188:191], 0
	v_mfma_f32_16x16x32_bf16 v[56:59], v[136:139], v[188:191], 0
	v_mfma_f32_16x16x32_bf16 v[44:47], v[128:131], v[208:211], 0
	v_mfma_f32_16x16x32_bf16 v[40:43], v[136:139], v[208:211], 0
	v_mfma_f32_16x16x32_bf16 v[28:31], v[128:131], v[216:219], 0
	v_mfma_f32_16x16x32_bf16 v[24:27], v[136:139], v[216:219], 0
	v_mfma_f32_16x16x32_bf16 v[12:15], v[128:131], v[224:227], 0
	v_mfma_f32_16x16x32_bf16 v[8:11], v[136:139], v[224:227], 0
	v_mfma_f32_16x16x32_bf16 v[60:63], v[132:135], v[204:207], v[60:63]
	v_mfma_f32_16x16x32_bf16 v[56:59], v[140:143], v[204:207], v[56:59]
	v_mfma_f32_16x16x32_bf16 v[44:47], v[132:135], v[212:215], v[44:47]
	v_mfma_f32_16x16x32_bf16 v[40:43], v[140:143], v[212:215], v[40:43]
	v_mfma_f32_16x16x32_bf16 v[28:31], v[132:135], v[220:223], v[28:31]
	v_mfma_f32_16x16x32_bf16 v[24:27], v[140:143], v[220:223], v[24:27]
	v_mfma_f32_16x16x32_bf16 v[12:15], v[132:135], v[228:231], v[12:15]
	v_mfma_f32_16x16x32_bf16 v[8:11], v[140:143], v[228:231], v[8:11]
	v_mfma_f32_16x16x32_bf16 v[52:55], v[144:147], v[188:191], 0
	v_mfma_f32_16x16x32_bf16 v[48:51], v[180:183], v[188:191], 0
	v_mfma_f32_16x16x32_bf16 v[36:39], v[144:147], v[208:211], 0
	v_mfma_f32_16x16x32_bf16 v[32:35], v[180:183], v[208:211], 0
	v_mfma_f32_16x16x32_bf16 v[20:23], v[144:147], v[216:219], 0
	v_mfma_f32_16x16x32_bf16 v[16:19], v[180:183], v[216:219], 0
	v_mfma_f32_16x16x32_bf16 v[4:7], v[144:147], v[224:227], 0
	v_mfma_f32_16x16x32_bf16 v[0:3], v[180:183], v[224:227], 0
	v_mfma_f32_16x16x32_bf16 v[52:55], v[148:151], v[204:207], v[52:55]
	v_mfma_f32_16x16x32_bf16 v[48:51], v[184:187], v[204:207], v[48:51]
	v_mfma_f32_16x16x32_bf16 v[36:39], v[148:151], v[212:215], v[36:39]
	v_mfma_f32_16x16x32_bf16 v[32:35], v[184:187], v[212:215], v[32:35]
	v_mfma_f32_16x16x32_bf16 v[20:23], v[148:151], v[220:223], v[20:23]
	v_mfma_f32_16x16x32_bf16 v[16:19], v[184:187], v[220:223], v[16:19]
	v_mfma_f32_16x16x32_bf16 v[4:7], v[148:151], v[228:231], v[4:7]
	v_mfma_f32_16x16x32_bf16 v[0:3], v[184:187], v[228:231], v[0:3]
	s_setprio 0
	s_barrier
	s_add_i32 s70, 0, 0x18000
	s_add_i32 s71, 0, 0x1c000
	v_add_u32_e32 v140, s70, v201
	v_add_u32_e32 v184, s71, v201
	ds_read_b128 v[128:131], v140
	ds_read_b128 v[132:135], v140 offset:1024
	ds_read_b128 v[136:139], v140 offset:2048
	ds_read_b128 v[140:143], v140 offset:3072
	ds_read_b128 v[144:147], v184
	ds_read_b128 v[148:151], v184 offset:1024
	ds_read_b128 v[180:183], v184 offset:2048
	ds_read_b128 v[184:187], v184 offset:3072
	s_add_u32 s18, s22, 0x160000
	s_addc_u32 s19, s23, 0
	s_mov_b32 m0, s40
	v_lshl_add_u64 v[240:241], s[18:19], 0, v[170:171]
	ds_read_b128 v[188:191], v202 offset:32768
	ds_read_b128 v[204:207], v202 offset:33792
	ds_read_b128 v[208:211], v202 offset:34816
	ds_read_b128 v[212:215], v202 offset:35840
	ds_read_b128 v[216:219], v202 offset:36864
	ds_read_b128 v[220:223], v202 offset:37888
	ds_read_b128 v[224:227], v202 offset:38912
	ds_read_b128 v[228:231], v202 offset:39936
	global_load_lds_dwordx4 v[240:241], off
	v_lshl_add_u64 v[240:241], s[18:19], 0, v[172:173]
	s_mov_b32 m0, s41
	s_nop 0
	global_load_lds_dwordx4 v[240:241], off
	s_waitcnt vmcnt(8)
	s_waitcnt lgkmcnt(0)
	s_barrier
	s_setprio 1
	s_waitcnt lgkmcnt(0)
	v_mfma_f32_16x16x32_bf16 v[124:127], v[128:131], v[188:191], v[124:127]
	v_mfma_f32_16x16x32_bf16 v[120:123], v[136:139], v[188:191], v[120:123]
	v_mfma_f32_16x16x32_bf16 v[108:111], v[128:131], v[208:211], v[108:111]
	v_mfma_f32_16x16x32_bf16 v[104:107], v[136:139], v[208:211], v[104:107]
	v_mfma_f32_16x16x32_bf16 v[92:95], v[128:131], v[216:219], v[92:95]
	v_mfma_f32_16x16x32_bf16 v[88:91], v[136:139], v[216:219], v[88:91]
	v_mfma_f32_16x16x32_bf16 v[76:79], v[128:131], v[224:227], v[76:79]
	v_mfma_f32_16x16x32_bf16 v[72:75], v[136:139], v[224:227], v[72:75]
	v_mfma_f32_16x16x32_bf16 v[124:127], v[132:135], v[204:207], v[124:127]
	v_mfma_f32_16x16x32_bf16 v[120:123], v[140:143], v[204:207], v[120:123]
	v_mfma_f32_16x16x32_bf16 v[108:111], v[132:135], v[212:215], v[108:111]
	v_mfma_f32_16x16x32_bf16 v[104:107], v[140:143], v[212:215], v[104:107]
	v_mfma_f32_16x16x32_bf16 v[92:95], v[132:135], v[220:223], v[92:95]
	v_mfma_f32_16x16x32_bf16 v[88:91], v[140:143], v[220:223], v[88:91]
	v_mfma_f32_16x16x32_bf16 v[76:79], v[132:135], v[228:231], v[76:79]
	v_mfma_f32_16x16x32_bf16 v[72:75], v[140:143], v[228:231], v[72:75]
	v_mfma_f32_16x16x32_bf16 v[116:119], v[144:147], v[188:191], v[116:119]
	v_mfma_f32_16x16x32_bf16 v[112:115], v[180:183], v[188:191], v[112:115]
	v_mfma_f32_16x16x32_bf16 v[100:103], v[144:147], v[208:211], v[100:103]
	v_mfma_f32_16x16x32_bf16 v[96:99], v[180:183], v[208:211], v[96:99]
	v_mfma_f32_16x16x32_bf16 v[84:87], v[144:147], v[216:219], v[84:87]
	v_mfma_f32_16x16x32_bf16 v[80:83], v[180:183], v[216:219], v[80:83]
	v_mfma_f32_16x16x32_bf16 v[68:71], v[144:147], v[224:227], v[68:71]
	v_mfma_f32_16x16x32_bf16 v[64:67], v[180:183], v[224:227], v[64:67]
	v_mfma_f32_16x16x32_bf16 v[116:119], v[148:151], v[204:207], v[116:119]
	v_mfma_f32_16x16x32_bf16 v[112:115], v[184:187], v[204:207], v[112:115]
	v_mfma_f32_16x16x32_bf16 v[100:103], v[148:151], v[212:215], v[100:103]
	v_mfma_f32_16x16x32_bf16 v[96:99], v[184:187], v[212:215], v[96:99]
	v_mfma_f32_16x16x32_bf16 v[84:87], v[148:151], v[220:223], v[84:87]
	v_mfma_f32_16x16x32_bf16 v[80:83], v[184:187], v[220:223], v[80:83]
	v_mfma_f32_16x16x32_bf16 v[68:71], v[148:151], v[228:231], v[68:71]
	v_mfma_f32_16x16x32_bf16 v[64:67], v[184:187], v[228:231], v[64:67]
	s_setprio 0
	s_barrier
; #define PG8_STAGE(bufoff, gbase, voff) do { _Pragma("unroll") for (int _i = 0; _i < 2; ++_i) \
;         __builtin_amdgcn_global_load_lds((const unsigned*)((const char*)(gbase) + (voff)[_i]), (LAS unsigned*)(lds + (bufoff) + ldsw + _i * 8192), 16, 0, 0); } while (0)
; #define PG8_LDA(dst, b, h) do { _Pragma("unroll") for (int m = 0; m < 4; ++m) _Pragma("unroll") for (int k = 0; k < 2; ++k) dst[m][k] = *(const LAS bf16x8*)(lds + PG8_SA(b, h) + aoff + m * 2048 + k * 1024); } while (0)
; #define PG8_LDB(dst, b, h) do { _Pragma("unroll") for (int n = 0; n < 2; ++n) _Pragma("unroll") for (int k = 0; k < 2; ++k) dst[n][k] = *(const LAS bf16x8*)(lds + PG8_SB(b, h) + boff + n * 2048 + k * 1024); } while (0)
; #define PG8_WAIT_V(n) asm volatile("s_waitcnt vmcnt(" #n ")" ::: "memory")
; template <class Epi, class Sched>
; __device__ __forceinline__ void gemm_phase(const int tid, LAS unsigned char* lds, const Gemm g, const Sched& S, const Epi& E) {
;     ...
;         for (int t = 0; t < nt; t += 2) {
;             const bool last = (t == nt - 2);
;             const char* a1 = cA + (size_t)(t + 1) * kstep;
;             const char* a2 = last ? nA : cA + (size_t)(t + 2) * kstep; const char* b2 = last ? nB : cB + (size_t)(t + 2) * kstep;
;             const char* a3 = a2 + kstep; const char* b3 = b2 + kstep;
;             if (last && has_next) S.a_ready(nxt);
;             PG8_LDB(B0, 0, 0); PG8_LDB(B1, 0, 1); PG8_SCHED; PG8_LDA(At, 0, 0); PG8_STAGE(PG8_SA(1, 1), a1 + hstep, voffA);
;             PG8_WAIT_V(8); PG8_WAIT_L(0); PG8_BAR; PG8_MMA(0, 0, At, B0); PG8_MMA(0, 1, At, B1); PG8_BAR; PG8_SCHED;
;             PG8_LDA(At, 0, 1); PG8_STAGE(PG8_SB(0, 0), b2, voffB); PG8_STAGE(PG8_SB(0, 1), b2 + hstep, voffB); PG8_STAGE(PG8_SA(0, 0), a2, voffA);
;             PG8_WAIT_V(8); PG8_WAIT_L(0); PG8_BAR; PG8_MMA(1, 0, At, B0); PG8_MMA(1, 1, At, B1); PG8_BAR; PG8_SCHED;
;             PG8_LDB(B0, 1, 0); PG8_LDB(B1, 1, 1); PG8_SCHED; PG8_LDA(At, 1, 0); PG8_STAGE(PG8_SA(0, 1), a2 + hstep, voffA);
;             PG8_WAIT_V(8); PG8_WAIT_L(0); PG8_BAR; PG8_MMA(0, 0, At, B0); PG8_MMA(0, 1, At, B1); PG8_BAR; PG8_SCHED;
;             PG8_LDA(At, 1, 1); PG8_STAGE(PG8_SB(1, 0), b3, voffB); PG8_STAGE(PG8_SB(1, 1), b3 + hstep, voffB); PG8_STAGE(PG8_SA(1, 0), a3, voffA);
;             PG8_WAIT_V(8); PG8_WAIT_L(0); PG8_BAR; PG8_MMA(1, 0, At, B0); PG8_MMA(1, 1, At, B1); PG8_BAR; PG8_SCHED;
	s_add_i32 s18, s70, s31
	v_lshl_add_u64 v[232:233], v[232:233], 0, s[34:35]
	s_mov_b32 m0, s18
	ds_read_b128 v[188:191], v202 offset:49152
	ds_read_b128 v[204:207], v202 offset:50176
	ds_read_b128 v[208:211], v202 offset:51200
	ds_read_b128 v[212:215], v202 offset:52224
	ds_read_b128 v[216:219], v202 offset:53248
	ds_read_b128 v[220:223], v202 offset:54272
	ds_read_b128 v[224:227], v202 offset:55296
	ds_read_b128 v[228:231], v202 offset:56320
	global_load_lds_dwordx4 v[232:233], off
	s_add_i32 m0, s18, 0x2000
	s_add_u32 s18, s20, 0x160080
	v_lshl_add_u64 v[232:233], v[234:235], 0, s[34:35]
	s_addc_u32 s19, s21, 0
	s_add_i32 s20, s71, s31
	global_load_lds_dwordx4 v[232:233], off
	v_lshl_add_u64 v[232:233], s[18:19], 0, v[152:153]
	s_mov_b32 m0, s20
	s_nop 0
	global_load_lds_dwordx4 v[232:233], off
	v_lshl_add_u64 v[232:233], s[18:19], 0, v[174:175]
	s_add_i32 m0, s20, 0x2000
	s_nop 0
	global_load_lds_dwordx4 v[232:233], off
	v_lshl_add_u64 v[232:233], v[236:237], 0, s[34:35]
	s_mov_b32 m0, s58
	s_nop 0
	global_load_lds_dwordx4 v[232:233], off
	v_lshl_add_u64 v[232:233], v[238:239], 0, s[34:35]
	s_mov_b32 m0, s59
	s_nop 0
	global_load_lds_dwordx4 v[232:233], off
	s_waitcnt vmcnt(8)
	s_waitcnt lgkmcnt(0)
	s_barrier
	s_setprio 1
	s_waitcnt lgkmcnt(0)
	v_mfma_f32_16x16x32_bf16 v[60:63], v[128:131], v[188:191], v[60:63]
	v_mfma_f32_16x16x32_bf16 v[56:59], v[136:139], v[188:191], v[56:59]
	v_mfma_f32_16x16x32_bf16 v[44:47], v[128:131], v[208:211], v[44:47]
	v_mfma_f32_16x16x32_bf16 v[40:43], v[136:139], v[208:211], v[40:43]
	v_mfma_f32_16x16x32_bf16 v[28:31], v[128:131], v[216:219], v[28:31]
	v_mfma_f32_16x16x32_bf16 v[24:27], v[136:139], v[216:219], v[24:27]
	v_mfma_f32_16x16x32_bf16 v[12:15], v[128:131], v[224:227], v[12:15]
	v_mfma_f32_16x16x32_bf16 v[8:11], v[136:139], v[224:227], v[8:11]
	v_mfma_f32_16x16x32_bf16 v[60:63], v[132:135], v[204:207], v[60:63]
	v_mfma_f32_16x16x32_bf16 v[56:59], v[140:143], v[204:207], v[56:59]
	v_mfma_f32_16x16x32_bf16 v[44:47], v[132:135], v[212:215], v[44:47]
	v_mfma_f32_16x16x32_bf16 v[40:43], v[140:143], v[212:215], v[40:43]
	v_mfma_f32_16x16x32_bf16 v[28:31], v[132:135], v[220:223], v[28:31]
	v_mfma_f32_16x16x32_bf16 v[24:27], v[140:143], v[220:223], v[24:27]
	v_mfma_f32_16x16x32_bf16 v[12:15], v[132:135], v[228:231], v[12:15]
	v_mfma_f32_16x16x32_bf16 v[8:11], v[140:143], v[228:231], v[8:11]
	v_mfma_f32_16x16x32_bf16 v[52:55], v[144:147], v[188:191], v[52:55]
	v_mfma_f32_16x16x32_bf16 v[48:51], v[180:183], v[188:191], v[48:51]
	v_mfma_f32_16x16x32_bf16 v[36:39], v[144:147], v[208:211], v[36:39]
	v_mfma_f32_16x16x32_bf16 v[32:35], v[180:183], v[208:211], v[32:35]
	v_mfma_f32_16x16x32_bf16 v[20:23], v[144:147], v[216:219], v[20:23]
	v_mfma_f32_16x16x32_bf16 v[16:19], v[180:183], v[216:219], v[16:19]
	v_mfma_f32_16x16x32_bf16 v[4:7], v[144:147], v[224:227], v[4:7]
	v_mfma_f32_16x16x32_bf16 v[0:3], v[180:183], v[224:227], v[0:3]
	v_mfma_f32_16x16x32_bf16 v[52:55], v[148:151], v[204:207], v[52:55]
	v_mfma_f32_16x16x32_bf16 v[48:51], v[184:187], v[204:207], v[48:51]
	v_mfma_f32_16x16x32_bf16 v[36:39], v[148:151], v[212:215], v[36:39]
	v_mfma_f32_16x16x32_bf16 v[32:35], v[184:187], v[212:215], v[32:35]
	v_mfma_f32_16x16x32_bf16 v[20:23], v[148:151], v[220:223], v[20:23]
	v_mfma_f32_16x16x32_bf16 v[16:19], v[184:187], v[220:223], v[16:19]
	v_mfma_f32_16x16x32_bf16 v[4:7], v[148:151], v[228:231], v[4:7]
	v_mfma_f32_16x16x32_bf16 v[0:3], v[184:187], v[228:231], v[0:3]
	s_setprio 0
	s_barrier
	s_add_i32 s69, s69, 2
	s_add_u32 s67, s67, 0x100
	s_addc_u32 s68, s68, 0
	s_cmpk_gt_u32 s69, 0x55
	s_mov_b64 s[18:19], s[4:5]
.LBB0_763:
	s_add_u32 s4, s18, 0x100
	s_addc_u32 s5, s19, 0
	s_add_i32 s70, 0, 0x10000
	s_cmpk_eq_i32 s69, 0x54
	s_cselect_b32 s23, s15, s5
	s_cselect_b32 s22, s14, s4
	s_cselect_b32 s21, s17, s68
	s_cselect_b32 s20, s16, s67
	s_add_i32 s71, 0, 0x14000
	v_add_u32_e32 v140, s70, v201
	v_add_u32_e32 v184, s71, v201
	ds_read_b128 v[128:131], v140
	ds_read_b128 v[132:135], v140 offset:1024
	ds_read_b128 v[136:139], v140 offset:2048
	ds_read_b128 v[140:143], v140 offset:3072
	ds_read_b128 v[144:147], v184
	ds_read_b128 v[148:151], v184 offset:1024
	ds_read_b128 v[180:183], v184 offset:2048
	ds_read_b128 v[184:187], v184 offset:3072
	v_lshl_add_u64 v[232:233], s[18:19], 0, v[176:177]
	s_add_i32 m0, s38, 0xc000
	ds_read_b128 v[188:191], v202
	ds_read_b128 v[204:207], v202 offset:1024
	ds_read_b128 v[208:211], v202 offset:2048
	ds_read_b128 v[212:215], v202 offset:3072
	ds_read_b128 v[216:219], v202 offset:4096
	ds_read_b128 v[220:223], v202 offset:5120
	ds_read_b128 v[224:227], v202 offset:6144
	ds_read_b128 v[228:231], v202 offset:7168
	global_load_lds_dwordx4 v[232:233], off
	v_lshl_add_u64 v[232:233], s[18:19], 0, v[178:179]
	s_add_i32 m0, s38, 0xe000
	s_nop 0
	global_load_lds_dwordx4 v[232:233], off
	s_waitcnt vmcnt(8)
	s_waitcnt lgkmcnt(0)
	s_barrier
; #define PG8_STAGE(bufoff, gbase, voff) do { _Pragma("unroll") for (int _i = 0; _i < 2; ++_i) \
;         __builtin_amdgcn_global_load_lds((const unsigned*)((const char*)(gbase) + (voff)[_i]), (LAS unsigned*)(lds + (bufoff) + ldsw + _i * 8192), 16, 0, 0); } while (0)
; #define PG8_LDA(dst, b, h) do { _Pragma("unroll") for (int m = 0; m < 4; ++m) _Pragma("unroll") for (int k = 0; k < 2; ++k) dst[m][k] = *(const LAS bf16x8*)(lds + PG8_SA(b, h) + aoff + m * 2048 + k * 1024); } while (0)
; #define PG8_MMA(ai, bj, At, Bt) do { __builtin_amdgcn_s_setprio(1); _Pragma("unroll") for (int m = 0; m < 4; ++m) _Pragma("unroll") for (int n = 0; n < 2; ++n) _Pragma("unroll") for (int k = 0; k < 2; ++k) \
;         acc[ai][bj][m][n] = __builtin_amdgcn_mfma_f32_16x16x32_bf16(Bt[n][k], At[m][k], acc[ai][bj][m][n], 0, 0, 0); __builtin_amdgcn_s_setprio(0); } while (0)
; #define PG8_WAIT_V(n) asm volatile("s_waitcnt vmcnt(" #n ")" ::: "memory")
; #define PG8_WAIT_L(n) asm volatile("s_waitcnt lgkmcnt(" #n ")" ::: "memory")
; #define PG8_BAR __builtin_amdgcn_s_barrier()
; #define PG8_SCHED __builtin_amdgcn_sched_barrier(0)
; template <class Epi, class Sched>
; __device__ __forceinline__ void gemm_phase(const int tid, LAS unsigned char* lds, const Gemm g, const Sched& S, const Epi& E) {
;     ...
;             PG8_WAIT_V(8); PG8_WAIT_L(0); PG8_BAR; PG8_MMA(0, 0, At, B0); PG8_MMA(0, 1, At, B1); PG8_BAR; PG8_SCHED;
;             PG8_LDA(At, 0, 1); PG8_STAGE(PG8_SB(0, 0), b2, voffB); PG8_STAGE(PG8_SB(0, 1), b2 + hstep, voffB); PG8_STAGE(PG8_SA(0, 0), a2, voffA);
;             PG8_WAIT_V(8); PG8_WAIT_L(0); PG8_BAR; PG8_MMA(1, 0, At, B0); PG8_MMA(1, 1, At, B1); PG8_BAR; PG8_SCHED;
	s_setprio 1
	s_waitcnt lgkmcnt(0)
	v_mfma_f32_16x16x32_bf16 v[124:127], v[128:131], v[188:191], v[124:127]
	v_mfma_f32_16x16x32_bf16 v[120:123], v[136:139], v[188:191], v[120:123]
	v_mfma_f32_16x16x32_bf16 v[108:111], v[128:131], v[208:211], v[108:111]
	v_mfma_f32_16x16x32_bf16 v[104:107], v[136:139], v[208:211], v[104:107]
	v_mfma_f32_16x16x32_bf16 v[92:95], v[128:131], v[216:219], v[92:95]
	v_mfma_f32_16x16x32_bf16 v[88:91], v[136:139], v[216:219], v[88:91]
	v_mfma_f32_16x16x32_bf16 v[76:79], v[128:131], v[224:227], v[76:79]
	v_mfma_f32_16x16x32_bf16 v[72:75], v[136:139], v[224:227], v[72:75]
	v_mfma_f32_16x16x32_bf16 v[124:127], v[132:135], v[204:207], v[124:127]
	v_mfma_f32_16x16x32_bf16 v[120:123], v[140:143], v[204:207], v[120:123]
	v_mfma_f32_16x16x32_bf16 v[108:111], v[132:135], v[212:215], v[108:111]
	v_mfma_f32_16x16x32_bf16 v[104:107], v[140:143], v[212:215], v[104:107]
	v_mfma_f32_16x16x32_bf16 v[92:95], v[132:135], v[220:223], v[92:95]
	v_mfma_f32_16x16x32_bf16 v[88:91], v[140:143], v[220:223], v[88:91]
	v_mfma_f32_16x16x32_bf16 v[76:79], v[132:135], v[228:231], v[76:79]
	v_mfma_f32_16x16x32_bf16 v[72:75], v[140:143], v[228:231], v[72:75]
	v_mfma_f32_16x16x32_bf16 v[116:119], v[144:147], v[188:191], v[116:119]
	v_mfma_f32_16x16x32_bf16 v[112:115], v[180:183], v[188:191], v[112:115]
	v_mfma_f32_16x16x32_bf16 v[100:103], v[144:147], v[208:211], v[100:103]
	v_mfma_f32_16x16x32_bf16 v[96:99], v[180:183], v[208:211], v[96:99]
	v_mfma_f32_16x16x32_bf16 v[84:87], v[144:147], v[216:219], v[84:87]
	v_mfma_f32_16x16x32_bf16 v[80:83], v[180:183], v[216:219], v[80:83]
	v_mfma_f32_16x16x32_bf16 v[68:71], v[144:147], v[224:227], v[68:71]
	v_mfma_f32_16x16x32_bf16 v[64:67], v[180:183], v[224:227], v[64:67]
	v_mfma_f32_16x16x32_bf16 v[116:119], v[148:151], v[204:207], v[116:119]
	v_mfma_f32_16x16x32_bf16 v[112:115], v[184:187], v[204:207], v[112:115]
	v_mfma_f32_16x16x32_bf16 v[100:103], v[148:151], v[212:215], v[100:103]
	v_mfma_f32_16x16x32_bf16 v[96:99], v[184:187], v[212:215], v[96:99]
	v_mfma_f32_16x16x32_bf16 v[84:87], v[148:151], v[220:223], v[84:87]
	v_mfma_f32_16x16x32_bf16 v[80:83], v[184:187], v[220:223], v[80:83]
	v_mfma_f32_16x16x32_bf16 v[68:71], v[148:151], v[228:231], v[68:71]
	v_mfma_f32_16x16x32_bf16 v[64:67], v[184:187], v[228:231], v[64:67]
	s_setprio 0
	s_barrier
	s_add_i32 s18, s70, s31
	v_lshl_add_u64 v[232:233], s[20:21], 0, v[152:153]
	s_mov_b32 m0, s18
	ds_read_b128 v[188:191], v202 offset:16384
	ds_read_b128 v[204:207], v202 offset:17408
	ds_read_b128 v[208:211], v202 offset:18432
	ds_read_b128 v[212:215], v202 offset:19456
	ds_read_b128 v[216:219], v202 offset:20480
	ds_read_b128 v[220:223], v202 offset:21504
	ds_read_b128 v[224:227], v202 offset:22528
	ds_read_b128 v[228:231], v202 offset:23552
	global_load_lds_dwordx4 v[232:233], off
	s_add_i32 m0, s18, 0x2000
	s_add_u32 s18, s20, 0x160000
	v_lshl_add_u64 v[234:235], s[20:21], 0, v[174:175]
	s_addc_u32 s19, s21, 0
	s_add_i32 s70, s71, s31
	global_load_lds_dwordx4 v[234:235], off
	v_lshl_add_u64 v[236:237], s[18:19], 0, v[152:153]
	s_mov_b32 m0, s70
	v_lshl_add_u64 v[238:239], s[22:23], 0, v[172:173]
	global_load_lds_dwordx4 v[236:237], off
	v_lshl_add_u64 v[236:237], s[18:19], 0, v[174:175]
	s_add_i32 m0, s70, 0x2000
	s_nop 0
	global_load_lds_dwordx4 v[236:237], off
	v_lshl_add_u64 v[236:237], s[22:23], 0, v[170:171]
	s_mov_b32 m0, s38
	s_nop 0
	global_load_lds_dwordx4 v[236:237], off
	s_mov_b32 m0, s39
	s_nop 0
	global_load_lds_dwordx4 v[238:239], off
	s_waitcnt vmcnt(8)
	s_waitcnt lgkmcnt(0)
	s_barrier
	s_setprio 1
	s_waitcnt lgkmcnt(0)
	v_mfma_f32_16x16x32_bf16 v[60:63], v[128:131], v[188:191], v[60:63]
	v_mfma_f32_16x16x32_bf16 v[56:59], v[136:139], v[188:191], v[56:59]
	v_mfma_f32_16x16x32_bf16 v[44:47], v[128:131], v[208:211], v[44:47]
	v_mfma_f32_16x16x32_bf16 v[40:43], v[136:139], v[208:211], v[40:43]
	v_mfma_f32_16x16x32_bf16 v[28:31], v[128:131], v[216:219], v[28:31]
	v_mfma_f32_16x16x32_bf16 v[24:27], v[136:139], v[216:219], v[24:27]
	v_mfma_f32_16x16x32_bf16 v[12:15], v[128:131], v[224:227], v[12:15]
	v_mfma_f32_16x16x32_bf16 v[8:11], v[136:139], v[224:227], v[8:11]
	v_mfma_f32_16x16x32_bf16 v[60:63], v[132:135], v[204:207], v[60:63]
	v_mfma_f32_16x16x32_bf16 v[56:59], v[140:143], v[204:207], v[56:59]
	v_mfma_f32_16x16x32_bf16 v[44:47], v[132:135], v[212:215], v[44:47]
	v_mfma_f32_16x16x32_bf16 v[40:43], v[140:143], v[212:215], v[40:43]
	v_mfma_f32_16x16x32_bf16 v[28:31], v[132:135], v[220:223], v[28:31]
	v_mfma_f32_16x16x32_bf16 v[24:27], v[140:143], v[220:223], v[24:27]
	v_mfma_f32_16x16x32_bf16 v[12:15], v[132:135], v[228:231], v[12:15]
	v_mfma_f32_16x16x32_bf16 v[8:11], v[140:143], v[228:231], v[8:11]
	v_mfma_f32_16x16x32_bf16 v[52:55], v[144:147], v[188:191], v[52:55]
	v_mfma_f32_16x16x32_bf16 v[48:51], v[180:183], v[188:191], v[48:51]
	v_mfma_f32_16x16x32_bf16 v[36:39], v[144:147], v[208:211], v[36:39]
	v_mfma_f32_16x16x32_bf16 v[32:35], v[180:183], v[208:211], v[32:35]
	v_mfma_f32_16x16x32_bf16 v[20:23], v[144:147], v[216:219], v[20:23]
	v_mfma_f32_16x16x32_bf16 v[16:19], v[180:183], v[216:219], v[16:19]
	v_mfma_f32_16x16x32_bf16 v[4:7], v[144:147], v[224:227], v[4:7]
	v_mfma_f32_16x16x32_bf16 v[0:3], v[180:183], v[224:227], v[0:3]
	v_mfma_f32_16x16x32_bf16 v[52:55], v[148:151], v[204:207], v[52:55]
	v_mfma_f32_16x16x32_bf16 v[48:51], v[184:187], v[204:207], v[48:51]
	v_mfma_f32_16x16x32_bf16 v[36:39], v[148:151], v[212:215], v[36:39]
	v_mfma_f32_16x16x32_bf16 v[32:35], v[184:187], v[212:215], v[32:35]
	v_mfma_f32_16x16x32_bf16 v[20:23], v[148:151], v[220:223], v[20:23]
	v_mfma_f32_16x16x32_bf16 v[16:19], v[184:187], v[220:223], v[16:19]
	v_mfma_f32_16x16x32_bf16 v[4:7], v[148:151], v[228:231], v[4:7]
	v_mfma_f32_16x16x32_bf16 v[0:3], v[184:187], v[228:231], v[0:3]
	s_setprio 0
	s_barrier
; #define PG8_STAGE(bufoff, gbase, voff) do { _Pragma("unroll") for (int _i = 0; _i < 2; ++_i) \
;         __builtin_amdgcn_global_load_lds((const unsigned*)((const char*)(gbase) + (voff)[_i]), (LAS unsigned*)(lds + (bufoff) + ldsw + _i * 8192), 16, 0, 0); } while (0)
; #define PG8_LDA(dst, b, h) do { _Pragma("unroll") for (int m = 0; m < 4; ++m) _Pragma("unroll") for (int k = 0; k < 2; ++k) dst[m][k] = *(const LAS bf16x8*)(lds + PG8_SA(b, h) + aoff + m * 2048 + k * 1024); } while (0)
; #define PG8_LDB(dst, b, h) do { _Pragma("unroll") for (int n = 0; n < 2; ++n) _Pragma("unroll") for (int k = 0; k < 2; ++k) dst[n][k] = *(const LAS bf16x8*)(lds + PG8_SB(b, h) + boff + n * 2048 + k * 1024); } while (0)
; #define PG8_MMA(ai, bj, At, Bt) do { __builtin_amdgcn_s_setprio(1); _Pragma("unroll") for (int m = 0; m < 4; ++m) _Pragma("unroll") for (int n = 0; n < 2; ++n) _Pragma("unroll") for (int k = 0; k < 2; ++k) \
;         acc[ai][bj][m][n] = __builtin_amdgcn_mfma_f32_16x16x32_bf16(Bt[n][k], At[m][k], acc[ai][bj][m][n], 0, 0, 0); __builtin_amdgcn_s_setprio(0); } while (0)
; #define PG8_WAIT_V(n) asm volatile("s_waitcnt vmcnt(" #n ")" ::: "memory")
; #define PG8_WAIT_L(n) asm volatile("s_waitcnt lgkmcnt(" #n ")" ::: "memory")
; #define PG8_BAR __builtin_amdgcn_s_barrier()
; #define PG8_SCHED __builtin_amdgcn_sched_barrier(0)
; template <class Epi, class Sched>
; __device__ __forceinline__ void gemm_phase(const int tid, LAS unsigned char* lds, const Gemm g, const Sched& S, const Epi& E) {
;     ...
;             PG8_LDB(B0, 1, 0); PG8_LDB(B1, 1, 1); PG8_SCHED; PG8_LDA(At, 1, 0); PG8_STAGE(PG8_SA(0, 1), a2 + hstep, voffA);
;             PG8_WAIT_V(8); PG8_WAIT_L(0); PG8_BAR; PG8_MMA(0, 0, At, B0); PG8_MMA(0, 1, At, B1); PG8_BAR; PG8_SCHED;
	s_add_i32 s70, 0, 0x18000
	s_add_i32 s71, 0, 0x1c000
	v_add_u32_e32 v140, s70, v201
	v_add_u32_e32 v184, s71, v201
	ds_read_b128 v[128:131], v140
	ds_read_b128 v[132:135], v140 offset:1024
	ds_read_b128 v[136:139], v140 offset:2048
	ds_read_b128 v[140:143], v140 offset:3072
	ds_read_b128 v[144:147], v184
	ds_read_b128 v[148:151], v184 offset:1024
	ds_read_b128 v[180:183], v184 offset:2048
	ds_read_b128 v[184:187], v184 offset:3072
	s_add_u32 s18, s22, 0x160000
	s_addc_u32 s19, s23, 0
	s_mov_b32 m0, s40
	v_lshl_add_u64 v[240:241], s[18:19], 0, v[170:171]
	ds_read_b128 v[188:191], v202 offset:32768
	ds_read_b128 v[204:207], v202 offset:33792
	ds_read_b128 v[208:211], v202 offset:34816
	ds_read_b128 v[212:215], v202 offset:35840
	ds_read_b128 v[216:219], v202 offset:36864
	ds_read_b128 v[220:223], v202 offset:37888
	ds_read_b128 v[224:227], v202 offset:38912
	ds_read_b128 v[228:231], v202 offset:39936
	global_load_lds_dwordx4 v[240:241], off
	v_lshl_add_u64 v[240:241], s[18:19], 0, v[172:173]
	s_mov_b32 m0, s41
	s_nop 0
	global_load_lds_dwordx4 v[240:241], off
	s_waitcnt vmcnt(8)
	s_waitcnt lgkmcnt(0)
	s_barrier
	s_setprio 1
	s_waitcnt lgkmcnt(0)
	v_mfma_f32_16x16x32_bf16 v[124:127], v[128:131], v[188:191], v[124:127]
	v_mfma_f32_16x16x32_bf16 v[120:123], v[136:139], v[188:191], v[120:123]
	v_mfma_f32_16x16x32_bf16 v[108:111], v[128:131], v[208:211], v[108:111]
	v_mfma_f32_16x16x32_bf16 v[104:107], v[136:139], v[208:211], v[104:107]
	v_mfma_f32_16x16x32_bf16 v[92:95], v[128:131], v[216:219], v[92:95]
	v_mfma_f32_16x16x32_bf16 v[88:91], v[136:139], v[216:219], v[88:91]
	v_mfma_f32_16x16x32_bf16 v[76:79], v[128:131], v[224:227], v[76:79]
	v_mfma_f32_16x16x32_bf16 v[72:75], v[136:139], v[224:227], v[72:75]
	v_mfma_f32_16x16x32_bf16 v[124:127], v[132:135], v[204:207], v[124:127]
	v_mfma_f32_16x16x32_bf16 v[120:123], v[140:143], v[204:207], v[120:123]
	v_mfma_f32_16x16x32_bf16 v[108:111], v[132:135], v[212:215], v[108:111]
	v_mfma_f32_16x16x32_bf16 v[104:107], v[140:143], v[212:215], v[104:107]
	v_mfma_f32_16x16x32_bf16 v[92:95], v[132:135], v[220:223], v[92:95]
	v_mfma_f32_16x16x32_bf16 v[88:91], v[140:143], v[220:223], v[88:91]
	v_mfma_f32_16x16x32_bf16 v[76:79], v[132:135], v[228:231], v[76:79]
	v_mfma_f32_16x16x32_bf16 v[72:75], v[140:143], v[228:231], v[72:75]
	v_mfma_f32_16x16x32_bf16 v[116:119], v[144:147], v[188:191], v[116:119]
	v_mfma_f32_16x16x32_bf16 v[112:115], v[180:183], v[188:191], v[112:115]
	v_mfma_f32_16x16x32_bf16 v[100:103], v[144:147], v[208:211], v[100:103]
	v_mfma_f32_16x16x32_bf16 v[96:99], v[180:183], v[208:211], v[96:99]
	v_mfma_f32_16x16x32_bf16 v[84:87], v[144:147], v[216:219], v[84:87]
	v_mfma_f32_16x16x32_bf16 v[80:83], v[180:183], v[216:219], v[80:83]
	v_mfma_f32_16x16x32_bf16 v[68:71], v[144:147], v[224:227], v[68:71]
	v_mfma_f32_16x16x32_bf16 v[64:67], v[180:183], v[224:227], v[64:67]
	v_mfma_f32_16x16x32_bf16 v[116:119], v[148:151], v[204:207], v[116:119]
	v_mfma_f32_16x16x32_bf16 v[112:115], v[184:187], v[204:207], v[112:115]
	v_mfma_f32_16x16x32_bf16 v[100:103], v[148:151], v[212:215], v[100:103]
	v_mfma_f32_16x16x32_bf16 v[96:99], v[184:187], v[212:215], v[96:99]
	v_mfma_f32_16x16x32_bf16 v[84:87], v[148:151], v[220:223], v[84:87]
	v_mfma_f32_16x16x32_bf16 v[80:83], v[184:187], v[220:223], v[80:83]
	v_mfma_f32_16x16x32_bf16 v[68:71], v[148:151], v[228:231], v[68:71]
	v_mfma_f32_16x16x32_bf16 v[64:67], v[184:187], v[228:231], v[64:67]
	s_setprio 0
	s_barrier
; #define PG8_STAGE(bufoff, gbase, voff) do { _Pragma("unroll") for (int _i = 0; _i < 2; ++_i) \
;         __builtin_amdgcn_global_load_lds((const unsigned*)((const char*)(gbase) + (voff)[_i]), (LAS unsigned*)(lds + (bufoff) + ldsw + _i * 8192), 16, 0, 0); } while (0)
; #define PG8_LDA(dst, b, h) do { _Pragma("unroll") for (int m = 0; m < 4; ++m) _Pragma("unroll") for (int k = 0; k < 2; ++k) dst[m][k] = *(const LAS bf16x8*)(lds + PG8_SA(b, h) + aoff + m * 2048 + k * 1024); } while (0)
; #define PG8_MMA(ai, bj, At, Bt) do { __builtin_amdgcn_s_setprio(1); _Pragma("unroll") for (int m = 0; m < 4; ++m) _Pragma("unroll") for (int n = 0; n < 2; ++n) _Pragma("unroll") for (int k = 0; k < 2; ++k) \
;         acc[ai][bj][m][n] = __builtin_amdgcn_mfma_f32_16x16x32_bf16(Bt[n][k], At[m][k], acc[ai][bj][m][n], 0, 0, 0); __builtin_amdgcn_s_setprio(0); } while (0)
; #define PG8_WAIT_V(n) asm volatile("s_waitcnt vmcnt(" #n ")" ::: "memory")
; #define PG8_WAIT_L(n) asm volatile("s_waitcnt lgkmcnt(" #n ")" ::: "memory")
; #define PG8_BAR __builtin_amdgcn_s_barrier()
; #define PG8_SCHED __builtin_amdgcn_sched_barrier(0)
; template <class Epi, class Sched>
; __device__ __forceinline__ void gemm_phase(const int tid, LAS unsigned char* lds, const Gemm g, const Sched& S, const Epi& E) {
;     ...
;             PG8_LDA(At, 1, 1); PG8_STAGE(PG8_SB(1, 0), b3, voffB); PG8_STAGE(PG8_SB(1, 1), b3 + hstep, voffB); PG8_STAGE(PG8_SA(1, 0), a3, voffA);
;             PG8_WAIT_V(8); PG8_WAIT_L(0); PG8_BAR; PG8_MMA(1, 0, At, B0); PG8_MMA(1, 1, At, B1); PG8_BAR; PG8_SCHED;
;         }
;         if (wr == 0) PG8_BAR;
	s_add_i32 s18, s70, s31
	v_lshl_add_u64 v[232:233], v[232:233], 0, s[34:35]
	s_mov_b32 m0, s18
	ds_read_b128 v[188:191], v202 offset:49152
	ds_read_b128 v[204:207], v202 offset:50176
	ds_read_b128 v[208:211], v202 offset:51200
	ds_read_b128 v[212:215], v202 offset:52224
	ds_read_b128 v[216:219], v202 offset:53248
	ds_read_b128 v[220:223], v202 offset:54272
	ds_read_b128 v[224:227], v202 offset:55296
	ds_read_b128 v[228:231], v202 offset:56320
	global_load_lds_dwordx4 v[232:233], off
	s_add_i32 m0, s18, 0x2000
	s_add_u32 s18, s20, 0x160080
	v_lshl_add_u64 v[232:233], v[234:235], 0, s[34:35]
	s_addc_u32 s19, s21, 0
	s_add_i32 s20, s71, s31
	global_load_lds_dwordx4 v[232:233], off
	v_lshl_add_u64 v[232:233], s[18:19], 0, v[152:153]
	s_mov_b32 m0, s20
	s_nop 0
	global_load_lds_dwordx4 v[232:233], off
	v_lshl_add_u64 v[232:233], s[18:19], 0, v[174:175]
	s_add_i32 m0, s20, 0x2000
	s_nop 0
	global_load_lds_dwordx4 v[232:233], off
	v_lshl_add_u64 v[232:233], v[236:237], 0, s[34:35]
	s_mov_b32 m0, s58
	s_nop 0
	global_load_lds_dwordx4 v[232:233], off
	v_lshl_add_u64 v[232:233], v[238:239], 0, s[34:35]
	s_mov_b32 m0, s59
	s_nop 0
	global_load_lds_dwordx4 v[232:233], off
	s_waitcnt vmcnt(8)
	s_waitcnt lgkmcnt(0)
	s_barrier
	s_setprio 1
	s_waitcnt lgkmcnt(0)
	v_mfma_f32_16x16x32_bf16 v[60:63], v[128:131], v[188:191], v[60:63]
	v_mfma_f32_16x16x32_bf16 v[56:59], v[136:139], v[188:191], v[56:59]
	v_mfma_f32_16x16x32_bf16 v[44:47], v[128:131], v[208:211], v[44:47]
	v_mfma_f32_16x16x32_bf16 v[40:43], v[136:139], v[208:211], v[40:43]
	v_mfma_f32_16x16x32_bf16 v[28:31], v[128:131], v[216:219], v[28:31]
	v_mfma_f32_16x16x32_bf16 v[24:27], v[136:139], v[216:219], v[24:27]
	v_mfma_f32_16x16x32_bf16 v[12:15], v[128:131], v[224:227], v[12:15]
	v_mfma_f32_16x16x32_bf16 v[8:11], v[136:139], v[224:227], v[8:11]
	v_mfma_f32_16x16x32_bf16 v[60:63], v[132:135], v[204:207], v[60:63]
	v_mfma_f32_16x16x32_bf16 v[56:59], v[140:143], v[204:207], v[56:59]
	v_mfma_f32_16x16x32_bf16 v[44:47], v[132:135], v[212:215], v[44:47]
	v_mfma_f32_16x16x32_bf16 v[40:43], v[140:143], v[212:215], v[40:43]
	v_mfma_f32_16x16x32_bf16 v[28:31], v[132:135], v[220:223], v[28:31]
	v_mfma_f32_16x16x32_bf16 v[24:27], v[140:143], v[220:223], v[24:27]
	v_mfma_f32_16x16x32_bf16 v[12:15], v[132:135], v[228:231], v[12:15]
	v_mfma_f32_16x16x32_bf16 v[8:11], v[140:143], v[228:231], v[8:11]
	v_mfma_f32_16x16x32_bf16 v[52:55], v[144:147], v[188:191], v[52:55]
	v_mfma_f32_16x16x32_bf16 v[48:51], v[180:183], v[188:191], v[48:51]
	v_mfma_f32_16x16x32_bf16 v[36:39], v[144:147], v[208:211], v[36:39]
	v_mfma_f32_16x16x32_bf16 v[32:35], v[180:183], v[208:211], v[32:35]
	v_mfma_f32_16x16x32_bf16 v[20:23], v[144:147], v[216:219], v[20:23]
	v_mfma_f32_16x16x32_bf16 v[16:19], v[180:183], v[216:219], v[16:19]
	v_mfma_f32_16x16x32_bf16 v[4:7], v[144:147], v[224:227], v[4:7]
	v_mfma_f32_16x16x32_bf16 v[0:3], v[180:183], v[224:227], v[0:3]
	v_mfma_f32_16x16x32_bf16 v[52:55], v[148:151], v[204:207], v[52:55]
	v_mfma_f32_16x16x32_bf16 v[48:51], v[184:187], v[204:207], v[48:51]
	v_mfma_f32_16x16x32_bf16 v[36:39], v[148:151], v[212:215], v[36:39]
	v_mfma_f32_16x16x32_bf16 v[32:35], v[184:187], v[212:215], v[32:35]
	v_mfma_f32_16x16x32_bf16 v[20:23], v[148:151], v[220:223], v[20:23]
	v_mfma_f32_16x16x32_bf16 v[16:19], v[184:187], v[220:223], v[16:19]
	v_mfma_f32_16x16x32_bf16 v[4:7], v[148:151], v[228:231], v[4:7]
	v_mfma_f32_16x16x32_bf16 v[0:3], v[184:187], v[228:231], v[0:3]
	s_setprio 0
	s_barrier
	s_add_i32 s69, s69, 2
	s_add_u32 s67, s67, 0x100
	s_addc_u32 s68, s68, 0
	s_cmpk_gt_u32 s69, 0x55
	s_mov_b64 s[18:19], s[4:5]
	s_cbranch_scc0 .LBB0_763
	s_and_b64 vcc, exec, s[12:13]
	s_cbranch_vccz .LBB0_766
	s_barrier
